# speedup vs baseline: 1.0055x; 1.0055x over previous
; #define tidx() tidx_(wv_)
; template <int NKT, typename KofsF, typename BiasF> ...
;   const int lane = tidx() & 63, fr = lane & 15, g = lane >> 4;
;   float s[NKT][4];
; #pragma unroll
;   for (int kt = 0; kt < NKT; ++kt) {
;     int key = kofs(kt) + fr;
;     const char* kp = (const char*)Ks + key * 128;
;     bf16x8 a0 = *(const bf16x8*)(kp + ((g ^ (key & 7)) << 4));
;     bf16x8 a1 = *(const bf16x8*)(kp + (((4 + g) ^ (key & 7)) << 4));
;     f32x4 acc = {0.f, 0.f, 0.f, 0.f};
;     acc = __builtin_amdgcn_mfma_f32_16x16x32_bf16(a0, bq0, acc, 0, 0, 0);
;     acc = __builtin_amdgcn_mfma_f32_16x16x32_bf16(a1, bq1, acc, 0, 0, 0);
; __device__ __forceinline__ void load_q(const u16* z, int ld, int col, int tok, bool rope, const float* tb, bf16x8& bq0, bf16x8& bq1, int wv_) {
;   const int g = (tidx() & 63) >> 4;
;   const u16* src = z + (size_t)tok * ld + col + g * 8;
;   uint4 c0 = *(const uint4*)src;
;   uint4 c1 = *(const uint4*)(src + 32);
;   float x1[8], x2[8];
;   unpack8(c0, x1);
;   unpack8(c1, x2);
;   if (rope) {
;     const float* t = tb + ((size_t)(tok & (SEQ_ - 1)) * 32 + g * 8) * 2;
; #pragma unroll
;     for (int i = 0; i < 8; ++i) {
;       float cs = t[2 * i], sn = t[2 * i + 1];
;       float a = x1[i] * cs - x2[i] * sn, b = x2[i] * cs + x1[i] * sn;
;       x1[i] = a; x2[i] = b;
;     }
;   }
; #pragma unroll
;   for (int i = 0; i < 8; ++i) { x1[i] *= 0.125f; x2[i] *= 0.125f; }
;   union { uint4 q; bf16x8 v; } cv;
;   cv.q = pack8(x1); bq0 = cv.v;
;   cv.q = pack8(x2); bq1 = cv.v;
; }
.LBB0_308:
	s_or_b64 exec, exec, s[4:5]
	v_mbcnt_lo_u32_b32 v3, -1, 0
	v_mbcnt_hi_u32_b32 v3, -1, v3
	v_mbcnt_lo_u32_b32 v33, -1, 0
	v_mbcnt_hi_u32_b32 v33, -1, v33
	v_lshlrev_b64 v[34:35], 1, v[0:1]
	v_or_b32_e32 v3, s63, v3
	v_ashrrev_i32_e32 v36, 6, v3
	v_lshl_add_u32 v46, v36, 4, s41
	v_and_or_b32 v3, v33, 15, v46
	v_lshl_add_u32 v32, v3, s11, v2
	v_mov_b64_e32 v[2:3], s[58:59]
	v_mad_i64_i32 v[2:3], s[4:5], v32, s73, v[2:3]
	v_mbcnt_lo_u32_b32 v4, -1, 0
	v_mbcnt_hi_u32_b32 v4, -1, v4
	v_lshl_add_u64 v[0:1], v[2:3], 0, v[34:35]
	v_lshrrev_b32_e32 v2, 1, v4
	v_and_b32_e32 v8, 24, v2
	v_lshlrev_b32_e32 v9, 5, v32
	v_lshlrev_b32_e32 v166, 1, v8
	v_and_or_b32 v8, v9, s64, v8
	v_lshl_add_u64 v[4:5], v[0:1], 0, v[166:167]
	v_lshlrev_b32_e32 v20, 3, v8
	global_load_dwordx4 v[0:3], v[4:5], off
	s_nop 0
	global_load_dwordx4 v[4:7], v[4:5], off offset:64
	s_nop 0
	global_load_dwordx4 v[8:11], v20, s[52:53]
	global_load_dwordx4 v[12:15], v20, s[52:53] offset:16
	global_load_dwordx4 v[16:19], v20, s[52:53] offset:32
	s_nop 0
	global_load_dwordx4 v[20:23], v20, s[52:53] offset:48
	s_waitcnt lgkmcnt(0)
	s_barrier
	s_waitcnt vmcnt(3)
	v_mov_b32_e32 v28, v8
	v_lshlrev_b32_e32 v25, 16, v1
	v_lshlrev_b32_e32 v24, 16, v0
	v_lshlrev_b32_e32 v27, 16, v5
	v_lshlrev_b32_e32 v26, 16, v4
	s_waitcnt vmcnt(2)
	v_mov_b32_e32 v29, v12
	v_mov_b32_e32 v12, v9
	v_mov_b32_e32 v8, v10
	v_mov_b32_e32 v9, v14
	v_mov_b32_e32 v14, v11
	v_lshlrev_b32_e32 v11, 16, v3
	v_lshlrev_b32_e32 v10, 16, v2
	v_lshlrev_b32_e32 v31, 16, v7
	v_lshlrev_b32_e32 v30, 16, v6
	s_waitcnt vmcnt(0)
	v_mov_b32_e32 v39, v20
	v_mov_b32_e32 v20, v17
	v_and_b32_e32 v1, 0xffff0000, v1
	v_and_b32_e32 v0, 0xffff0000, v0
	v_and_b32_e32 v5, 0xffff0000, v5
	v_and_b32_e32 v4, 0xffff0000, v4
	v_and_b32_e32 v3, 0xffff0000, v3
	v_and_b32_e32 v2, 0xffff0000, v2
	v_and_b32_e32 v7, 0xffff0000, v7
	v_and_b32_e32 v6, 0xffff0000, v6
	v_mov_b32_e32 v38, v16
	v_mov_b32_e32 v16, v18
	v_mov_b32_e32 v17, v22
	v_mov_b32_e32 v22, v19
	v_pk_mul_f32 v[18:19], v[12:13], v[24:25]
	v_pk_mul_f32 v[12:13], v[12:13], v[26:27]
	v_pk_mul_f32 v[42:43], v[20:21], v[10:11]
	v_pk_mul_f32 v[20:21], v[20:21], v[30:31]
	v_pk_mul_f32 v[40:41], v[14:15], v[0:1]
	v_pk_mul_f32 v[14:15], v[14:15], v[4:5]
	v_pk_mul_f32 v[44:45], v[22:23], v[2:3]
	v_pk_mul_f32 v[22:23], v[22:23], v[6:7]
	v_pk_fma_f32 v[12:13], v[28:29], v[24:25], v[12:13] neg_lo:[0,0,1] neg_hi:[0,0,1]
	v_pk_fma_f32 v[10:11], v[38:39], v[10:11], v[20:21] neg_lo:[0,0,1] neg_hi:[0,0,1]
	v_pk_fma_f32 v[0:1], v[8:9], v[0:1], v[14:15] neg_lo:[0,0,1] neg_hi:[0,0,1]
	v_pk_fma_f32 v[2:3], v[16:17], v[2:3], v[22:23] neg_lo:[0,0,1] neg_hi:[0,0,1]
	v_pk_mul_f32 v[12:13], v[12:13], s[86:87] op_sel_hi:[1,0]
	v_pk_mul_f32 v[10:11], v[10:11], s[86:87] op_sel_hi:[1,0]
	v_pk_fma_f32 v[18:19], v[28:29], v[26:27], v[18:19]
	v_pk_mul_f32 v[0:1], v[0:1], s[86:87] op_sel_hi:[1,0]
	v_pk_mul_f32 v[2:3], v[2:3], s[86:87] op_sel_hi:[1,0]
	v_bfe_u32 v20, v12, 16, 1
	v_bfe_u32 v22, v10, 16, 1
	v_pk_fma_f32 v[4:5], v[8:9], v[4:5], v[40:41]
	v_pk_fma_f32 v[6:7], v[16:17], v[6:7], v[44:45]
	v_pk_mul_f32 v[14:15], v[18:19], s[86:87] op_sel_hi:[1,0]
	v_bfe_u32 v17, v2, 16, 1
	v_bfe_u32 v19, v0, 16, 1
	v_bfe_u32 v21, v13, 16, 1
	v_bfe_u32 v23, v11, 16, 1
	v_add3_u32 v10, v10, v22, s48
	v_add3_u32 v12, v12, v20, s48
	v_pk_fma_f32 v[8:9], v[38:39], v[30:31], v[42:43]
	v_pk_mul_f32 v[4:5], v[4:5], s[86:87] op_sel_hi:[1,0]
	v_pk_mul_f32 v[6:7], v[6:7], s[86:87] op_sel_hi:[1,0]
	v_bfe_u32 v16, v3, 16, 1
	v_bfe_u32 v18, v1, 16, 1
	v_add3_u32 v0, v0, v19, s48
	v_add3_u32 v2, v2, v17, s48
	v_add3_u32 v11, v11, v23, s48
	v_add3_u32 v13, v13, v21, s48
	v_lshrrev_b32_e32 v12, 16, v12
	v_lshrrev_b32_e32 v10, 16, v10
	v_pk_mul_f32 v[8:9], v[8:9], s[86:87] op_sel_hi:[1,0]
	v_add3_u32 v1, v1, v18, s48
	v_add3_u32 v3, v3, v16, s48
	v_lshrrev_b32_e32 v13, 16, v13
	v_lshrrev_b32_e32 v11, 16, v11
	v_and_or_b32 v2, v2, s97, v10
	v_and_or_b32 v0, v0, s97, v12
	v_bfe_u32 v10, v7, 16, 1
	v_bfe_u32 v12, v5, 16, 1
	v_and_or_b32 v3, v3, s97, v11
	v_and_or_b32 v1, v1, s97, v13
	v_bfe_u32 v11, v6, 16, 1
	v_bfe_u32 v13, v4, 16, 1
	v_add3_u32 v5, v5, v12, s48
	v_add3_u32 v7, v7, v10, s48
	v_bfe_u32 v10, v14, 16, 1
	v_bfe_u32 v12, v8, 16, 1
	v_add3_u32 v4, v4, v13, s48
	v_add3_u32 v6, v6, v11, s48
	v_bfe_u32 v11, v15, 16, 1
	v_bfe_u32 v13, v9, 16, 1
	v_add3_u32 v8, v8, v12, s48
	v_add3_u32 v10, v14, v10, s48
	v_add3_u32 v9, v9, v13, s48
	v_add3_u32 v11, v15, v11, s48
	v_lshrrev_b32_e32 v12, 16, v10
	v_lshrrev_b32_e32 v8, 16, v8
	v_mbcnt_lo_u32_b32 v16, -1, 0
	v_mbcnt_hi_u32_b32 v16, -1, v16
	v_lshrrev_b32_e32 v13, 16, v11
	v_and_b32_e32 v38, 15, v16
	v_lshrrev_b32_e32 v9, 16, v9
	v_and_or_b32 v10, v6, s97, v8
	v_and_or_b32 v8, v4, s97, v12
	v_bfe_u32 v37, v16, 4, 2
	v_lshlrev_b32_e32 v4, 7, v38
	v_lshlrev_b32_e32 v6, 11, v36
	v_and_or_b32 v11, v7, s97, v9
	v_and_or_b32 v9, v5, s97, v13
	v_bitop3_b32 v5, v37, v16, 7 bitop3:0x78
	v_add3_u32 v12, 0, v4, v6
	v_lshl_add_u32 v49, v5, 4, v12
	ds_read_b128 v[4:7], v49
	v_and_b32_e32 v13, 7, v16
	v_bitop3_b32 v13, v37, v13, 4 bitop3:0x36
	v_lshl_add_u32 v50, v13, 4, v12
	ds_read_b128 v[12:15], v50
	ds_read_b128 v[20:23], v50 offset:2048
	v_and_b32_e32 v39, 63, v16
	ds_read_b128 v[16:19], v49 offset:2048
	s_waitcnt lgkmcnt(3)
	v_mfma_f32_16x16x32_bf16 v[4:7], v[4:7], v[0:3], 0
	v_lshl_or_b32 v24, v37, 2, v178
	v_or_b32_e32 v25, 64, v38
	v_add_u32_e32 v41, v24, v46
	s_waitcnt lgkmcnt(2)
; template <int NKT, typename KofsF, typename BiasF> ...
;     ...
;   for (int kt = 0; kt < NKT; ++kt) {
;     int key = kofs(kt) + fr;
;     const char* kp = (const char*)Ks + key * 128;
;     bf16x8 a0 = *(const bf16x8*)(kp + ((g ^ (key & 7)) << 4));
;     bf16x8 a1 = *(const bf16x8*)(kp + (((4 + g) ^ (key & 7)) << 4));
;     f32x4 acc = {0.f, 0.f, 0.f, 0.f};
;     acc = __builtin_amdgcn_mfma_f32_16x16x32_bf16(a0, bq0, acc, 0, 0, 0);
;     acc = __builtin_amdgcn_mfma_f32_16x16x32_bf16(a1, bq1, acc, 0, 0, 0);
; #pragma unroll
;     for (int j = 0; j < 4; ++j) s[kt][j] = acc[j] + bias(kt, g * 4 + j, fr);
; __device__ __forceinline__ void attnA_item(unsigned char* ws, int dil, int item, bool first, unsigned char* lds, int wv_) {
;     ...
;   auto bias = [&](int kt, int kj, int frq) -> float {
;     int ik = i0 - 64 + 16 * w + 16 * kt + kj;
;     int iqq = i0 + 16 * w + frq;
;     int dd = iqq - ik;
;     bool ok = (ik >= 0) && (ik < m) && (dd <= 64) && (dd >= -64);
;     return ok ? 0.f : -INFINITY;
;   };
	v_mfma_f32_16x16x32_bf16 v[4:7], v[12:15], v[8:11], v[4:7]
	v_sub_u32_e32 v12, v25, v24
	v_cmp_gt_u32_e64 s[4:5], s49, v12
	v_cmp_gt_i32_e64 s[6:7], s30, v41
	v_add_u32_e32 v45, v25, v46
	v_cmp_lt_i32_e32 vcc, -1, v41
	s_and_b64 s[4:5], s[4:5], s[6:7]
	v_or_b32_e32 v12, 1, v41
	s_and_b64 s[4:5], vcc, s[4:5]
	v_sub_u32_e32 v13, v45, v12
	v_cndmask_b32_e64 v40, v179, 0, s[4:5]
	v_cmp_gt_u32_e64 s[4:5], s49, v13
	v_cmp_gt_i32_e64 s[6:7], s30, v12
	s_and_b64 s[4:5], s[6:7], s[4:5]
	v_or_b32_e32 v12, 2, v41
	s_and_b64 s[4:5], vcc, s[4:5]
	v_sub_u32_e32 v13, v45, v12
	v_cndmask_b32_e64 v42, v179, 0, s[4:5]
	v_cmp_gt_u32_e64 s[4:5], s49, v13
	v_cmp_gt_i32_e64 s[6:7], s30, v12
	s_and_b64 s[4:5], s[6:7], s[4:5]
	v_or_b32_e32 v12, 3, v41
	s_and_b64 s[4:5], vcc, s[4:5]
	v_sub_u32_e32 v13, v45, v12
	v_cndmask_b32_e64 v43, v179, 0, s[4:5]
	v_cmp_gt_u32_e64 s[4:5], s49, v13
	v_cmp_gt_i32_e64 s[6:7], s30, v12
	s_and_b64 s[4:5], s[6:7], s[4:5]
	s_waitcnt lgkmcnt(0)
	v_mfma_f32_16x16x32_bf16 v[12:15], v[16:19], v[0:3], 0
	s_and_b64 s[4:5], vcc, s[4:5]
	v_add_u32_e32 v16, 16, v41
	v_cndmask_b32_e64 v44, v179, 0, s[4:5]
	s_movk_i32 s4, 0xffef
	v_sub_u32_e32 v17, v45, v16
	v_cmp_lt_i32_e32 vcc, s4, v41
	v_cmp_gt_u32_e64 s[4:5], s49, v17
	v_cmp_gt_i32_e64 s[6:7], s30, v16
	s_and_b64 s[4:5], s[6:7], s[4:5]
	s_and_b64 s[4:5], vcc, s[4:5]
	v_add_u32_e32 v16, 17, v41
	v_cndmask_b32_e64 v46, v179, 0, s[4:5]
	s_movk_i32 s4, 0xffee
	v_sub_u32_e32 v17, v45, v16
	v_cmp_lt_i32_e32 vcc, s4, v41
	v_cmp_gt_u32_e64 s[4:5], s49, v17
	v_cmp_gt_i32_e64 s[6:7], s30, v16
	s_and_b64 s[4:5], s[6:7], s[4:5]
	s_and_b64 s[4:5], vcc, s[4:5]
	v_add_u32_e32 v16, 18, v41
	v_cndmask_b32_e64 v47, v179, 0, s[4:5]
	s_movk_i32 s4, 0xffed
	v_sub_u32_e32 v17, v45, v16
	v_cmp_lt_i32_e32 vcc, s4, v41
	v_cmp_gt_u32_e64 s[4:5], s49, v17
	v_cmp_gt_i32_e64 s[6:7], s30, v16
	ds_read_b128 v[16:19], v49 offset:4096
	v_mfma_f32_16x16x32_bf16 v[12:15], v[20:23], v[8:11], v[12:15]
	ds_read_b128 v[20:23], v50 offset:4096
	ds_read_b128 v[28:31], v50 offset:6144
	s_and_b64 s[4:5], s[6:7], s[4:5]
	s_and_b64 s[4:5], vcc, s[4:5]
	v_add_u32_e32 v24, 19, v41
	v_cndmask_b32_e64 v48, v179, 0, s[4:5]
	s_movk_i32 s4, 0xffec
	v_sub_u32_e32 v25, v45, v24
	v_cmp_lt_i32_e32 vcc, s4, v41
	v_cmp_gt_u32_e64 s[4:5], s49, v25
	v_cmp_gt_i32_e64 s[6:7], s30, v24
	ds_read_b128 v[24:27], v49 offset:6144
	s_waitcnt lgkmcnt(3)
	v_mfma_f32_16x16x32_bf16 v[16:19], v[16:19], v[0:3], 0
	s_and_b64 s[4:5], s[6:7], s[4:5]
	s_and_b64 s[4:5], vcc, s[4:5]
	v_cndmask_b32_e64 v51, v179, 0, s[4:5]
	s_waitcnt lgkmcnt(2)
	v_mfma_f32_16x16x32_bf16 v[16:19], v[20:23], v[8:11], v[16:19]
	v_add_u32_e32 v20, 32, v41
	s_movk_i32 s4, 0xffdf
	v_sub_u32_e32 v21, v45, v20
	v_cmp_lt_i32_e32 vcc, s4, v41
	v_cmp_gt_u32_e64 s[4:5], s49, v21
	v_cmp_gt_i32_e64 s[6:7], s30, v20
	s_and_b64 s[4:5], s[6:7], s[4:5]
	s_and_b64 s[4:5], vcc, s[4:5]
	v_add_u32_e32 v20, 33, v41
	v_cndmask_b32_e64 v76, v179, 0, s[4:5]
	s_movk_i32 s4, 0xffde
	v_sub_u32_e32 v21, v45, v20
	v_cmp_lt_i32_e32 vcc, s4, v41
	v_cmp_gt_u32_e64 s[4:5], s49, v21
	v_cmp_gt_i32_e64 s[6:7], s30, v20
	s_and_b64 s[4:5], s[6:7], s[4:5]
	s_and_b64 s[4:5], vcc, s[4:5]
	v_add_u32_e32 v20, 34, v41
	v_cndmask_b32_e64 v77, v179, 0, s[4:5]
	s_movk_i32 s4, 0xffdd
	v_sub_u32_e32 v21, v45, v20
	v_cmp_lt_i32_e32 vcc, s4, v41
	v_cmp_gt_u32_e64 s[4:5], s49, v21
	v_cmp_gt_i32_e64 s[6:7], s30, v20
	s_and_b64 s[4:5], s[6:7], s[4:5]
	s_and_b64 s[4:5], vcc, s[4:5]
	v_add_u32_e32 v20, 35, v41
	v_cndmask_b32_e64 v78, v179, 0, s[4:5]
	s_movk_i32 s4, 0xffdc
	v_sub_u32_e32 v21, v45, v20
	v_cmp_lt_i32_e32 vcc, s4, v41
	v_cmp_gt_u32_e64 s[4:5], s49, v21
	v_cmp_gt_i32_e64 s[6:7], s30, v20
	s_and_b64 s[4:5], s[6:7], s[4:5]
	s_waitcnt lgkmcnt(0)
	v_mfma_f32_16x16x32_bf16 v[20:23], v[24:27], v[0:3], 0
	s_and_b64 s[4:5], vcc, s[4:5]
	v_add_u32_e32 v24, 48, v41
	v_cndmask_b32_e64 v79, v179, 0, s[4:5]
	s_movk_i32 s4, 0xffcf
	v_sub_u32_e32 v25, v45, v24
	v_cmp_lt_i32_e32 vcc, s4, v41
	v_cmp_gt_u32_e64 s[4:5], s49, v25
	v_cmp_gt_i32_e64 s[6:7], s30, v24
	s_and_b64 s[4:5], s[6:7], s[4:5]
	s_and_b64 s[4:5], vcc, s[4:5]
	v_add_u32_e32 v24, 49, v41
	v_cndmask_b32_e64 v80, v179, 0, s[4:5]
	s_movk_i32 s4, 0xffce
	v_sub_u32_e32 v25, v45, v24
	v_cmp_lt_i32_e32 vcc, s4, v41
	v_cmp_gt_u32_e64 s[4:5], s49, v25
	v_cmp_gt_i32_e64 s[6:7], s30, v24
	s_and_b64 s[4:5], s[6:7], s[4:5]
	s_and_b64 s[4:5], vcc, s[4:5]
	v_add_u32_e32 v24, 50, v41
	v_cndmask_b32_e64 v81, v179, 0, s[4:5]
	s_movk_i32 s4, 0xffcd
	v_sub_u32_e32 v25, v45, v24
	v_cmp_lt_i32_e32 vcc, s4, v41
	v_cmp_gt_u32_e64 s[4:5], s49, v25
	v_cmp_gt_i32_e64 s[6:7], s30, v24
	ds_read_b128 v[24:27], v49 offset:8192
	v_mfma_f32_16x16x32_bf16 v[20:23], v[28:31], v[8:11], v[20:23]
	ds_read_b128 v[28:31], v50 offset:8192
	ds_read_b128 v[56:59], v50 offset:10240
	s_and_b64 s[4:5], s[6:7], s[4:5]
	s_and_b64 s[4:5], vcc, s[4:5]
	v_add_u32_e32 v52, 51, v41
	v_cndmask_b32_e64 v82, v179, 0, s[4:5]
	s_movk_i32 s4, 0xffcc
	v_sub_u32_e32 v53, v45, v52
	v_cmp_lt_i32_e32 vcc, s4, v41
	v_cmp_gt_u32_e64 s[4:5], s49, v53
	v_cmp_gt_i32_e64 s[6:7], s30, v52
	ds_read_b128 v[52:55], v49 offset:10240
	s_waitcnt lgkmcnt(3)
	v_mfma_f32_16x16x32_bf16 v[24:27], v[24:27], v[0:3], 0
	s_and_b64 s[4:5], s[6:7], s[4:5]
	s_and_b64 s[4:5], vcc, s[4:5]
	v_cndmask_b32_e64 v83, v179, 0, s[4:5]
	s_waitcnt lgkmcnt(2)
; template <int NKT, typename KofsF, typename BiasF> ...
;     ...
;   for (int kt = 0; kt < NKT; ++kt) {
;     int key = kofs(kt) + fr;
;     const char* kp = (const char*)Ks + key * 128;
;     bf16x8 a0 = *(const bf16x8*)(kp + ((g ^ (key & 7)) << 4));
;     bf16x8 a1 = *(const bf16x8*)(kp + (((4 + g) ^ (key & 7)) << 4));
;     f32x4 acc = {0.f, 0.f, 0.f, 0.f};
;     acc = __builtin_amdgcn_mfma_f32_16x16x32_bf16(a0, bq0, acc, 0, 0, 0);
;     acc = __builtin_amdgcn_mfma_f32_16x16x32_bf16(a1, bq1, acc, 0, 0, 0);
; #pragma unroll
;     for (int j = 0; j < 4; ++j) s[kt][j] = acc[j] + bias(kt, g * 4 + j, fr);
; __device__ __forceinline__ void attnA_item(unsigned char* ws, int dil, int item, bool first, unsigned char* lds, int wv_) {
;     ...
;   auto bias = [&](int kt, int kj, int frq) -> float {
;     int ik = i0 - 64 + 16 * w + 16 * kt + kj;
;     int iqq = i0 + 16 * w + frq;
;     int dd = iqq - ik;
;     bool ok = (ik >= 0) && (ik < m) && (dd <= 64) && (dd >= -64);
;     return ok ? 0.f : -INFINITY;
;   };
	v_mfma_f32_16x16x32_bf16 v[24:27], v[28:31], v[8:11], v[24:27]
	v_add_u32_e32 v28, 64, v41
	s_movk_i32 s4, 0xffbf
	v_sub_u32_e32 v29, v45, v28
	v_cmp_lt_i32_e32 vcc, s4, v41
	v_cmp_gt_u32_e64 s[4:5], s49, v29
	v_cmp_gt_i32_e64 s[6:7], s30, v28
	s_and_b64 s[4:5], s[6:7], s[4:5]
	s_and_b64 s[4:5], vcc, s[4:5]
	v_add_u32_e32 v28, 0x41, v41
	v_cndmask_b32_e64 v84, v179, 0, s[4:5]
	s_movk_i32 s4, 0xffbe
	v_sub_u32_e32 v29, v45, v28
	v_cmp_lt_i32_e32 vcc, s4, v41
	v_cmp_gt_u32_e64 s[4:5], s49, v29
	v_cmp_gt_i32_e64 s[6:7], s30, v28
	s_and_b64 s[4:5], s[6:7], s[4:5]
	s_and_b64 s[4:5], vcc, s[4:5]
	v_add_u32_e32 v28, 0x42, v41
	v_cndmask_b32_e64 v85, v179, 0, s[4:5]
	s_movk_i32 s4, 0xffbd
	v_sub_u32_e32 v29, v45, v28
	v_cmp_lt_i32_e32 vcc, s4, v41
	v_cmp_gt_u32_e64 s[4:5], s49, v29
	v_cmp_gt_i32_e64 s[6:7], s30, v28
	s_and_b64 s[4:5], s[6:7], s[4:5]
	s_and_b64 s[4:5], vcc, s[4:5]
	v_add_u32_e32 v28, 0x43, v41
	v_cndmask_b32_e64 v86, v179, 0, s[4:5]
	s_movk_i32 s4, 0xffbc
	v_sub_u32_e32 v29, v45, v28
	v_cmp_lt_i32_e32 vcc, s4, v41
	v_cmp_gt_u32_e64 s[4:5], s49, v29
	v_cmp_gt_i32_e64 s[6:7], s30, v28
	s_and_b64 s[4:5], s[6:7], s[4:5]
	s_waitcnt lgkmcnt(0)
	v_mfma_f32_16x16x32_bf16 v[28:31], v[52:55], v[0:3], 0
	s_and_b64 s[4:5], vcc, s[4:5]
	v_add_u32_e32 v52, 0x50, v41
	v_cndmask_b32_e64 v87, v179, 0, s[4:5]
	s_movk_i32 s4, 0xffaf
	v_sub_u32_e32 v53, v45, v52
	v_cmp_lt_i32_e32 vcc, s4, v41
	v_cmp_gt_u32_e64 s[4:5], s49, v53
	v_cmp_gt_i32_e64 s[6:7], s30, v52
	s_and_b64 s[4:5], s[6:7], s[4:5]
	s_and_b64 s[4:5], vcc, s[4:5]
	v_add_u32_e32 v52, 0x51, v41
	v_cndmask_b32_e64 v88, v179, 0, s[4:5]
	s_movk_i32 s4, 0xffae
	v_sub_u32_e32 v53, v45, v52
	v_cmp_lt_i32_e32 vcc, s4, v41
	v_cmp_gt_u32_e64 s[4:5], s49, v53
	v_cmp_gt_i32_e64 s[6:7], s30, v52
	s_and_b64 s[4:5], s[6:7], s[4:5]
	s_and_b64 s[4:5], vcc, s[4:5]
	v_add_u32_e32 v52, 0x52, v41
	v_cndmask_b32_e64 v89, v179, 0, s[4:5]
	s_movk_i32 s4, 0xffad
	v_sub_u32_e32 v53, v45, v52
	v_cmp_lt_i32_e32 vcc, s4, v41
	v_cmp_gt_u32_e64 s[4:5], s49, v53
	v_cmp_gt_i32_e64 s[6:7], s30, v52
	ds_read_b128 v[52:55], v49 offset:12288
	v_mfma_f32_16x16x32_bf16 v[28:31], v[56:59], v[8:11], v[28:31]
	ds_read_b128 v[56:59], v50 offset:12288
	ds_read_b128 v[64:67], v50 offset:14336
	s_and_b64 s[4:5], s[6:7], s[4:5]
	s_and_b64 s[4:5], vcc, s[4:5]
	v_add_u32_e32 v60, 0x53, v41
	v_cndmask_b32_e64 v90, v179, 0, s[4:5]
	s_movk_i32 s4, 0xffac
	v_sub_u32_e32 v61, v45, v60
	v_cmp_lt_i32_e32 vcc, s4, v41
	v_cmp_gt_u32_e64 s[4:5], s49, v61
	v_cmp_gt_i32_e64 s[6:7], s30, v60
	ds_read_b128 v[60:63], v49 offset:14336
	s_waitcnt lgkmcnt(3)
	v_mfma_f32_16x16x32_bf16 v[52:55], v[52:55], v[0:3], 0
	s_and_b64 s[4:5], s[6:7], s[4:5]
	s_and_b64 s[4:5], vcc, s[4:5]
	v_cndmask_b32_e64 v91, v179, 0, s[4:5]
	s_waitcnt lgkmcnt(2)
	v_mfma_f32_16x16x32_bf16 v[52:55], v[56:59], v[8:11], v[52:55]
	v_add_u32_e32 v56, 0x60, v41
	s_movk_i32 s4, 0xff9f
	v_sub_u32_e32 v57, v45, v56
	v_cmp_lt_i32_e32 vcc, s4, v41
	v_cmp_gt_u32_e64 s[4:5], s49, v57
	v_cmp_gt_i32_e64 s[6:7], s30, v56
	s_and_b64 s[4:5], s[6:7], s[4:5]
	s_and_b64 s[4:5], vcc, s[4:5]
	v_add_u32_e32 v56, 0x61, v41
	v_cndmask_b32_e64 v92, v179, 0, s[4:5]
	s_movk_i32 s4, 0xff9e
	v_sub_u32_e32 v57, v45, v56
	v_cmp_lt_i32_e32 vcc, s4, v41
	v_cmp_gt_u32_e64 s[4:5], s49, v57
	v_cmp_gt_i32_e64 s[6:7], s30, v56
	s_and_b64 s[4:5], s[6:7], s[4:5]
	s_and_b64 s[4:5], vcc, s[4:5]
	v_add_u32_e32 v56, 0x62, v41
	v_cndmask_b32_e64 v93, v179, 0, s[4:5]
	s_movk_i32 s4, 0xff9d
	v_sub_u32_e32 v57, v45, v56
	v_cmp_lt_i32_e32 vcc, s4, v41
	v_cmp_gt_u32_e64 s[4:5], s49, v57
	v_cmp_gt_i32_e64 s[6:7], s30, v56
	s_and_b64 s[4:5], s[6:7], s[4:5]
	s_and_b64 s[4:5], vcc, s[4:5]
	v_add_u32_e32 v56, 0x63, v41
	v_cndmask_b32_e64 v94, v179, 0, s[4:5]
	s_movk_i32 s4, 0xff9c
	v_sub_u32_e32 v57, v45, v56
	v_cmp_lt_i32_e32 vcc, s4, v41
	v_cmp_gt_u32_e64 s[4:5], s49, v57
	v_cmp_gt_i32_e64 s[6:7], s30, v56
	s_and_b64 s[4:5], s[6:7], s[4:5]
	s_waitcnt lgkmcnt(0)
	v_mfma_f32_16x16x32_bf16 v[56:59], v[60:63], v[0:3], 0
	s_and_b64 s[4:5], vcc, s[4:5]
	v_add_u32_e32 v60, 0x70, v41
	v_cndmask_b32_e64 v95, v179, 0, s[4:5]
	s_movk_i32 s4, 0xff8f
	v_sub_u32_e32 v61, v45, v60
	v_cmp_lt_i32_e32 vcc, s4, v41
	v_cmp_gt_u32_e64 s[4:5], s49, v61
	v_cmp_gt_i32_e64 s[6:7], s30, v60
	s_and_b64 s[4:5], s[6:7], s[4:5]
	s_and_b64 s[4:5], vcc, s[4:5]
	v_add_u32_e32 v60, 0x71, v41
	v_cndmask_b32_e64 v96, v179, 0, s[4:5]
	s_movk_i32 s4, 0xff8e
	v_sub_u32_e32 v61, v45, v60
	v_cmp_lt_i32_e32 vcc, s4, v41
	v_cmp_gt_u32_e64 s[4:5], s49, v61
	v_cmp_gt_i32_e64 s[6:7], s30, v60
	s_and_b64 s[4:5], s[6:7], s[4:5]
	s_and_b64 s[4:5], vcc, s[4:5]
	v_add_u32_e32 v60, 0x72, v41
	v_cndmask_b32_e64 v97, v179, 0, s[4:5]
	s_movk_i32 s4, 0xff8d
	v_sub_u32_e32 v61, v45, v60
	v_cmp_lt_i32_e32 vcc, s4, v41
	v_cmp_gt_u32_e64 s[4:5], s49, v61
	v_cmp_gt_i32_e64 s[6:7], s30, v60
	ds_read_b128 v[60:63], v49 offset:16384
	v_mfma_f32_16x16x32_bf16 v[56:59], v[64:67], v[8:11], v[56:59]
	ds_read_b128 v[64:67], v50 offset:16384
	ds_read_b128 v[72:75], v50 offset:18432
	s_and_b64 s[4:5], s[6:7], s[4:5]
	s_and_b64 s[4:5], vcc, s[4:5]
	v_add_u32_e32 v68, 0x73, v41
	v_cndmask_b32_e64 v98, v179, 0, s[4:5]
	s_movk_i32 s4, 0xff8c
	v_sub_u32_e32 v69, v45, v68
	v_cmp_lt_i32_e32 vcc, s4, v41
	v_cmp_gt_u32_e64 s[4:5], s49, v69
	v_cmp_gt_i32_e64 s[6:7], s30, v68
	ds_read_b128 v[68:71], v49 offset:18432
	s_waitcnt lgkmcnt(3)
	v_mfma_f32_16x16x32_bf16 v[60:63], v[60:63], v[0:3], 0
	s_and_b64 s[4:5], s[6:7], s[4:5]
	s_and_b64 s[4:5], vcc, s[4:5]
	v_add_u32_e32 v50, 0x80, v41
	v_cndmask_b32_e64 v49, v179, 0, s[4:5]
	s_waitcnt lgkmcnt(2)
; template <int NKT, typename KofsF, typename BiasF> ...
;     ...
;     for (int j = 0; j < 4; ++j) s[kt][j] = acc[j] + bias(kt, g * 4 + j, fr);
;   }
;   float mx = -INFINITY;
; #pragma unroll
;   for (int kt = 0; kt < NKT; ++kt)
; #pragma unroll
;     for (int j = 0; j < 4; ++j) mx = fmaxf(mx, s[kt][j]);
;   mx = fmaxf(mx, bperm_xor(mx, lane, 16));
;   mx = fmaxf(mx, bperm_xor(mx, lane, 32));
; __device__ __forceinline__ void attnA_item(unsigned char* ws, int dil, int item, bool first, unsigned char* lds, int wv_) {
;     ...
;   auto bias = [&](int kt, int kj, int frq) -> float {
;     int ik = i0 - 64 + 16 * w + 16 * kt + kj;
;     int iqq = i0 + 16 * w + frq;
;     int dd = iqq - ik;
;     bool ok = (ik >= 0) && (ik < m) && (dd <= 64) && (dd >= -64);
;     return ok ? 0.f : -INFINITY;
;   };
	v_mfma_f32_16x16x32_bf16 v[60:63], v[64:67], v[8:11], v[60:63]
	s_movk_i32 s4, 0xff7f
	v_sub_u32_e32 v64, v45, v50
	v_cmp_lt_i32_e32 vcc, s4, v41
	v_cmp_gt_u32_e64 s[4:5], s49, v64
	v_cmp_gt_i32_e64 s[6:7], s30, v50
	s_and_b64 s[4:5], s[6:7], s[4:5]
	s_and_b64 s[4:5], vcc, s[4:5]
	v_add_u32_e32 v64, 0x81, v41
	v_cndmask_b32_e64 v50, v179, 0, s[4:5]
	s_movk_i32 s4, 0xff7e
	v_sub_u32_e32 v65, v45, v64
	v_cmp_lt_i32_e32 vcc, s4, v41
	v_cmp_gt_u32_e64 s[4:5], s49, v65
	v_cmp_gt_i32_e64 s[6:7], s30, v64
	s_and_b64 s[4:5], s[6:7], s[4:5]
	s_and_b64 s[4:5], vcc, s[4:5]
	v_add_u32_e32 v64, 0x82, v41
	v_cndmask_b32_e64 v99, v179, 0, s[4:5]
	s_movk_i32 s4, 0xff7d
	v_sub_u32_e32 v65, v45, v64
	v_cmp_lt_i32_e32 vcc, s4, v41
	v_cmp_gt_u32_e64 s[4:5], s49, v65
	v_cmp_gt_i32_e64 s[6:7], s30, v64
	s_and_b64 s[4:5], s[6:7], s[4:5]
	s_and_b64 s[4:5], vcc, s[4:5]
	v_add_u32_e32 v64, 0x83, v41
	s_waitcnt lgkmcnt(0)
	v_mfma_f32_16x16x32_bf16 v[0:3], v[68:71], v[0:3], 0
	v_cndmask_b32_e64 v100, v179, 0, s[4:5]
	s_movk_i32 s4, 0xff7c
	v_sub_u32_e32 v65, v45, v64
	v_cmp_lt_i32_e32 vcc, s4, v41
	v_cmp_gt_u32_e64 s[4:5], s49, v65
	v_cmp_gt_i32_e64 s[6:7], s30, v64
	s_and_b64 s[4:5], s[6:7], s[4:5]
	s_and_b64 s[4:5], vcc, s[4:5]
	v_mfma_f32_16x16x32_bf16 v[64:67], v[72:75], v[8:11], v[0:3]
	v_cndmask_b32_e64 v68, v179, 0, s[4:5]
	s_movk_i32 s4, 0xff6f
	v_cmp_lt_i32_e32 vcc, s4, v41
	v_add_u32_e32 v0, 0x90, v41
	v_sub_u32_e32 v1, v45, v0
	v_cmp_gt_u32_e64 s[4:5], s49, v1
	v_cmp_gt_i32_e64 s[6:7], s30, v0
	s_and_b64 s[4:5], s[6:7], s[4:5]
	s_and_b64 s[4:5], vcc, s[4:5]
	v_add_u32_e32 v1, 0x91, v41
	v_cndmask_b32_e64 v0, v179, 0, s[4:5]
	s_movk_i32 s4, 0xff6e
	v_sub_u32_e32 v2, v45, v1
	v_cmp_lt_i32_e32 vcc, s4, v41
	v_cmp_gt_u32_e64 s[4:5], s49, v2
	v_cmp_gt_i32_e64 s[6:7], s30, v1
	s_and_b64 s[4:5], s[6:7], s[4:5]
	s_and_b64 s[4:5], vcc, s[4:5]
	v_add_u32_e32 v2, 0x92, v41
	v_cndmask_b32_e64 v1, v179, 0, s[4:5]
	s_movk_i32 s4, 0xff6d
	v_sub_u32_e32 v3, v45, v2
	v_cmp_lt_i32_e32 vcc, s4, v41
	v_cmp_gt_u32_e64 s[4:5], s49, v3
	v_cmp_gt_i32_e64 s[6:7], s30, v2
	s_and_b64 s[4:5], s[6:7], s[4:5]
	s_and_b64 s[4:5], vcc, s[4:5]
	v_add_u32_e32 v3, 0x93, v41
	v_cndmask_b32_e64 v2, v179, 0, s[4:5]
	s_movk_i32 s4, 0xff6c
	v_sub_u32_e32 v8, v45, v3
	v_cmp_lt_i32_e32 vcc, s4, v41
	v_cmp_gt_u32_e64 s[4:5], s49, v8
	v_cmp_gt_i32_e64 s[6:7], s30, v3
	s_and_b64 s[4:5], s[6:7], s[4:5]
	s_and_b64 s[4:5], vcc, s[4:5]
	v_cndmask_b32_e64 v9, v179, 0, s[4:5]
	v_add_f32_e32 v5, v5, v42
	v_add_f32_e32 v4, v4, v40
	s_mov_b32 s4, 0xff800000
	v_add_f32_e32 v10, v0, v64
	v_add_f32_e32 v7, v7, v44
	v_add_f32_e32 v6, v6, v43
	v_max3_f32 v0, v4, s4, v5
	v_add_f32_e32 v13, v13, v47
	v_add_f32_e32 v12, v12, v46
	v_max3_f32 v0, v0, v6, v7
	v_add_f32_e32 v15, v15, v51
	v_add_f32_e32 v14, v14, v48
	v_max3_f32 v0, v0, v12, v13
	v_add_f32_e32 v49, v49, v59
	v_add_f32_e32 v17, v77, v17
	v_add_f32_e32 v59, v76, v16
	v_max3_f32 v0, v0, v14, v15
	v_add_f32_e32 v19, v79, v19
	v_add_f32_e32 v18, v78, v18
	v_max3_f32 v0, v0, v59, v17
	v_add_f32_e32 v21, v81, v21
	v_add_f32_e32 v20, v80, v20
	v_max3_f32 v0, v0, v18, v19
	v_add_f32_e32 v23, v83, v23
	v_add_f32_e32 v22, v82, v22
	v_max3_f32 v0, v0, v20, v21
	v_add_f32_e32 v25, v85, v25
	v_add_f32_e32 v24, v84, v24
	v_max3_f32 v0, v0, v22, v23
	v_add_f32_e32 v27, v87, v27
	v_add_f32_e32 v26, v86, v26
	v_max3_f32 v0, v0, v24, v25
	v_add_f32_e32 v29, v89, v29
	v_add_f32_e32 v28, v88, v28
	v_max3_f32 v0, v0, v26, v27
	v_add_f32_e32 v31, v91, v31
	v_add_f32_e32 v30, v90, v30
	v_max3_f32 v0, v0, v28, v29
	v_add_f32_e32 v53, v93, v53
	v_add_f32_e32 v52, v92, v52
	v_max3_f32 v0, v0, v30, v31
	v_add_f32_e32 v55, v95, v55
	v_add_f32_e32 v54, v94, v54
	v_max3_f32 v0, v0, v52, v53
	v_add_f32_e32 v57, v97, v57
	v_add_f32_e32 v56, v96, v56
	v_max3_f32 v0, v0, v54, v55
	v_add_f32_e32 v58, v98, v58
	v_max3_f32 v0, v0, v56, v57
	v_add_f32_e32 v45, v99, v61
	v_add_f32_e32 v50, v50, v60
	v_max3_f32 v0, v0, v58, v49
	v_add_f32_e32 v11, v68, v63
	v_add_f32_e32 v41, v100, v62
	v_max3_f32 v0, v0, v50, v45
	v_add_f32_e32 v8, v1, v65
	v_max3_f32 v0, v0, v41, v11
	v_add_f32_e32 v3, v2, v66
	v_add_f32_e32 v2, v9, v67
	v_max3_f32 v0, v0, v10, v8
	v_lshlrev_b32_e32 v9, 2, v39
	v_max3_f32 v0, v0, v3, v2
	v_xor_b32_e32 v1, 64, v9
	ds_bpermute_b32 v16, v1, v0
	s_waitcnt lgkmcnt(0)
	v_max_f32_e32 v16, v16, v16
	v_max_f32_e32 v16, v0, v16
	v_xor_b32_e32 v0, 0x80, v9
	ds_bpermute_b32 v9, v0, v16
	s_waitcnt lgkmcnt(0)
; template <int NKT, typename KofsF, typename BiasF> ...
;     ...
;   if (has_sink) mx = fmaxf(mx, sinkv);
;   float l = 0.f;
; #pragma unroll
;   for (int kt = 0; kt < NKT; ++kt)
; #pragma unroll
;     for (int j = 0; j < 4; ++j) {
;       float pz = exp2f((s[kt][j] - mx) * 1.4426950408889634f);
;       l += pz;
;       s[kt][j] = pz;
;     }
;   l += bperm_xor(l, lane, 16);
;   l += bperm_xor(l, lane, 32);
;   if (has_sink) l += exp2f((sinkv - mx) * 1.4426950408889634f);
; #pragma unroll
;   for (int dt = 0; dt < 4; ++dt) oacc[dt] = f32x4{0.f, 0.f, 0.f, 0.f};
; #pragma unroll
;   for (int u = 0; u < NKT / 2; ++u) {
;     bf16x8 bp;
; #pragma unroll
;     for (int i = 0; i < 4; ++i) {
;       bp[i] = (short)f2bf(s[2 * u][i]);
;       bp[4 + i] = (short)f2bf(s[2 * u + 1][i]);
;     }
;     int k0 = kofs(2 * u) + g * 4, k1 = kofs(2 * u + 1) + g * 4;
; #pragma unroll
;     for (int dt = 0; dt < 4; ++dt) {
;       const u16* vrow = Vt + (dt * 16 + fr) * NKP;
;       uint2 v0 = *(const uint2*)(vrow + k0);
;       uint2 v1 = *(const uint2*)(vrow + k1);
	v_max_f32_e32 v9, v9, v9
	v_max_f32_e32 v16, v16, v9
	v_sub_f32_e32 v4, v4, v16
	v_mul_f32_e32 v9, 0x3fb8aa3b, v4
	v_sub_f32_e32 v5, v5, v16
	v_sub_f32_e32 v6, v6, v16
	v_exp_f32_e32 v4, v9
	v_mul_f32_e32 v9, 0x3fb8aa3b, v5
	v_cmp_gt_f32_e64 s[4:5], s46, v9
	v_mul_f32_e32 v39, 0x3fb8aa3b, v6
	v_sub_f32_e32 v7, v7, v16
	v_cndmask_b32_e64 v9, 0, v180, s[4:5]
	v_fmac_f32_e32 v9, 0x3fb8aa3b, v5
	v_exp_f32_e32 v5, v9
	v_mul_f32_e32 v40, 0x3fb8aa3b, v7
	v_sub_f32_e32 v12, v12, v16
	v_exp_f32_e32 v6, v39
	v_sub_f32_e32 v13, v13, v16
	v_exp_f32_e32 v7, v40
	v_mul_f32_e32 v40, 0x3fb8aa3b, v13
	v_sub_f32_e32 v14, v14, v16
	v_mul_f32_e32 v39, 0x3fb8aa3b, v12
	v_sub_f32_e32 v15, v15, v16
	v_sub_f32_e32 v17, v17, v16
	v_exp_f32_e32 v12, v39
	v_mul_f32_e32 v42, 0x3fb8aa3b, v17
	v_exp_f32_e32 v13, v40
	v_mul_f32_e32 v40, 0x3fb8aa3b, v15
	v_sub_f32_e32 v18, v18, v16
	v_mul_f32_e32 v39, 0x3fb8aa3b, v14
	v_sub_f32_e32 v19, v19, v16
	v_exp_f32_e32 v14, v39
	v_cndmask_b32_e64 v9, 0, v178, s[4:5]
	v_exp_f32_e32 v15, v40
	v_ldexp_f32 v5, v5, v9
	v_add_f32_e32 v9, v4, v5
	v_sub_f32_e32 v39, v59, v16
	v_mul_f32_e32 v40, 0x3fb8aa3b, v39
	v_add_f32_e32 v9, v6, v9
	v_add_f32_e32 v9, v7, v9
	v_exp_f32_e32 v39, v40
	v_add_f32_e32 v9, v12, v9
	v_exp_f32_e32 v17, v42
	v_mul_f32_e32 v42, 0x3fb8aa3b, v19
	v_add_f32_e32 v9, v13, v9
	v_mul_f32_e32 v40, 0x3fb8aa3b, v18
	v_add_f32_e32 v9, v14, v9
	v_add_f32_e32 v9, v15, v9
	v_exp_f32_e32 v18, v40
	v_add_f32_e32 v9, v39, v9
	v_mov_b32_e32 v40, v18
	v_exp_f32_e32 v19, v42
	v_add_f32_e32 v9, v17, v9
	v_add_f32_e32 v9, v40, v9
	v_mov_b32_e32 v42, v19
	v_sub_f32_e32 v18, v20, v16
	v_mul_f32_e32 v19, 0x3fb8aa3b, v18
	v_sub_f32_e32 v20, v21, v16
	v_mul_f32_e32 v21, 0x3fb8aa3b, v20
	v_exp_f32_e32 v18, v19
	v_sub_f32_e32 v11, v11, v16
	v_mov_b32_e32 v43, v18
	v_exp_f32_e32 v20, v21
	v_add_f32_e32 v9, v42, v9
	v_add_f32_e32 v9, v43, v9
	v_mov_b32_e32 v44, v20
	v_sub_f32_e32 v18, v22, v16
	v_mul_f32_e32 v19, 0x3fb8aa3b, v18
	v_sub_f32_e32 v20, v23, v16
	v_mul_f32_e32 v21, 0x3fb8aa3b, v20
	v_exp_f32_e32 v18, v19
	v_add_f32_e32 v9, v44, v9
	v_mov_b32_e32 v46, v18
	v_exp_f32_e32 v20, v21
	v_add_f32_e32 v9, v46, v9
	s_movk_i32 s4, 0x230
	v_mov_b32_e32 v47, v20
	v_sub_f32_e32 v18, v24, v16
	v_mul_f32_e32 v19, 0x3fb8aa3b, v18
	v_sub_f32_e32 v20, v25, v16
	v_mul_f32_e32 v21, 0x3fb8aa3b, v20
	v_exp_f32_e32 v18, v19
	v_add_f32_e32 v9, v47, v9
	v_mov_b32_e32 v48, v18
	v_exp_f32_e32 v20, v21
	v_add_f32_e32 v9, v48, v9
	v_bfe_u32 v23, v5, 16, 1
	v_mov_b32_e32 v51, v20
	v_sub_f32_e32 v18, v26, v16
	v_mul_f32_e32 v19, 0x3fb8aa3b, v18
	v_sub_f32_e32 v20, v27, v16
	v_mul_f32_e32 v21, 0x3fb8aa3b, v20
	v_exp_f32_e32 v18, v19
	v_bfe_u32 v24, v4, 16, 1
	v_mov_b32_e32 v59, v18
	v_exp_f32_e32 v20, v21
	v_add_f32_e32 v9, v51, v9
	v_add3_u32 v24, v4, v24, s48
	v_mov_b32_e32 v60, v20
	v_sub_f32_e32 v18, v28, v16
	v_mul_f32_e32 v19, 0x3fb8aa3b, v18
	v_sub_f32_e32 v20, v29, v16
	v_mul_f32_e32 v21, 0x3fb8aa3b, v20
	v_exp_f32_e32 v18, v19
	v_add3_u32 v23, v5, v23, s48
	v_mov_b32_e32 v61, v18
	v_exp_f32_e32 v20, v21
	v_lshlrev_b32_e32 v4, 5, v36
	v_lshlrev_b32_e32 v5, 3, v37
	v_mov_b32_e32 v62, v20
	v_sub_f32_e32 v18, v30, v16
	v_mul_f32_e32 v19, 0x3fb8aa3b, v18
	v_sub_f32_e32 v20, v31, v16
	v_mul_f32_e32 v21, 0x3fb8aa3b, v20
	v_exp_f32_e32 v18, v19
	v_add_f32_e32 v9, v59, v9
	v_mov_b32_e32 v30, v18
	v_exp_f32_e32 v20, v21
	v_bfe_u32 v22, v6, 16, 1
	v_add_f32_e32 v9, v60, v9
	v_mov_b32_e32 v31, v20
	v_sub_f32_e32 v18, v52, v16
	v_mul_f32_e32 v19, 0x3fb8aa3b, v18
	v_sub_f32_e32 v20, v53, v16
	v_mul_f32_e32 v21, 0x3fb8aa3b, v20
	v_exp_f32_e32 v18, v19
	v_add3_u32 v22, v6, v22, s48
	v_mov_b32_e32 v52, v18
	v_exp_f32_e32 v20, v21
	v_add_f32_e32 v9, v61, v9
	v_add_f32_e32 v9, v62, v9
	v_mov_b32_e32 v53, v20
	v_sub_f32_e32 v18, v54, v16
	v_mul_f32_e32 v19, 0x3fb8aa3b, v18
	v_sub_f32_e32 v20, v55, v16
	v_mul_f32_e32 v21, 0x3fb8aa3b, v20
	v_exp_f32_e32 v18, v19
	v_add_f32_e32 v9, v30, v9
	v_mov_b32_e32 v54, v18
	v_exp_f32_e32 v20, v21
	v_add_f32_e32 v9, v31, v9
	v_add_f32_e32 v9, v52, v9
	v_mov_b32_e32 v55, v20
	v_sub_f32_e32 v18, v56, v16
	v_mul_f32_e32 v19, 0x3fb8aa3b, v18
	v_sub_f32_e32 v20, v57, v16
	v_mul_f32_e32 v21, 0x3fb8aa3b, v20
	v_exp_f32_e32 v18, v19
	v_add_f32_e32 v9, v53, v9
	v_mov_b32_e32 v56, v18
	v_exp_f32_e32 v20, v21
	v_add_f32_e32 v9, v54, v9
	v_add_f32_e32 v9, v55, v9
	v_mov_b32_e32 v57, v20
	v_sub_f32_e32 v18, v58, v16
	v_mul_f32_e32 v19, 0x3fb8aa3b, v18
	v_sub_f32_e32 v20, v49, v16
	v_mul_f32_e32 v21, 0x3fb8aa3b, v20
	v_exp_f32_e32 v18, v19
	v_add_f32_e32 v9, v56, v9
	v_mov_b32_e32 v49, v18
	v_exp_f32_e32 v20, v21
	v_add_f32_e32 v9, v57, v9
	v_bfe_u32 v36, v39, 16, 1
	v_mov_b32_e32 v58, v20
	v_sub_f32_e32 v18, v50, v16
	v_mul_f32_e32 v19, 0x3fb8aa3b, v18
	v_sub_f32_e32 v20, v45, v16
	v_mul_f32_e32 v21, 0x3fb8aa3b, v20
	v_exp_f32_e32 v18, v19
	v_add_f32_e32 v9, v49, v9
	v_mov_b32_e32 v45, v18
	v_exp_f32_e32 v20, v21
	v_bfe_u32 v21, v7, 16, 1
	v_add3_u32 v25, v7, v21, s48
	v_mov_b32_e32 v50, v20
	v_sub_f32_e32 v18, v41, v16
	v_mul_f32_e32 v19, 0x3fb8aa3b, v18
	v_mul_f32_e32 v20, 0x3fb8aa3b, v11
	v_sub_f32_e32 v41, v10, v16
	v_exp_f32_e32 v18, v19
	v_mad_u32_u24 v10, v38, s4, 0
	v_mov_b32_e32 v63, v18
	v_exp_f32_e32 v11, v20
	v_bfe_u32 v19, v13, 16, 1
	v_bfe_u32 v20, v12, 16, 1
	v_add3_u32 v26, v10, v4, v5
	v_mov_b32_e32 v64, v11
	v_bfe_u32 v11, v15, 16, 1
	v_bfe_u32 v18, v14, 16, 1
	v_add3_u32 v20, v12, v20, s48
	v_add3_u32 v19, v13, v19, s48
	v_add_u32_e32 v65, 0x8800, v26
	v_add_u32_e32 v66, 0xa800, v26
	v_add_u32_e32 v67, 0xc800, v26
	v_add_u32_e32 v68, 0xf000, v26
	ds_read2_b64 v[4:7], v65 offset1:4
	v_add3_u32 v14, v14, v18, s48
	v_add3_u32 v15, v15, v11, s48
	ds_read2_b64 v[10:13], v66 offset0:96 offset1:100
	v_perm_b32 v20, v19, v20, s47
	v_perm_b32 v19, v25, v22, s47
	v_perm_b32 v18, v23, v24, s47
	ds_read2_b64 v[22:25], v67 offset0:192 offset1:196
	ds_read2_b64 v[26:29], v68 offset0:32 offset1:36
	v_perm_b32 v21, v15, v14, s47
	v_mul_f32_e32 v14, 0x3fb8aa3b, v41
	v_cmp_gt_f32_e32 vcc, s46, v14
	s_waitcnt lgkmcnt(3)
; template <int NKT, typename KofsF, typename BiasF> ...
;     ...
; #pragma unroll
;   for (int dt = 0; dt < 4; ++dt) oacc[dt] = f32x4{0.f, 0.f, 0.f, 0.f};
; #pragma unroll
;   for (int u = 0; u < NKT / 2; ++u) {
;     bf16x8 bp;
; #pragma unroll
;     for (int i = 0; i < 4; ++i) {
;       bp[i] = (short)f2bf(s[2 * u][i]);
;       bp[4 + i] = (short)f2bf(s[2 * u + 1][i]);
;     }
;     int k0 = kofs(2 * u) + g * 4, k1 = kofs(2 * u + 1) + g * 4;
; #pragma unroll
;     for (int dt = 0; dt < 4; ++dt) {
;       const u16* vrow = Vt + (dt * 16 + fr) * NKP;
;       uint2 v0 = *(const uint2*)(vrow + k0);
;       uint2 v1 = *(const uint2*)(vrow + k1);
;       union { uint4 q; bf16x8 v; } cv;
;       cv.q = make_uint4(v0.x, v0.y, v1.x, v1.y);
;       oacc[dt] = __builtin_amdgcn_mfma_f32_16x16x32_bf16(cv.v, bp, oacc[dt], 0, 0, 0);
;     }
;   }
;   m_out = mx;
;   l_out = l;
; __device__ __forceinline__ void attnA_item(unsigned char* ws, int dil, int item, bool first, unsigned char* lds, int wv_) {
;     ...
;   float* ml = aml + ((size_t)tq * 12 + h) * 2;
;   u16* op = O + (size_t)tq * D_ + h * 64;
;   if (first) {
	v_mfma_f32_16x16x32_bf16 v[4:7], v[4:7], v[18:21], 0
	v_add3_u32 v71, v39, v36, s48
	v_cndmask_b32_e32 v14, 0, v180, vcc
	v_fmac_f32_e32 v14, 0x3fb8aa3b, v41
	s_waitcnt lgkmcnt(2)
	v_mfma_f32_16x16x32_bf16 v[10:13], v[10:13], v[18:21], 0
	ds_read2_b64 v[36:39], v66 offset0:104 offset1:108
	v_add_f32_e32 v9, v58, v9
	v_add_f32_e32 v9, v45, v9
	s_waitcnt lgkmcnt(2)
	v_mfma_f32_16x16x32_bf16 v[22:25], v[22:25], v[18:21], 0
	v_exp_f32_e32 v14, v14
	v_add_f32_e32 v9, v50, v9
	v_add_f32_e32 v9, v63, v9
	s_waitcnt lgkmcnt(1)
	v_mfma_f32_16x16x32_bf16 v[18:21], v[26:29], v[18:21], 0
	v_bfe_u32 v26, v43, 16, 1
	v_bfe_u32 v27, v42, 16, 1
	v_bfe_u32 v28, v40, 16, 1
	v_bfe_u32 v29, v17, 16, 1
	v_add3_u32 v17, v17, v29, s48
	v_add3_u32 v40, v40, v28, s48
	v_add3_u32 v41, v42, v27, s48
	v_add3_u32 v42, v43, v26, s48
	ds_read2_b64 v[26:29], v65 offset0:8 offset1:12
	v_add_f32_e32 v69, v64, v9
	v_cndmask_b32_e32 v9, 0, v178, vcc
	v_ldexp_f32 v70, v14, v9
	v_bfe_u32 v9, v47, 16, 1
	v_bfe_u32 v14, v46, 16, 1
	v_bfe_u32 v15, v44, 16, 1
	v_add3_u32 v15, v44, v15, s48
	v_add3_u32 v14, v46, v14, s48
	v_add3_u32 v9, v47, v9, s48
	v_perm_b32 v43, v9, v14, s47
	v_perm_b32 v42, v15, v42, s47
	v_perm_b32 v41, v41, v40, s47
	v_perm_b32 v40, v17, v71, s47
	v_sub_f32_e32 v17, v8, v16
	v_mul_f32_e32 v44, 0x3fb8aa3b, v17
	s_waitcnt lgkmcnt(0)
	v_mfma_f32_16x16x32_bf16 v[4:7], v[26:29], v[40:43], v[4:7]
	ds_read2_b64 v[26:29], v67 offset0:200 offset1:204
	v_cmp_gt_f32_e32 vcc, s46, v44
	v_sub_f32_e32 v3, v3, v16
	v_mfma_f32_16x16x32_bf16 v[8:11], v[36:39], v[40:43], v[10:13]
	v_cndmask_b32_e32 v36, 0, v180, vcc
	v_fmac_f32_e32 v36, 0x3fb8aa3b, v17
	v_exp_f32_e32 v17, v36
	ds_read2_b64 v[12:15], v68 offset0:40 offset1:44
	s_waitcnt lgkmcnt(1)
	v_mfma_f32_16x16x32_bf16 v[22:25], v[26:29], v[40:43], v[22:25]
	v_bfe_u32 v28, v51, 16, 1
	v_cndmask_b32_e32 v26, 0, v178, vcc
	v_ldexp_f32 v17, v17, v26
	s_waitcnt lgkmcnt(0)
	v_mfma_f32_16x16x32_bf16 v[12:15], v[12:15], v[40:43], v[18:21]
	s_nop 2
	v_bfe_u32 v18, v62, 16, 1
	v_bfe_u32 v19, v61, 16, 1
	v_bfe_u32 v20, v60, 16, 1
	v_bfe_u32 v21, v59, 16, 1
	v_add3_u32 v41, v51, v28, s48
	v_add3_u32 v42, v59, v21, s48
	v_add3_u32 v43, v60, v20, s48
	v_add3_u32 v28, v61, v19, s48
	v_add3_u32 v46, v62, v18, s48
	ds_read2_b64 v[18:21], v65 offset0:16 offset1:20
	v_bfe_u32 v26, v31, 16, 1
	v_bfe_u32 v27, v30, 16, 1
	v_bfe_u32 v29, v48, 16, 1
	v_add3_u32 v40, v48, v29, s48
	v_add3_u32 v27, v30, v27, s48
	v_add3_u32 v26, v31, v26, s48
	v_perm_b32 v29, v26, v27, s47
	v_perm_b32 v28, v46, v28, s47
	v_perm_b32 v27, v43, v42, s47
	v_perm_b32 v26, v41, v40, s47
	ds_read2_b64 v[36:39], v66 offset0:112 offset1:116
	ds_read2_b64 v[40:43], v67 offset0:208 offset1:212
	s_waitcnt lgkmcnt(2)
	v_mfma_f32_16x16x32_bf16 v[4:7], v[18:21], v[26:29], v[4:7]
	ds_read2_b64 v[18:21], v68 offset0:48 offset1:52
	v_mul_f32_e32 v31, 0x3fb8aa3b, v3
	v_cmp_gt_f32_e32 vcc, s46, v31
	s_waitcnt lgkmcnt(2)
	v_mfma_f32_16x16x32_bf16 v[8:11], v[36:39], v[26:29], v[8:11]
	v_cndmask_b32_e32 v31, 0, v180, vcc
	v_sub_f32_e32 v2, v2, v16
	v_fmac_f32_e32 v31, 0x3fb8aa3b, v3
	s_waitcnt lgkmcnt(1)
	v_mfma_f32_16x16x32_bf16 v[22:25], v[40:43], v[26:29], v[22:25]
	v_exp_f32_e32 v3, v31
	v_cndmask_b32_e32 v31, 0, v178, vcc
	v_add_f32_e32 v44, v70, v69
	s_waitcnt lgkmcnt(0)
	v_mfma_f32_16x16x32_bf16 v[12:15], v[18:21], v[26:29], v[12:15]
	v_bfe_u32 v26, v58, 16, 1
	v_bfe_u32 v27, v49, 16, 1
	v_bfe_u32 v28, v57, 16, 1
	v_bfe_u32 v18, v56, 16, 1
	v_bfe_u32 v19, v55, 16, 1
	v_bfe_u32 v20, v54, 16, 1
	v_bfe_u32 v21, v53, 16, 1
	v_bfe_u32 v29, v52, 16, 1
	v_add3_u32 v36, v52, v29, s48
	v_add3_u32 v40, v53, v21, s48
	v_add3_u32 v37, v54, v20, s48
	v_add3_u32 v41, v55, v19, s48
	v_add3_u32 v38, v56, v18, s48
	ds_read2_b64 v[18:21], v65 offset0:24 offset1:28
	v_add3_u32 v42, v57, v28, s48
	v_add3_u32 v39, v49, v27, s48
	v_add3_u32 v43, v58, v26, s48
	ds_read2_b64 v[26:29], v66 offset0:120 offset1:124
	v_perm_b32 v39, v43, v39, s47
	v_perm_b32 v38, v42, v38, s47
	v_perm_b32 v37, v41, v37, s47
	v_perm_b32 v36, v40, v36, s47
	v_mul_f32_e32 v40, 0x3fb8aa3b, v2
	v_cmp_gt_f32_e32 vcc, s46, v40
	s_waitcnt lgkmcnt(1)
	v_mfma_f32_16x16x32_bf16 v[4:7], v[18:21], v[36:39], v[4:7]
	ds_read2_b64 v[18:21], v67 offset0:216 offset1:220
	v_cndmask_b32_e32 v40, 0, v180, vcc
	v_fmac_f32_e32 v40, 0x3fb8aa3b, v2
	s_waitcnt lgkmcnt(1)
	v_mfma_f32_16x16x32_bf16 v[8:11], v[26:29], v[36:39], v[8:11]
	ds_read2_b64 v[26:29], v68 offset0:56 offset1:60
	v_exp_f32_e32 v2, v40
	v_ldexp_f32 v31, v3, v31
	s_waitcnt lgkmcnt(1)
	v_mfma_f32_16x16x32_bf16 v[18:21], v[18:21], v[36:39], v[22:25]
	v_cndmask_b32_e32 v3, 0, v178, vcc
	v_ldexp_f32 v40, v2, v3
	v_bfe_u32 v2, v40, 16, 1
	s_waitcnt lgkmcnt(0)
	v_mfma_f32_16x16x32_bf16 v[22:25], v[26:29], v[36:39], v[12:15]
	v_bfe_u32 v27, v45, 16, 1
	v_add3_u32 v41, v45, v27, s48
	ds_read2_b64 v[36:39], v66 offset0:128 offset1:132
	v_bfe_u32 v12, v70, 16, 1
	v_bfe_u32 v13, v64, 16, 1
	v_bfe_u32 v14, v63, 16, 1
	v_bfe_u32 v15, v50, 16, 1
	v_add3_u32 v42, v50, v15, s48
	v_add3_u32 v27, v63, v14, s48
	v_add3_u32 v43, v64, v13, s48
	v_add3_u32 v28, v70, v12, s48
	ds_read2_b64 v[12:15], v65 offset0:32 offset1:36
	v_bfe_u32 v3, v31, 16, 1
	v_bfe_u32 v26, v17, 16, 1
	v_add_f32_e32 v30, v17, v44
	v_add3_u32 v17, v17, v26, s48
	v_add3_u32 v3, v31, v3, s48
	v_add3_u32 v2, v40, v2, s48
	v_perm_b32 v29, v2, v3, s47
	v_perm_b32 v28, v17, v28, s47
	v_perm_b32 v27, v43, v27, s47
	v_perm_b32 v26, v42, v41, s47
	s_ashr_i32 s4, s40, 31
	v_bfe_u32 v17, v33, 4, 2
	s_waitcnt lgkmcnt(0)
	v_mfma_f32_16x16x32_bf16 v[12:15], v[12:15], v[26:29], v[4:7]
	v_ashrrev_i32_e32 v33, 31, v32
	s_and_b64 vcc, exec, s[2:3]
	v_lshlrev_b32_e32 v166, 3, v17
	ds_read2_b64 v[2:5], v67 offset0:224 offset1:228
	v_add_f32_e32 v6, v31, v30
	v_add_f32_e32 v6, v40, v6
	v_mfma_f32_16x16x32_bf16 v[8:11], v[36:39], v[26:29], v[8:11]
	ds_read2_b64 v[36:39], v68 offset0:64 offset1:68
	ds_bpermute_b32 v1, v1, v6
	s_waitcnt lgkmcnt(0)
	v_add_f32_e32 v30, v6, v1
	v_mfma_f32_16x16x32_bf16 v[4:7], v[2:5], v[26:29], v[18:21]
	s_nop 2
	ds_bpermute_b32 v18, v0, v30
	v_mov_b32_e32 v20, s40
	v_mov_b32_e32 v21, s4
	v_mfma_f32_16x16x32_bf16 v[0:3], v[36:39], v[26:29], v[22:25]
	v_mad_i64_i32 v[20:21], s[4:5], v32, 12, v[20:21]
	v_readlane_b32 s4, v251, 36
	s_nop 0
	v_lshlrev_b64 v[22:23], 12, v[32:33]
	v_readlane_b32 s5, v251, 37
	v_lshl_add_u64 v[22:23], s[68:69], 0, v[22:23]
	s_waitcnt lgkmcnt(0)
	v_add_f32_e32 v19, v30, v18
	v_lshl_add_u64 v[20:21], v[20:21], 3, s[4:5]
	v_lshl_add_u64 v[22:23], v[22:23], 0, v[34:35]
	v_cmp_eq_u32_e64 s[4:5], 0, v17
	s_cbranch_vccz .LBB0_312
; __device__ __forceinline__ float bflo(u32 w) { return __uint_as_float(w << 16); }
; __device__ __forceinline__ float bfhi(u32 w) { return __uint_as_float(w & 0xffff0000u); }
; __device__ __forceinline__ u32 pack2(float a, float b) { return (u32)f2bf(a) | ((u32)f2bf(b) << 16); }
; __device__ __forceinline__ void attnA_item(unsigned char* ws, int dil, int item, bool first, unsigned char* lds, int wv_) {
;     ...
;   } else {
;     float mo = ml[0], lo = ml[1];
;     float mn = fmaxf(mo, mb);
;     float ca = lo * __expf(mo - mn), cb = __expf(mb - mn);
;     float ln = ca + cb * lb;
;     float inv = 1.f / ln;
;     __builtin_amdgcn_wave_barrier();
; #pragma unroll
;     for (int dt = 0; dt < 4; ++dt) {
;       uint2 old = *(const uint2*)(op + dt * 16 + g * 4);
;       float o0 = (bflo(old.x) * ca + oacc[dt][0] * cb) * inv;
;       float o1 = (bfhi(old.x) * ca + oacc[dt][1] * cb) * inv;
;       float o2 = (bflo(old.y) * ca + oacc[dt][2] * cb) * inv;
;       float o3 = (bfhi(old.y) * ca + oacc[dt][3] * cb) * inv;
;       *(uint2*)(op + dt * 16 + g * 4) = make_uint2(pack2(o0, o1), pack2(o2, o3));
;     }
;     if (g == 0) { ml[0] = mn; ml[1] = ln; }
	global_load_dwordx2 v[26:27], v[20:21], off
	v_lshl_add_u64 v[28:29], v[22:23], 0, v[166:167]
	global_load_dwordx2 v[30:31], v[28:29], off
	global_load_dwordx2 v[32:33], v[28:29], off offset:32
	global_load_dwordx2 v[34:35], v[28:29], off offset:64
	global_load_dwordx2 v[48:49], v[28:29], off offset:96
	v_max_f32_e32 v24, v16, v16
	v_mov_b32_e32 v38, v13
	v_mov_b32_e32 v39, v15
	v_mov_b32_e32 v40, v8
	v_mov_b32_e32 v41, v10
	v_mov_b32_e32 v42, v9
	v_mov_b32_e32 v43, v11
	v_mov_b32_e32 v36, v12
	v_mov_b32_e32 v37, v14
	v_mov_b32_e32 v44, v4
	v_mov_b32_e32 v45, v6
	v_mov_b32_e32 v46, v5
	v_mov_b32_e32 v47, v7
	s_waitcnt vmcnt(3)
	v_lshlrev_b32_e32 v51, 16, v31
	v_max_f32_e32 v25, v26, v26
	v_max_f32_e32 v24, v25, v24
	v_sub_f32_e32 v25, v26, v24
	v_sub_f32_e32 v26, v16, v24
	v_mul_f32_e32 v25, 0x3fb8aa3b, v25
	v_mul_f32_e32 v26, 0x3fb8aa3b, v26
	v_exp_f32_e32 v54, v25
	v_exp_f32_e32 v55, v26
	v_mov_b32_e32 v18, v27
	v_lshlrev_b32_e32 v50, 16, v30
	v_and_b32_e32 v31, 0xffff0000, v31
	v_pk_mul_f32 v[56:57], v[18:19], v[54:55]
	v_and_b32_e32 v30, 0xffff0000, v30
	s_waitcnt vmcnt(2)
	v_lshlrev_b32_e32 v53, 16, v33
	v_lshlrev_b32_e32 v52, 16, v32
	v_add_f32_e32 v25, v56, v57
	v_mov_b32_e32 v18, v55
	v_pk_mul_f32 v[30:31], v[56:57], v[30:31] op_sel_hi:[0,1]
	v_pk_mul_f32 v[52:53], v[56:57], v[52:53] op_sel_hi:[0,1]
	v_div_scale_f32 v54, s[6:7], v25, v25, 1.0
	v_pk_fma_f32 v[30:31], v[38:39], v[18:19], v[30:31] op_sel_hi:[1,0,1]
	v_pk_fma_f32 v[38:39], v[40:41], v[18:19], v[52:53] op_sel_hi:[1,0,1]
	v_rcp_f32_e32 v40, v54
	v_and_b32_e32 v33, 0xffff0000, v33
	v_and_b32_e32 v32, 0xffff0000, v32
	v_div_scale_f32 v55, vcc, 1.0, v25, 1.0
	v_fma_f32 v41, -v54, v40, 1.0
	v_fmac_f32_e32 v40, v41, v40
	v_pk_mul_f32 v[32:33], v[56:57], v[32:33] op_sel_hi:[0,1]
	v_mul_f32_e32 v41, v55, v40
	v_pk_fma_f32 v[32:33], v[42:43], v[18:19], v[32:33] op_sel_hi:[1,0,1]
	v_fma_f32 v42, -v54, v41, v55
	v_fmac_f32_e32 v41, v42, v40
	v_fma_f32 v42, -v54, v41, v55
	s_waitcnt vmcnt(1)
	v_lshlrev_b32_e32 v27, 16, v35
	v_lshlrev_b32_e32 v26, 16, v34
	v_div_fmas_f32 v40, v42, v40, v41
	v_and_b32_e32 v35, 0xffff0000, v35
	v_and_b32_e32 v34, 0xffff0000, v34
	v_pk_mul_f32 v[50:51], v[56:57], v[50:51] op_sel_hi:[0,1]
	v_pk_mul_f32 v[26:27], v[56:57], v[26:27] op_sel_hi:[0,1]
	v_div_fixup_f32 v40, v40, v25, 1.0
	v_pk_mul_f32 v[34:35], v[56:57], v[34:35] op_sel_hi:[0,1]
	v_pk_fma_f32 v[36:37], v[36:37], v[18:19], v[50:51] op_sel_hi:[1,0,1]
	v_pk_fma_f32 v[26:27], v[44:45], v[18:19], v[26:27] op_sel_hi:[1,0,1]
	v_pk_mul_f32 v[30:31], v[40:41], v[30:31] op_sel_hi:[0,1]
	v_pk_mul_f32 v[32:33], v[40:41], v[32:33] op_sel_hi:[0,1]
	v_pk_fma_f32 v[34:35], v[46:47], v[18:19], v[34:35] op_sel_hi:[1,0,1]
	v_pk_mul_f32 v[36:37], v[40:41], v[36:37] op_sel_hi:[0,1]
	v_pk_mul_f32 v[38:39], v[40:41], v[38:39] op_sel_hi:[0,1]
	v_pk_mul_f32 v[26:27], v[40:41], v[26:27] op_sel_hi:[0,1]
	v_and_b32_sdwa v43, v31, v177 dst_sel:DWORD dst_unused:UNUSED_PAD src0_sel:WORD_1 src1_sel:DWORD
	v_and_b32_sdwa v44, v30, v177 dst_sel:DWORD dst_unused:UNUSED_PAD src0_sel:WORD_1 src1_sel:DWORD
	v_and_b32_sdwa v50, v32, v177 dst_sel:DWORD dst_unused:UNUSED_PAD src0_sel:WORD_1 src1_sel:DWORD
	v_pk_mul_f32 v[34:35], v[40:41], v[34:35] op_sel_hi:[0,1]
	v_and_b32_sdwa v41, v37, v177 dst_sel:DWORD dst_unused:UNUSED_PAD src0_sel:WORD_1 src1_sel:DWORD
	v_and_b32_sdwa v42, v36, v177 dst_sel:DWORD dst_unused:UNUSED_PAD src0_sel:WORD_1 src1_sel:DWORD
	v_and_b32_sdwa v46, v38, v177 dst_sel:DWORD dst_unused:UNUSED_PAD src0_sel:WORD_1 src1_sel:DWORD
	v_and_b32_sdwa v47, v33, v177 dst_sel:DWORD dst_unused:UNUSED_PAD src0_sel:WORD_1 src1_sel:DWORD
	v_and_b32_sdwa v52, v26, v177 dst_sel:DWORD dst_unused:UNUSED_PAD src0_sel:WORD_1 src1_sel:DWORD
	v_add3_u32 v31, v31, v43, s48
	v_add3_u32 v30, v30, v44, s48
	v_add3_u32 v32, v32, v50, s48
	v_and_b32_sdwa v45, v39, v177 dst_sel:DWORD dst_unused:UNUSED_PAD src0_sel:WORD_1 src1_sel:DWORD
	v_and_b32_sdwa v51, v27, v177 dst_sel:DWORD dst_unused:UNUSED_PAD src0_sel:WORD_1 src1_sel:DWORD
	v_and_b32_sdwa v53, v35, v177 dst_sel:DWORD dst_unused:UNUSED_PAD src0_sel:WORD_1 src1_sel:DWORD
	v_and_b32_sdwa v54, v34, v177 dst_sel:DWORD dst_unused:UNUSED_PAD src0_sel:WORD_1 src1_sel:DWORD
	v_add3_u32 v36, v36, v42, s48
	v_add3_u32 v37, v37, v41, s48
	v_add3_u32 v38, v38, v46, s48
	v_add3_u32 v33, v33, v47, s48
	v_add3_u32 v41, v26, v52, s48
	v_and_b32_e32 v26, 0xffff0000, v31
	v_and_b32_e32 v30, 0xffff0000, v30
	v_and_b32_e32 v32, 0xffff0000, v32
	v_add3_u32 v39, v39, v45, s48
	v_add3_u32 v42, v27, v51, s48
	v_add3_u32 v35, v35, v53, s48
	v_add3_u32 v34, v34, v54, s48
	v_and_b32_e32 v31, 0xffff0000, v33
	v_or_b32_sdwa v27, v26, v37 dst_sel:DWORD dst_unused:UNUSED_PAD src0_sel:DWORD src1_sel:WORD_1
	v_or_b32_sdwa v26, v30, v36 dst_sel:DWORD dst_unused:UNUSED_PAD src0_sel:DWORD src1_sel:WORD_1
	v_or_b32_sdwa v30, v32, v38 dst_sel:DWORD dst_unused:UNUSED_PAD src0_sel:DWORD src1_sel:WORD_1
	v_or_b32_sdwa v31, v31, v39 dst_sel:DWORD dst_unused:UNUSED_PAD src0_sel:DWORD src1_sel:WORD_1
	global_store_dwordx2 v[28:29], v[26:27], off
	global_store_dwordx2 v[28:29], v[30:31], off offset:32
	v_and_b32_e32 v26, 0xffff0000, v35
	v_and_b32_e32 v30, 0xffff0000, v34
	v_or_b32_sdwa v27, v26, v42 dst_sel:DWORD dst_unused:UNUSED_PAD src0_sel:DWORD src1_sel:WORD_1
	v_or_b32_sdwa v26, v30, v41 dst_sel:DWORD dst_unused:UNUSED_PAD src0_sel:DWORD src1_sel:WORD_1
	global_store_dwordx2 v[28:29], v[26:27], off offset:64
	s_waitcnt vmcnt(3)
	v_lshlrev_b32_e32 v27, 16, v49
	v_lshlrev_b32_e32 v26, 16, v48
	v_pk_mul_f32 v[26:27], v[56:57], v[26:27] op_sel_hi:[0,1]
	v_mov_b32_e32 v30, v0
	v_mov_b32_e32 v31, v2
	v_pk_fma_f32 v[26:27], v[30:31], v[18:19], v[26:27] op_sel_hi:[1,0,1]
	v_and_b32_e32 v31, 0xffff0000, v49
	v_and_b32_e32 v30, 0xffff0000, v48
	v_pk_mul_f32 v[30:31], v[56:57], v[30:31] op_sel_hi:[0,1]
	v_mov_b32_e32 v32, v1
	v_mov_b32_e32 v33, v3
	v_pk_mul_f32 v[26:27], v[40:41], v[26:27] op_sel_hi:[0,1]
	v_pk_fma_f32 v[30:31], v[32:33], v[18:19], v[30:31] op_sel_hi:[1,0,1]
	v_and_b32_sdwa v18, v27, v177 dst_sel:DWORD dst_unused:UNUSED_PAD src0_sel:WORD_1 src1_sel:DWORD
	v_pk_mul_f32 v[30:31], v[40:41], v[30:31] op_sel_hi:[0,1]
	v_and_b32_sdwa v32, v26, v177 dst_sel:DWORD dst_unused:UNUSED_PAD src0_sel:WORD_1 src1_sel:DWORD
	v_add3_u32 v26, v26, v32, s48
	v_add3_u32 v18, v27, v18, s48
	v_and_b32_sdwa v27, v31, v177 dst_sel:DWORD dst_unused:UNUSED_PAD src0_sel:WORD_1 src1_sel:DWORD
	v_and_b32_sdwa v32, v30, v177 dst_sel:DWORD dst_unused:UNUSED_PAD src0_sel:WORD_1 src1_sel:DWORD
	v_add3_u32 v27, v31, v27, s48
	v_add3_u32 v30, v30, v32, s48
	v_and_b32_e32 v27, 0xffff0000, v27
	v_and_b32_e32 v30, 0xffff0000, v30
	v_or_b32_sdwa v27, v27, v18 dst_sel:DWORD dst_unused:UNUSED_PAD src0_sel:DWORD src1_sel:WORD_1
	v_or_b32_sdwa v26, v30, v26 dst_sel:DWORD dst_unused:UNUSED_PAD src0_sel:DWORD src1_sel:WORD_1
	global_store_dwordx2 v[28:29], v[26:27], off offset:96
	s_and_saveexec_b64 s[6:7], s[4:5]
	s_cbranch_execz .LBB0_311
	global_store_dwordx2 v[20:21], v[24:25], off

; #define tidx() tidx_(wv_)
; __device__ __forceinline__ void load_q(const u16* z, int ld, int col, int tok, bool rope, const float* tb, bf16x8& bq0, bf16x8& bq1, int wv_) {
;   const int g = (tidx() & 63) >> 4;
;   const u16* src = z + (size_t)tok * ld + col + g * 8;
;   uint4 c0 = *(const uint4*)src;
;   uint4 c1 = *(const uint4*)(src + 32);
;   float x1[8], x2[8];
;   unpack8(c0, x1);
;   unpack8(c1, x2);
;   if (rope) {
;     const float* t = tb + ((size_t)(tok & (SEQ_ - 1)) * 32 + g * 8) * 2;
; #pragma unroll
;     for (int i = 0; i < 8; ++i) {
;       float cs = t[2 * i], sn = t[2 * i + 1];
;       float a = x1[i] * cs - x2[i] * sn, b = x2[i] * cs + x1[i] * sn;
;       x1[i] = a; x2[i] = b;
;     }
;   }
; #pragma unroll
;   for (int i = 0; i < 8; ++i) { x1[i] *= 0.125f; x2[i] *= 0.125f; }
;   union { uint4 q; bf16x8 v; } cv;
;   cv.q = pack8(x1); bq0 = cv.v;
;   cv.q = pack8(x2); bq1 = cv.v;
; }
; __device__ __forceinline__ void attnC_item(unsigned char* ws, int item, unsigned char* lds, int wv_) {
;     ...
;   const int tq = b * SEQ_ + i0 + fr;
;   bf16x8 bq0, bq1;
;   load_q(z, CDC_, hq * 64, tq, true, tb, bq0, bq1, wv_);
;   float sinkv = inp(ws, 30)[hq];
;   __syncthreads();
.LBB0_465:
	s_or_b64 exec, exec, s[2:3]
	v_mbcnt_lo_u32_b32 v1, -1, 0
	v_mbcnt_hi_u32_b32 v1, -1, v1
	v_mbcnt_lo_u32_b32 v12, -1, 0
	v_mbcnt_hi_u32_b32 v12, -1, v12
	v_mov_b64_e32 v[14:15], s[58:59]
	v_and_b32_e32 v2, 15, v12
	v_or3_b32 v8, v0, v2, s12
	v_mbcnt_lo_u32_b32 v0, -1, 0
	v_mbcnt_hi_u32_b32 v0, -1, v0
	v_or_b32_e32 v1, s63, v1
	v_lshrrev_b32_e32 v0, 1, v0
	v_ashrrev_i32_e32 v1, 6, v1
	v_and_b32_e32 v9, 24, v0
	v_lshlrev_b32_e32 v0, 5, v8
	v_lshl_add_u32 v30, s13, 3, v1
	v_and_or_b32 v0, v0, s64, v9
	v_lshlrev_b32_e32 v11, 3, v0
	v_lshlrev_b32_e32 v10, 6, v30
	global_load_dwordx4 v[0:3], v11, s[52:53] offset:16
	global_load_dwordx4 v[4:7], v11, s[52:53]
	v_mad_i64_i32 v[22:23], s[2:3], v8, s92, v[14:15]
	global_load_dwordx4 v[14:17], v11, s[52:53] offset:48
	global_load_dwordx4 v[18:21], v11, s[52:53] offset:32
	v_ashrrev_i32_e32 v11, 31, v10
	v_lshlrev_b64 v[10:11], 1, v[10:11]
	v_lshl_add_u64 v[22:23], v[22:23], 0, v[10:11]
	v_lshlrev_b32_e32 v166, 1, v9
	v_lshl_add_u64 v[26:27], v[22:23], 0, v[166:167]
	global_load_dwordx4 v[22:25], v[26:27], off
	s_nop 0
	global_load_dwordx4 v[26:29], v[26:27], off offset:64
	s_load_dwordx2 s[2:3], s[0:1], 0xf0
	v_ashrrev_i32_e32 v31, 31, v30
	s_add_i32 s11, s11, s39
	s_waitcnt vmcnt(5)
	v_mov_b32_e32 v33, v0
	s_waitcnt vmcnt(4)
	v_mov_b32_e32 v32, v4
	v_mov_b32_e32 v0, v5
	v_mov_b32_e32 v4, v6
	v_mov_b32_e32 v5, v2
	v_mov_b32_e32 v2, v7
	s_waitcnt vmcnt(2)
	v_mov_b32_e32 v6, v18
	v_mov_b32_e32 v7, v14
	v_mov_b32_e32 v14, v19
	v_mov_b32_e32 v18, v20
	v_mov_b32_e32 v19, v16
	v_mov_b32_e32 v16, v21
	s_waitcnt vmcnt(1)
	v_lshlrev_b32_e32 v21, 16, v23
	v_lshlrev_b32_e32 v20, 16, v22
	v_and_b32_e32 v23, 0xffff0000, v23
	v_and_b32_e32 v22, 0xffff0000, v22
	s_waitcnt vmcnt(0)
	v_lshlrev_b32_e32 v35, 16, v27
	v_lshlrev_b32_e32 v34, 16, v26
	v_and_b32_e32 v27, 0xffff0000, v27
	v_and_b32_e32 v26, 0xffff0000, v26
	v_lshlrev_b32_e32 v37, 16, v25
	v_lshlrev_b32_e32 v36, 16, v24
	v_lshlrev_b32_e32 v39, 16, v29
	v_lshlrev_b32_e32 v38, 16, v28
	v_and_b32_e32 v25, 0xffff0000, v25
	v_and_b32_e32 v24, 0xffff0000, v24
	v_and_b32_e32 v29, 0xffff0000, v29
	v_and_b32_e32 v28, 0xffff0000, v28
	v_pk_mul_f32 v[42:43], v[2:3], v[22:23]
	v_pk_mul_f32 v[2:3], v[2:3], v[26:27]
	v_pk_mul_f32 v[44:45], v[14:15], v[36:37]
	v_pk_mul_f32 v[14:15], v[14:15], v[38:39]
	v_pk_mul_f32 v[46:47], v[16:17], v[24:25]
	v_pk_mul_f32 v[16:17], v[16:17], v[28:29]
	v_pk_fma_f32 v[26:27], v[4:5], v[26:27], v[42:43]
	v_pk_fma_f32 v[2:3], v[4:5], v[22:23], v[2:3] neg_lo:[0,0,1] neg_hi:[0,0,1]
	v_pk_fma_f32 v[4:5], v[6:7], v[38:39], v[44:45]
	v_pk_fma_f32 v[6:7], v[6:7], v[36:37], v[14:15] neg_lo:[0,0,1] neg_hi:[0,0,1]
	v_pk_mul_f32 v[40:41], v[0:1], v[20:21]
	v_pk_mul_f32 v[0:1], v[0:1], v[34:35]
	v_pk_fma_f32 v[14:15], v[18:19], v[24:25], v[16:17] neg_lo:[0,0,1] neg_hi:[0,0,1]
	v_pk_mul_f32 v[6:7], v[6:7], s[86:87] op_sel_hi:[1,0]
	v_pk_fma_f32 v[0:1], v[32:33], v[20:21], v[0:1] neg_lo:[0,0,1] neg_hi:[0,0,1]
	v_pk_fma_f32 v[20:21], v[18:19], v[28:29], v[46:47]
	v_pk_mul_f32 v[18:19], v[26:27], s[86:87] op_sel_hi:[1,0]
	v_pk_mul_f32 v[2:3], v[2:3], s[86:87] op_sel_hi:[1,0]
	v_pk_mul_f32 v[14:15], v[14:15], s[86:87] op_sel_hi:[1,0]
	v_bfe_u32 v27, v7, 16, 1
	v_pk_fma_f32 v[34:35], v[32:33], v[34:35], v[40:41]
	v_bfe_u32 v9, v15, 16, 1
	v_bfe_u32 v13, v14, 16, 1
	v_bfe_u32 v22, v3, 16, 1
	v_bfe_u32 v23, v2, 16, 1
	v_bfe_u32 v26, v6, 16, 1
	v_add3_u32 v7, v7, v27, s48
	v_pk_mul_f32 v[16:17], v[34:35], s[86:87] op_sel_hi:[1,0]
	v_pk_mul_f32 v[4:5], v[4:5], s[86:87] op_sel_hi:[1,0]
	v_pk_mul_f32 v[20:21], v[20:21], s[86:87] op_sel_hi:[1,0]
	v_add3_u32 v23, v2, v23, s48
	v_add3_u32 v22, v3, v22, s48
	v_add3_u32 v2, v14, v13, s48
	v_add3_u32 v3, v15, v9, s48
	v_add3_u32 v6, v6, v26, s48
	v_lshrrev_b32_e32 v7, 16, v7
	v_bfe_u32 v9, v19, 16, 1
	v_bfe_u32 v13, v18, 16, 1
	v_lshrrev_b32_e32 v6, 16, v6
	v_and_or_b32 v3, v3, s97, v7
	v_bfe_u32 v7, v20, 16, 1
	v_add3_u32 v13, v18, v13, s48
	v_add3_u32 v9, v19, v9, s48
	v_bfe_u32 v15, v17, 16, 1
	v_bfe_u32 v18, v4, 16, 1
	v_bfe_u32 v19, v5, 16, 1
	v_and_or_b32 v2, v2, s97, v6
	v_bfe_u32 v6, v21, 16, 1
	v_add3_u32 v14, v20, v7, s48
	v_bfe_u32 v7, v16, 16, 1
	v_add3_u32 v5, v5, v19, s48
	v_add3_u32 v4, v4, v18, s48
	v_add3_u32 v15, v17, v15, s48
	v_add3_u32 v6, v21, v6, s48
	v_add3_u32 v7, v16, v7, s48
	v_lshrrev_b32_e32 v15, 16, v15
	v_lshrrev_b32_e32 v4, 16, v4
	v_lshrrev_b32_e32 v5, 16, v5
	v_lshrrev_b32_e32 v16, 16, v7
	v_and_or_b32 v7, v6, s97, v5
	v_and_or_b32 v6, v14, s97, v4
	v_and_or_b32 v5, v9, s97, v15
	s_waitcnt lgkmcnt(0)
	v_lshl_add_u64 v[14:15], v[30:31], 2, s[2:3]
	v_pk_mul_f32 v[0:1], v[0:1], s[86:87] op_sel_hi:[1,0]
	v_and_or_b32 v4, v13, s97, v16
	global_load_dword v9, v[14:15], off
	s_barrier
; template <int NKT, typename KofsF, typename BiasF> ...
;     ...
;   for (int kt = 0; kt < NKT; ++kt) {
;     int key = kofs(kt) + fr;
;     const char* kp = (const char*)Ks + key * 128;
;     bf16x8 a0 = *(const bf16x8*)(kp + ((g ^ (key & 7)) << 4));
;     bf16x8 a1 = *(const bf16x8*)(kp + (((4 + g) ^ (key & 7)) << 4));
;     f32x4 acc = {0.f, 0.f, 0.f, 0.f};
;     acc = __builtin_amdgcn_mfma_f32_16x16x32_bf16(a0, bq0, acc, 0, 0, 0);
;     acc = __builtin_amdgcn_mfma_f32_16x16x32_bf16(a1, bq1, acc, 0, 0, 0);
; #pragma unroll
;     for (int j = 0; j < 4; ++j) s[kt][j] = acc[j] + bias(kt, g * 4 + j, fr);
; __device__ __forceinline__ void attnC_item(unsigned char* ws, int item, unsigned char* lds, int wv_) {
;     ...
;   auto bias = [&](int kt, int kj, int frq) -> float {
;     int ik = i0 - 128 + 16 * kt + kj;
;     int dd = (i0 + frq) - ik;
;     bool ok = (ik >= 0) && (ik < SEQ_) && (dd <= 128) && (dd >= -128);
;     return ok ? 0.f : -INFINITY;
;   };
	v_mbcnt_lo_u32_b32 v16, -1, 0
	v_mbcnt_hi_u32_b32 v16, -1, v16
	v_bfe_u32 v24, v0, 16, 1
	v_bfe_u32 v13, v16, 4, 2
	v_bfe_u32 v25, v1, 16, 1
	v_and_b32_e32 v14, 15, v16
	v_bitop3_b32 v17, v13, v16, 7 bitop3:0x78
	v_add3_u32 v1, v1, v25, s48
	v_add3_u32 v0, v0, v24, s48
	v_lshlrev_b32_e32 v19, 4, v17
	v_lshl_add_u32 v33, v14, 7, 0
	v_lshrrev_b32_e32 v0, 16, v0
	v_lshrrev_b32_e32 v1, 16, v1
	v_add_u32_e32 v17, v33, v19
	v_and_or_b32 v1, v22, s97, v1
	v_and_or_b32 v0, v23, s97, v0
	v_and_b32_e32 v15, 7, v16
	ds_read_b128 v[20:23], v17
	ds_read_b128 v[48:51], v17 offset:8192
	v_bitop3_b32 v15, v13, v15, 4 bitop3:0x36
	v_lshlrev_b32_e32 v47, 4, v15
	v_add_u32_e32 v15, v33, v47
	ds_read_b128 v[24:27], v15
	ds_read_b128 v[52:55], v15 offset:8192
	s_waitcnt lgkmcnt(3)
	v_mfma_f32_16x16x32_bf16 v[20:23], v[20:23], v[0:3], 0
	v_lshl_or_b32 v28, v13, 2, v149
	v_or_b32_e32 v65, 0x80, v14
	v_add_u32_e32 v18, s12, v28
	s_waitcnt lgkmcnt(1)
	v_mfma_f32_16x16x32_bf16 v[20:23], v[24:27], v[4:7], v[20:23]
	v_sub_u32_e32 v24, v65, v28
	v_cmp_gt_u32_e32 vcc, s72, v18
	v_cmp_gt_u32_e64 s[4:5], s96, v24
	s_and_b64 s[2:3], vcc, s[4:5]
	v_cndmask_b32_e64 v24, v179, 0, s[2:3]
	s_nop 2
	v_add_f32_e32 v46, v20, v24
	v_sub_u32_e32 v20, v28, v65
	s_movk_i32 s2, 0xfefe
	v_cmp_lt_u32_e64 s[4:5], s2, v20
	s_and_b64 s[2:3], vcc, s[4:5]
	v_cndmask_b32_e64 v20, v179, 0, s[2:3]
	v_add_f32_e32 v45, v21, v20
	v_add_u32_e32 v21, 0x800, v33
	v_add_u32_e32 v24, v21, v19
	v_add_u32_e32 v69, s12, v65
	ds_read_b128 v[24:27], v24
	v_sub_u32_e32 v66, v69, v18
	v_add_u32_e32 v20, -2, v66
	v_cmp_gt_u32_e64 s[4:5], s96, v20
	v_add_u32_e32 v20, v21, v47
	ds_read_b128 v[28:31], v20
	s_and_b64 s[2:3], vcc, s[4:5]
	v_cndmask_b32_e64 v20, v179, 0, s[2:3]
	v_add_f32_e32 v44, v22, v20
	v_add_u32_e32 v20, -3, v66
	s_waitcnt lgkmcnt(1)
	v_mfma_f32_16x16x32_bf16 v[24:27], v[24:27], v[0:3], 0
	v_cmp_gt_u32_e64 s[4:5], s96, v20
	s_and_b64 s[2:3], vcc, s[4:5]
	v_cndmask_b32_e64 v20, v179, 0, s[2:3]
	v_add_f32_e32 v43, v23, v20
	s_waitcnt lgkmcnt(0)
	v_mfma_f32_16x16x32_bf16 v[20:23], v[28:31], v[4:7], v[24:27]
	ds_read_b128 v[60:63], v17 offset:12288
	ds_read_b128 v[70:73], v17 offset:18432
	ds_read_b128 v[74:77], v15 offset:18432
	v_add_u32_e32 v24, 16, v18
	v_cmp_gt_u32_e32 vcc, s72, v24
	v_sub_u32_e32 v24, v69, v24
	v_cmp_gt_u32_e64 s[4:5], s96, v24
	s_and_b64 s[2:3], vcc, s[4:5]
	v_cndmask_b32_e64 v24, v179, 0, s[2:3]
	v_add_f32_e32 v41, v20, v24
	v_add_u32_e32 v20, 17, v18
	v_cmp_gt_u32_e32 vcc, s72, v20
	v_sub_u32_e32 v20, v69, v20
	v_cmp_gt_u32_e64 s[4:5], s96, v20
	s_and_b64 s[2:3], vcc, s[4:5]
	v_cndmask_b32_e64 v20, v179, 0, s[2:3]
	v_add_f32_e32 v39, v21, v20
	v_add_u32_e32 v20, 18, v18
	v_cmp_gt_u32_e32 vcc, s72, v20
	v_sub_u32_e32 v20, v69, v20
	v_cmp_gt_u32_e64 s[4:5], s96, v20
	v_add_u32_e32 v20, 0x1000, v33
	v_add_u32_e32 v21, v20, v19
	ds_read_b128 v[24:27], v21
	v_add_u32_e32 v20, v20, v47
	ds_read_b128 v[28:31], v20
	v_add_u32_e32 v20, 19, v18
	s_and_b64 s[2:3], vcc, s[4:5]
	v_cmp_gt_u32_e32 vcc, s72, v20
	v_sub_u32_e32 v20, v69, v20
	s_waitcnt lgkmcnt(1)
	v_mfma_f32_16x16x32_bf16 v[24:27], v[24:27], v[0:3], 0
	v_cmp_gt_u32_e64 s[4:5], s96, v20
	v_cndmask_b32_e64 v21, v179, 0, s[2:3]
	s_and_b64 s[2:3], vcc, s[4:5]
	v_cndmask_b32_e64 v20, v179, 0, s[2:3]
	v_add_f32_e32 v36, v22, v21
	v_add_f32_e32 v37, v23, v20
	s_waitcnt lgkmcnt(0)
	v_mfma_f32_16x16x32_bf16 v[20:23], v[28:31], v[4:7], v[24:27]
	v_add_u32_e32 v31, 0x62, v18
	ds_read_b128 v[82:85], v17 offset:22528
	v_and_b32_e32 v16, 63, v16
	v_add_u32_e32 v24, 32, v18
	v_cmp_gt_u32_e32 vcc, s72, v24
	v_sub_u32_e32 v24, v69, v24
	v_cmp_gt_u32_e64 s[4:5], s96, v24
	s_and_b64 s[2:3], vcc, s[4:5]
	v_cndmask_b32_e64 v24, v179, 0, s[2:3]
	v_add_f32_e32 v35, v24, v20
	v_add_u32_e32 v20, 33, v18
	v_cmp_gt_u32_e32 vcc, s72, v20
	v_sub_u32_e32 v20, v69, v20
	v_cmp_gt_u32_e64 s[4:5], s96, v20
	s_and_b64 s[2:3], vcc, s[4:5]
	v_cndmask_b32_e64 v20, v179, 0, s[2:3]
	v_add_f32_e32 v32, v20, v21
	v_add_u32_e32 v20, 34, v18
	v_cmp_gt_u32_e32 vcc, s72, v20
	v_sub_u32_e32 v20, v69, v20
	v_cmp_gt_u32_e64 s[4:5], s96, v20
	v_add_u32_e32 v20, 0x1800, v33
	v_add_u32_e32 v21, v20, v19
	ds_read_b128 v[24:27], v21
	v_add_u32_e32 v20, v20, v47
	ds_read_b128 v[56:59], v20
	v_add_u32_e32 v20, 35, v18
	s_and_b64 s[2:3], vcc, s[4:5]
	v_cmp_gt_u32_e32 vcc, s72, v20
	v_sub_u32_e32 v20, v69, v20
	s_waitcnt lgkmcnt(1)
	v_mfma_f32_16x16x32_bf16 v[24:27], v[24:27], v[0:3], 0
	v_cmp_gt_u32_e64 s[4:5], s96, v20
	v_cndmask_b32_e64 v21, v179, 0, s[2:3]
	s_and_b64 s[2:3], vcc, s[4:5]
	v_cndmask_b32_e64 v20, v179, 0, s[2:3]
	v_add_f32_e32 v29, v21, v22
	v_add_f32_e32 v30, v20, v23
	s_waitcnt lgkmcnt(0)
; template <int NKT, typename KofsF, typename BiasF> ...
;     ...
;   for (int kt = 0; kt < NKT; ++kt) {
;     int key = kofs(kt) + fr;
;     const char* kp = (const char*)Ks + key * 128;
;     bf16x8 a0 = *(const bf16x8*)(kp + ((g ^ (key & 7)) << 4));
;     bf16x8 a1 = *(const bf16x8*)(kp + (((4 + g) ^ (key & 7)) << 4));
;     f32x4 acc = {0.f, 0.f, 0.f, 0.f};
;     acc = __builtin_amdgcn_mfma_f32_16x16x32_bf16(a0, bq0, acc, 0, 0, 0);
;     acc = __builtin_amdgcn_mfma_f32_16x16x32_bf16(a1, bq1, acc, 0, 0, 0);
; #pragma unroll
;     for (int j = 0; j < 4; ++j) s[kt][j] = acc[j] + bias(kt, g * 4 + j, fr);
; __device__ __forceinline__ void attnC_item(unsigned char* ws, int item, unsigned char* lds, int wv_) {
;     ...
;   auto bias = [&](int kt, int kj, int frq) -> float {
;     int ik = i0 - 128 + 16 * kt + kj;
;     int dd = (i0 + frq) - ik;
;     bool ok = (ik >= 0) && (ik < SEQ_) && (dd <= 128) && (dd >= -128);
;     return ok ? 0.f : -INFINITY;
;   };
	v_mfma_f32_16x16x32_bf16 v[20:23], v[56:59], v[4:7], v[24:27]
	ds_read_b128 v[56:59], v15 offset:10240
	v_mul_u32_u24_e32 v14, 0x250, v14
	ds_read_b128 v[90:93], v15 offset:26624
	v_add_u32_e32 v24, 48, v18
	v_cmp_gt_u32_e32 vcc, s72, v24
	v_sub_u32_e32 v24, v69, v24
	v_cmp_gt_u32_e64 s[4:5], s96, v24
	s_and_b64 s[2:3], vcc, s[4:5]
	v_cndmask_b32_e64 v24, v179, 0, s[2:3]
	v_add_f32_e32 v27, v24, v20
	v_add_u32_e32 v20, 49, v18
	v_cmp_gt_u32_e32 vcc, s72, v20
	v_sub_u32_e32 v20, v69, v20
	v_cmp_gt_u32_e64 s[4:5], s96, v20
	s_and_b64 s[2:3], vcc, s[4:5]
	v_cndmask_b32_e64 v20, v179, 0, s[2:3]
	v_add_f32_e32 v25, v20, v21
	v_add_u32_e32 v20, 50, v18
	v_cmp_gt_u32_e32 vcc, s72, v20
	v_sub_u32_e32 v20, v69, v20
	v_cmp_gt_u32_e64 s[4:5], s96, v20
	s_and_b64 s[2:3], vcc, s[4:5]
	v_cndmask_b32_e64 v20, v179, 0, s[2:3]
	v_add_f32_e32 v24, v20, v22
	v_add_u32_e32 v20, 51, v18
	v_cmp_gt_u32_e32 vcc, s72, v20
	v_sub_u32_e32 v20, v69, v20
	v_cmp_gt_u32_e64 s[4:5], s96, v20
	v_mfma_f32_16x16x32_bf16 v[48:51], v[48:51], v[0:3], 0
	s_and_b64 s[2:3], vcc, s[4:5]
	v_cndmask_b32_e64 v20, v179, 0, s[2:3]
	v_add_f32_e32 v23, v20, v23
	v_add_u32_e32 v20, 64, v18
	v_mfma_f32_16x16x32_bf16 v[48:51], v[52:55], v[4:7], v[48:51]
	v_cmp_gt_u32_e32 vcc, s72, v20
	v_sub_u32_e32 v20, v69, v20
	v_cmp_gt_u32_e64 s[4:5], s96, v20
	ds_read_b128 v[52:55], v17 offset:10240
	s_and_b64 s[2:3], vcc, s[4:5]
	v_cndmask_b32_e64 v20, v179, 0, s[2:3]
	s_nop 1
	v_add_f32_e32 v21, v20, v48
	v_add_u32_e32 v20, 0x41, v18
	v_cmp_gt_u32_e32 vcc, s72, v20
	v_sub_u32_e32 v20, v69, v20
	v_cmp_gt_u32_e64 s[4:5], s96, v20
	v_add_u32_e32 v22, 0x42, v18
	s_and_b64 s[2:3], vcc, s[4:5]
	v_cmp_gt_u32_e32 vcc, s72, v22
	v_sub_u32_e32 v22, v69, v22
	v_cmp_gt_u32_e64 s[4:5], s96, v22
	v_add_u32_e32 v26, 0x43, v18
	v_cndmask_b32_e64 v20, v179, 0, s[2:3]
	s_and_b64 s[2:3], vcc, s[4:5]
	v_cmp_gt_u32_e32 vcc, s72, v26
	v_sub_u32_e32 v26, v69, v26
	v_cmp_gt_u32_e64 s[4:5], s96, v26
	s_waitcnt lgkmcnt(0)
	v_mfma_f32_16x16x32_bf16 v[52:55], v[52:55], v[0:3], 0
	v_cndmask_b32_e64 v22, v179, 0, s[2:3]
	s_and_b64 s[2:3], vcc, s[4:5]
	v_cndmask_b32_e64 v26, v179, 0, s[2:3]
	v_add_f32_e32 v42, v26, v51
	v_add_u32_e32 v26, 0x50, v18
	v_add_f32_e32 v20, v20, v49
	v_add_f32_e32 v22, v22, v50
	ds_read_b128 v[48:51], v15 offset:12288
	v_mfma_f32_16x16x32_bf16 v[52:55], v[56:59], v[4:7], v[52:55]
	v_cmp_gt_u32_e32 vcc, s72, v26
	v_sub_u32_e32 v26, v69, v26
	v_cmp_gt_u32_e64 s[4:5], s96, v26
	s_and_b64 s[2:3], vcc, s[4:5]
	v_cndmask_b32_e64 v26, v179, 0, s[2:3]
	s_nop 2
	v_add_f32_e32 v40, v26, v52
	v_add_u32_e32 v26, 0x51, v18
	v_cmp_gt_u32_e32 vcc, s72, v26
	v_sub_u32_e32 v26, v69, v26
	v_cmp_gt_u32_e64 s[4:5], s96, v26
	s_and_b64 s[2:3], vcc, s[4:5]
	v_cndmask_b32_e64 v26, v179, 0, s[2:3]
	v_add_f32_e32 v38, v26, v53
	v_add_u32_e32 v26, 0x52, v18
	v_cmp_gt_u32_e32 vcc, s72, v26
	v_sub_u32_e32 v26, v69, v26
	v_cmp_gt_u32_e64 s[4:5], s96, v26
	s_and_b64 s[2:3], vcc, s[4:5]
	v_cndmask_b32_e64 v26, v179, 0, s[2:3]
	v_add_f32_e32 v34, v26, v54
	v_add_u32_e32 v26, 0x53, v18
	v_cmp_gt_u32_e32 vcc, s72, v26
	v_sub_u32_e32 v26, v69, v26
	v_cmp_gt_u32_e64 s[4:5], s96, v26
	v_mfma_f32_16x16x32_bf16 v[56:59], v[60:63], v[0:3], 0
	s_and_b64 s[2:3], vcc, s[4:5]
	v_cndmask_b32_e64 v26, v179, 0, s[2:3]
	v_add_f32_e32 v33, v26, v55
	v_add_u32_e32 v26, 0x60, v18
	s_waitcnt lgkmcnt(0)
	v_mfma_f32_16x16x32_bf16 v[48:51], v[48:51], v[4:7], v[56:59]
	v_cmp_gt_u32_e32 vcc, s72, v26
	v_sub_u32_e32 v26, v69, v26
	ds_read_b128 v[52:55], v17 offset:14336
	v_cmp_gt_u32_e64 s[4:5], s96, v26
	s_and_b64 s[2:3], vcc, s[4:5]
	v_cndmask_b32_e64 v26, v179, 0, s[2:3]
	s_nop 1
	v_add_f32_e32 v28, v26, v48
	v_add_u32_e32 v26, 0x61, v18
	ds_read_b128 v[56:59], v15 offset:14336
	v_cmp_gt_u32_e32 vcc, s72, v26
	v_sub_u32_e32 v26, v69, v26
	v_cmp_gt_u32_e64 s[4:5], s96, v26
	s_and_b64 s[2:3], vcc, s[4:5]
	v_cmp_gt_u32_e32 vcc, s72, v31
	v_sub_u32_e32 v31, v69, v31
	v_cmp_gt_u32_e64 s[4:5], s96, v31
	v_add_u32_e32 v48, 0x63, v18
	v_cndmask_b32_e64 v26, v179, 0, s[2:3]
	s_and_b64 s[2:3], vcc, s[4:5]
	v_cmp_gt_u32_e32 vcc, s72, v48
	v_sub_u32_e32 v48, v69, v48
	s_waitcnt lgkmcnt(1)
	v_mfma_f32_16x16x32_bf16 v[52:55], v[52:55], v[0:3], 0
	v_cmp_gt_u32_e64 s[4:5], s96, v48
	v_cndmask_b32_e64 v31, v179, 0, s[2:3]
	s_and_b64 s[2:3], vcc, s[4:5]
	v_cndmask_b32_e64 v48, v179, 0, s[2:3]
	v_add_f32_e32 v26, v26, v49
	v_add_f32_e32 v31, v31, v50
	v_add_f32_e32 v64, v48, v51
	s_waitcnt lgkmcnt(0)
	v_mfma_f32_16x16x32_bf16 v[48:51], v[56:59], v[4:7], v[52:55]
	ds_read_b128 v[98:101], v15 offset:30720
	s_nop 1
	v_add_u32_e32 v52, 0x70, v18
	v_cmp_gt_u32_e32 vcc, s72, v52
	v_sub_u32_e32 v52, v69, v52
	v_cmp_gt_u32_e64 s[4:5], s96, v52
	s_and_b64 s[2:3], vcc, s[4:5]
	v_cndmask_b32_e64 v52, v179, 0, s[2:3]
	v_add_f32_e32 v62, v52, v48
	v_add_u32_e32 v48, 0x71, v18
	v_cmp_gt_u32_e32 vcc, s72, v48
	v_sub_u32_e32 v48, v69, v48
	v_cmp_gt_u32_e64 s[4:5], s96, v48
	s_and_b64 s[2:3], vcc, s[4:5]
	v_cndmask_b32_e64 v48, v179, 0, s[2:3]
	v_add_f32_e32 v61, v48, v49
	v_add_u32_e32 v48, 0x72, v18
	v_cmp_gt_u32_e32 vcc, s72, v48
	v_sub_u32_e32 v48, v69, v48
	v_cmp_gt_u32_e64 s[4:5], s96, v48
	v_lshl_add_u32 v48, v65, 7, 0
	v_add_u32_e32 v19, v48, v19
	ds_read_b128 v[52:55], v19
	s_and_b64 s[2:3], vcc, s[4:5]
	v_cndmask_b32_e64 v19, v179, 0, s[2:3]
	v_add_f32_e32 v58, v19, v50
	v_add_u32_e32 v19, v48, v47
	ds_read_b128 v[78:81], v19
	v_add_u32_e32 v19, 0x73, v18
	s_waitcnt lgkmcnt(1)
	v_mfma_f32_16x16x32_bf16 v[52:55], v[52:55], v[0:3], 0
	v_cmp_gt_u32_e32 vcc, s72, v19
	v_sub_u32_e32 v19, v69, v19
	v_cmp_gt_u32_e64 s[4:5], s96, v19
	s_and_b64 s[2:3], vcc, s[4:5]
	v_cndmask_b32_e64 v19, v179, 0, s[2:3]
	s_waitcnt lgkmcnt(0)
; template <int NKT, typename KofsF, typename BiasF> ...
;     ...
;   for (int kt = 0; kt < NKT; ++kt) {
;     int key = kofs(kt) + fr;
;     const char* kp = (const char*)Ks + key * 128;
;     bf16x8 a0 = *(const bf16x8*)(kp + ((g ^ (key & 7)) << 4));
;     bf16x8 a1 = *(const bf16x8*)(kp + (((4 + g) ^ (key & 7)) << 4));
;     f32x4 acc = {0.f, 0.f, 0.f, 0.f};
;     acc = __builtin_amdgcn_mfma_f32_16x16x32_bf16(a0, bq0, acc, 0, 0, 0);
;     acc = __builtin_amdgcn_mfma_f32_16x16x32_bf16(a1, bq1, acc, 0, 0, 0);
; #pragma unroll
;     for (int j = 0; j < 4; ++j) s[kt][j] = acc[j] + bias(kt, g * 4 + j, fr);
; __device__ __forceinline__ void attnC_item(unsigned char* ws, int item, unsigned char* lds, int wv_) {
;     ...
;   auto bias = [&](int kt, int kj, int frq) -> float {
;     int ik = i0 - 128 + 16 * kt + kj;
;     int dd = (i0 + frq) - ik;
;     bool ok = (ik >= 0) && (ik < SEQ_) && (dd <= 128) && (dd >= -128);
;     return ok ? 0.f : -INFINITY;
;   };
	v_mfma_f32_16x16x32_bf16 v[54:57], v[78:81], v[4:7], v[52:55]
	v_add_f32_e32 v59, v19, v51
	v_add_u32_e32 v19, 0xffffff80, v66
	v_cmp_gt_u32_e32 vcc, s96, v19
	v_mfma_f32_16x16x32_bf16 v[70:73], v[70:73], v[0:3], 0
	ds_read_b128 v[78:81], v15 offset:20480
	v_cndmask_b32_e64 v19, v179, 0, vcc
	s_nop 1
	v_add_f32_e32 v54, v19, v54
	v_add_u32_e32 v19, 0x81, v18
	v_cmp_gt_u32_e32 vcc, s72, v19
	v_sub_u32_e32 v19, v69, v19
	v_cmp_gt_u32_e64 s[4:5], s96, v19
	s_and_b64 s[2:3], vcc, s[4:5]
	v_cndmask_b32_e64 v19, v179, 0, s[2:3]
	v_add_f32_e32 v52, v19, v55
	v_add_u32_e32 v19, 0x82, v18
	v_cmp_gt_u32_e32 vcc, s72, v19
	v_sub_u32_e32 v19, v69, v19
	v_cmp_gt_u32_e64 s[4:5], s96, v19
	s_and_b64 s[2:3], vcc, s[4:5]
	v_cndmask_b32_e64 v19, v179, 0, s[2:3]
	v_add_f32_e32 v51, v19, v56
	v_add_u32_e32 v19, 0x83, v18
	v_cmp_gt_u32_e32 vcc, s72, v19
	v_sub_u32_e32 v19, v69, v19
	v_cmp_gt_u32_e64 s[4:5], s96, v19
	s_and_b64 s[2:3], vcc, s[4:5]
	v_cndmask_b32_e64 v19, v179, 0, s[2:3]
	v_add_f32_e32 v50, v19, v57
	v_add_u32_e32 v19, 0x90, v18
	v_mfma_f32_16x16x32_bf16 v[70:73], v[74:77], v[4:7], v[70:73]
	v_cmp_gt_u32_e32 vcc, s72, v19
	v_sub_u32_e32 v19, v69, v19
	v_cmp_gt_u32_e64 s[4:5], s96, v19
	s_and_b64 s[2:3], vcc, s[4:5]
	v_cndmask_b32_e64 v19, v179, 0, s[2:3]
	s_nop 2
	v_add_f32_e32 v48, v19, v70
	v_add_u32_e32 v19, 0x91, v18
	v_cmp_gt_u32_e32 vcc, s72, v19
	v_sub_u32_e32 v19, v69, v19
	v_cmp_gt_u32_e64 s[4:5], s96, v19
	s_and_b64 s[2:3], vcc, s[4:5]
	ds_read_b128 v[74:77], v17 offset:20480
	v_cndmask_b32_e64 v19, v179, 0, s[2:3]
	v_add_f32_e32 v47, v19, v71
	v_add_u32_e32 v19, 0x92, v18
	v_cmp_gt_u32_e32 vcc, s72, v19
	v_sub_u32_e32 v19, v69, v19
	v_cmp_gt_u32_e64 s[4:5], s96, v19
	s_and_b64 s[2:3], vcc, s[4:5]
	v_cndmask_b32_e64 v19, v179, 0, s[2:3]
	v_add_f32_e32 v49, v19, v72
	v_add_u32_e32 v19, 0x93, v18
	v_cmp_gt_u32_e32 vcc, s72, v19
	v_sub_u32_e32 v19, v69, v19
	v_cmp_gt_u32_e64 s[4:5], s96, v19
	s_waitcnt lgkmcnt(0)
	v_mfma_f32_16x16x32_bf16 v[74:77], v[74:77], v[0:3], 0
	s_and_b64 s[2:3], vcc, s[4:5]
	v_cndmask_b32_e64 v19, v179, 0, s[2:3]
	v_add_f32_e32 v68, v19, v73
	v_add_u32_e32 v19, 0xa0, v18
	ds_read_b128 v[70:73], v15 offset:22528
	v_mfma_f32_16x16x32_bf16 v[74:77], v[78:81], v[4:7], v[74:77]
	v_cmp_gt_u32_e32 vcc, s72, v19
	v_sub_u32_e32 v19, v69, v19
	v_cmp_gt_u32_e64 s[4:5], s96, v19
	s_and_b64 s[2:3], vcc, s[4:5]
	v_cndmask_b32_e64 v19, v179, 0, s[2:3]
	s_nop 2
	v_add_f32_e32 v66, v19, v74
	v_add_u32_e32 v19, 0xa1, v18
	v_cmp_gt_u32_e32 vcc, s72, v19
	v_sub_u32_e32 v19, v69, v19
	v_cmp_gt_u32_e64 s[4:5], s96, v19
	s_and_b64 s[2:3], vcc, s[4:5]
	v_cndmask_b32_e64 v19, v179, 0, s[2:3]
	v_add_f32_e32 v63, v19, v75
	v_add_u32_e32 v19, 0xa2, v18
	v_cmp_gt_u32_e32 vcc, s72, v19
	v_sub_u32_e32 v19, v69, v19
	v_cmp_gt_u32_e64 s[4:5], s96, v19
	s_and_b64 s[2:3], vcc, s[4:5]
	v_cndmask_b32_e64 v19, v179, 0, s[2:3]
	v_add_f32_e32 v60, v19, v76
	v_add_u32_e32 v19, 0xa3, v18
	v_cmp_gt_u32_e32 vcc, s72, v19
	v_sub_u32_e32 v19, v69, v19
	v_cmp_gt_u32_e64 s[4:5], s96, v19
	v_mfma_f32_16x16x32_bf16 v[78:81], v[82:85], v[0:3], 0
	s_and_b64 s[2:3], vcc, s[4:5]
	v_cndmask_b32_e64 v19, v179, 0, s[2:3]
	v_add_f32_e32 v57, v19, v77
	v_add_u32_e32 v19, 0xb0, v18
	s_waitcnt lgkmcnt(0)
	v_mfma_f32_16x16x32_bf16 v[70:73], v[70:73], v[4:7], v[78:81]
	v_cmp_gt_u32_e32 vcc, s72, v19
	v_sub_u32_e32 v19, v69, v19
	v_cmp_gt_u32_e64 s[4:5], s96, v19
	s_and_b64 s[2:3], vcc, s[4:5]
	v_cndmask_b32_e64 v19, v179, 0, s[2:3]
	s_nop 2
	v_add_f32_e32 v55, v19, v70
	v_add_u32_e32 v19, 0xb1, v18
	v_cmp_gt_u32_e32 vcc, s72, v19
	v_sub_u32_e32 v19, v69, v19
	v_cmp_gt_u32_e64 s[4:5], s96, v19
	s_and_b64 s[2:3], vcc, s[4:5]
	ds_read_b128 v[74:77], v17 offset:24576
	ds_read_b128 v[82:85], v17 offset:26624
	v_cndmask_b32_e64 v19, v179, 0, s[2:3]
	v_add_f32_e32 v53, v19, v71
	v_add_u32_e32 v19, 0xb2, v18
	v_cmp_gt_u32_e32 vcc, s72, v19
	v_sub_u32_e32 v19, v69, v19
	v_cmp_gt_u32_e64 s[4:5], s96, v19
	ds_read_b128 v[78:81], v15 offset:24576
	s_and_b64 s[2:3], vcc, s[4:5]
	v_cndmask_b32_e64 v19, v179, 0, s[2:3]
	v_add_f32_e32 v56, v19, v72
	v_add_u32_e32 v19, 0xb3, v18
	v_cmp_gt_u32_e32 vcc, s72, v19
	v_sub_u32_e32 v19, v69, v19
	v_cmp_gt_u32_e64 s[4:5], s96, v19
	s_waitcnt lgkmcnt(2)
	v_mfma_f32_16x16x32_bf16 v[86:89], v[74:77], v[0:3], 0
	s_and_b64 s[2:3], vcc, s[4:5]
	v_cndmask_b32_e64 v19, v179, 0, s[2:3]
	v_add_f32_e32 v77, v19, v73
	v_add_u32_e32 v19, 0xc0, v18
	s_waitcnt lgkmcnt(0)
	v_mfma_f32_16x16x32_bf16 v[78:81], v[78:81], v[4:7], v[86:89]
	v_cmp_gt_u32_e32 vcc, s72, v19
	v_sub_u32_e32 v19, v69, v19
	v_cmp_gt_u32_e64 s[4:5], s96, v19
	s_and_b64 s[2:3], vcc, s[4:5]
	v_cndmask_b32_e64 v19, v179, 0, s[2:3]
	s_nop 2
	v_add_f32_e32 v75, v19, v78
	v_add_u32_e32 v19, 0xc1, v18
	v_cmp_gt_u32_e32 vcc, s72, v19
	v_sub_u32_e32 v19, v69, v19
	v_cmp_gt_u32_e64 s[4:5], s96, v19
	s_and_b64 s[2:3], vcc, s[4:5]
	v_cndmask_b32_e64 v19, v179, 0, s[2:3]
	v_add_f32_e32 v73, v19, v79
	v_add_u32_e32 v19, 0xc2, v18
	v_cmp_gt_u32_e32 vcc, s72, v19
	v_sub_u32_e32 v19, v69, v19
	v_cmp_gt_u32_e64 s[4:5], s96, v19
	s_and_b64 s[2:3], vcc, s[4:5]
	v_cndmask_b32_e64 v19, v179, 0, s[2:3]
	v_add_f32_e32 v72, v19, v80
	v_add_u32_e32 v19, 0xc3, v18
	v_cmp_gt_u32_e32 vcc, s72, v19
	v_sub_u32_e32 v19, v69, v19
	v_cmp_gt_u32_e64 s[4:5], s96, v19
	v_mfma_f32_16x16x32_bf16 v[82:85], v[82:85], v[0:3], 0
	s_and_b64 s[2:3], vcc, s[4:5]
	v_cndmask_b32_e64 v19, v179, 0, s[2:3]
	v_add_f32_e32 v71, v19, v81
	v_add_u32_e32 v19, 0xd0, v18
	v_mfma_f32_16x16x32_bf16 v[78:81], v[90:93], v[4:7], v[82:85]
	v_cmp_gt_u32_e32 vcc, s72, v19
	v_sub_u32_e32 v19, v69, v19
	v_cmp_gt_u32_e64 s[4:5], s96, v19
	s_and_b64 s[2:3], vcc, s[4:5]
	v_cndmask_b32_e64 v19, v179, 0, s[2:3]
	s_nop 2
	v_add_f32_e32 v67, v19, v78
	v_add_u32_e32 v19, 0xd1, v18
	v_cmp_gt_u32_e32 vcc, s72, v19
	v_sub_u32_e32 v19, v69, v19
	v_cmp_gt_u32_e64 s[4:5], s96, v19
	s_and_b64 s[2:3], vcc, s[4:5]
	ds_read_b128 v[82:85], v17 offset:28672
	ds_read_b128 v[90:93], v17 offset:30720
	v_cndmask_b32_e64 v19, v179, 0, s[2:3]
	v_add_f32_e32 v65, v19, v79
	v_add_u32_e32 v19, 0xd2, v18
	v_cmp_gt_u32_e32 vcc, s72, v19
	v_sub_u32_e32 v19, v69, v19
	v_cmp_gt_u32_e64 s[4:5], s96, v19
	ds_read_b128 v[86:89], v15 offset:28672
	s_and_b64 s[2:3], vcc, s[4:5]
	v_cndmask_b32_e64 v19, v179, 0, s[2:3]
	v_add_f32_e32 v70, v19, v80
	v_add_u32_e32 v19, 0xd3, v18
	v_cmp_gt_u32_e32 vcc, s72, v19
	v_sub_u32_e32 v19, v69, v19
	v_cmp_gt_u32_e64 s[4:5], s96, v19
	s_waitcnt lgkmcnt(2)
; template <int NKT, typename KofsF, typename BiasF> ...
;     ...
;     for (int j = 0; j < 4; ++j) s[kt][j] = acc[j] + bias(kt, g * 4 + j, fr);
;   }
;   float mx = -INFINITY;
; #pragma unroll
;   for (int kt = 0; kt < NKT; ++kt)
; #pragma unroll
;     for (int j = 0; j < 4; ++j) mx = fmaxf(mx, s[kt][j]);
;   mx = fmaxf(mx, bperm_xor(mx, lane, 16));
;   mx = fmaxf(mx, bperm_xor(mx, lane, 32));
; __device__ __forceinline__ void attnC_item(unsigned char* ws, int item, unsigned char* lds, int wv_) {
;     ...
;   auto bias = [&](int kt, int kj, int frq) -> float {
;     int ik = i0 - 128 + 16 * kt + kj;
;     int dd = (i0 + frq) - ik;
;     bool ok = (ik >= 0) && (ik < SEQ_) && (dd <= 128) && (dd >= -128);
;     return ok ? 0.f : -INFINITY;
;   };
	v_mfma_f32_16x16x32_bf16 v[94:97], v[82:85], v[0:3], 0
	s_and_b64 s[2:3], vcc, s[4:5]
	v_cndmask_b32_e64 v19, v179, 0, s[2:3]
	v_add_f32_e32 v83, v19, v81
	v_add_u32_e32 v19, 0xe0, v18
	s_waitcnt lgkmcnt(0)
	v_mfma_f32_16x16x32_bf16 v[84:87], v[86:89], v[4:7], v[94:97]
	v_cmp_gt_u32_e32 vcc, s72, v19
	v_sub_u32_e32 v19, v69, v19
	v_cmp_gt_u32_e64 s[4:5], s96, v19
	s_and_b64 s[2:3], vcc, s[4:5]
	v_cndmask_b32_e64 v19, v179, 0, s[2:3]
	s_nop 2
	v_add_f32_e32 v82, v19, v84
	v_add_u32_e32 v19, 0xe1, v18
	v_cmp_gt_u32_e32 vcc, s72, v19
	v_sub_u32_e32 v19, v69, v19
	v_cmp_gt_u32_e64 s[4:5], s96, v19
	s_and_b64 s[2:3], vcc, s[4:5]
	v_cndmask_b32_e64 v19, v179, 0, s[2:3]
	v_add_f32_e32 v81, v19, v85
	v_add_u32_e32 v19, 0xe2, v18
	v_cmp_gt_u32_e32 vcc, s72, v19
	v_sub_u32_e32 v19, v69, v19
	v_cmp_gt_u32_e64 s[4:5], s96, v19
	s_and_b64 s[2:3], vcc, s[4:5]
	v_cndmask_b32_e64 v19, v179, 0, s[2:3]
	v_add_f32_e32 v80, v19, v86
	v_add_u32_e32 v19, 0xe3, v18
	v_cmp_gt_u32_e32 vcc, s72, v19
	v_sub_u32_e32 v19, v69, v19
	v_cmp_gt_u32_e64 s[4:5], s96, v19
	v_mfma_f32_16x16x32_bf16 v[88:91], v[90:93], v[0:3], 0
	s_and_b64 s[2:3], vcc, s[4:5]
	v_cndmask_b32_e64 v19, v179, 0, s[2:3]
	v_add_f32_e32 v79, v19, v87
	v_add_u32_e32 v19, 0xf0, v18
	v_mfma_f32_16x16x32_bf16 v[84:87], v[98:101], v[4:7], v[88:91]
	v_cmp_gt_u32_e32 vcc, s72, v19
	v_sub_u32_e32 v19, v69, v19
	v_cmp_gt_u32_e64 s[4:5], s96, v19
	s_and_b64 s[2:3], vcc, s[4:5]
	v_cndmask_b32_e64 v19, v179, 0, s[2:3]
	s_nop 2
	v_add_f32_e32 v76, v19, v84
	v_add_u32_e32 v19, 0xf1, v18
	v_cmp_gt_u32_e32 vcc, s72, v19
	v_sub_u32_e32 v19, v69, v19
	v_cmp_gt_u32_e64 s[4:5], s96, v19
	ds_read_b128 v[88:91], v17 offset:32768
	ds_read_b128 v[96:99], v17 offset:34816
	s_and_b64 s[2:3], vcc, s[4:5]
	v_cndmask_b32_e64 v19, v179, 0, s[2:3]
	v_add_f32_e32 v74, v19, v85
	v_add_u32_e32 v19, 0xf2, v18
	v_cmp_gt_u32_e32 vcc, s72, v19
	v_sub_u32_e32 v19, v69, v19
	ds_read_b128 v[92:95], v15 offset:32768
	ds_read_b128 v[100:103], v15 offset:34816
	v_cmp_gt_u32_e64 s[4:5], s96, v19
	s_and_b64 s[2:3], vcc, s[4:5]
	v_cndmask_b32_e64 v19, v179, 0, s[2:3]
	v_add_f32_e32 v78, v19, v86
	v_add_u32_e32 v19, 0xf3, v18
	v_cmp_gt_u32_e32 vcc, s72, v19
	v_sub_u32_e32 v19, v69, v19
	s_waitcnt lgkmcnt(3)
	v_mfma_f32_16x16x32_bf16 v[88:91], v[88:91], v[0:3], 0
	v_cmp_gt_u32_e64 s[4:5], s96, v19
	s_and_b64 s[2:3], vcc, s[4:5]
	v_cndmask_b32_e64 v17, v179, 0, s[2:3]
	v_add_u32_e32 v15, 0x100, v18
	v_add_f32_e32 v85, v17, v87
	s_waitcnt lgkmcnt(1)
	v_mfma_f32_16x16x32_bf16 v[86:89], v[92:95], v[4:7], v[88:91]
	v_cmp_gt_u32_e32 vcc, s72, v15
	v_sub_u32_e32 v15, v69, v15
	v_cmp_gt_u32_e64 s[4:5], s96, v15
	s_and_b64 s[2:3], vcc, s[4:5]
	v_cndmask_b32_e64 v15, v179, 0, s[2:3]
	s_nop 2
	v_add_f32_e32 v84, v15, v86
	v_add_u32_e32 v15, 0x101, v18
	v_cmp_gt_u32_e32 vcc, s72, v15
	v_sub_u32_e32 v15, v69, v15
	v_cmp_gt_u32_e64 s[4:5], s96, v15
	s_and_b64 s[2:3], vcc, s[4:5]
	v_cndmask_b32_e64 v15, v179, 0, s[2:3]
	v_add_f32_e32 v19, v15, v87
	v_add_u32_e32 v15, 0x102, v18
	v_cmp_gt_u32_e32 vcc, s72, v15
	v_sub_u32_e32 v15, v69, v15
	v_cmp_gt_u32_e64 s[4:5], s96, v15
	s_and_b64 s[2:3], vcc, s[4:5]
	v_mfma_f32_16x16x32_bf16 v[0:3], v[96:99], v[0:3], 0
	v_cndmask_b32_e64 v15, v179, 0, s[2:3]
	v_add_f32_e32 v17, v15, v88
	v_add_u32_e32 v15, 0x103, v18
	v_cmp_gt_u32_e32 vcc, s72, v15
	v_sub_u32_e32 v15, v69, v15
	v_cmp_gt_u32_e64 s[4:5], s96, v15
	s_waitcnt lgkmcnt(0)
	v_mfma_f32_16x16x32_bf16 v[0:3], v[100:103], v[4:7], v[0:3]
	v_add_u32_e32 v4, 0x110, v18
	s_and_b64 s[2:3], vcc, s[4:5]
	v_cmp_gt_u32_e32 vcc, s72, v4
	v_sub_u32_e32 v4, v69, v4
	v_cmp_gt_u32_e64 s[4:5], s96, v4
	v_cndmask_b32_e64 v15, v179, 0, s[2:3]
	s_and_b64 s[2:3], vcc, s[4:5]
	v_cndmask_b32_e64 v4, v179, 0, s[2:3]
	v_add_f32_e32 v6, v4, v0
	v_add_u32_e32 v0, 0x111, v18
	v_cmp_gt_u32_e32 vcc, s72, v0
	v_sub_u32_e32 v0, v69, v0
	v_cmp_gt_u32_e64 s[4:5], s96, v0
	s_and_b64 s[2:3], vcc, s[4:5]
	v_cndmask_b32_e64 v0, v179, 0, s[2:3]
	v_add_f32_e32 v5, v0, v1
	v_add_u32_e32 v0, 0x112, v18
	v_cmp_gt_u32_e32 vcc, s72, v0
	v_sub_u32_e32 v0, v69, v0
	v_cmp_gt_u32_e64 s[4:5], s96, v0
	s_and_b64 s[2:3], vcc, s[4:5]
	v_cndmask_b32_e64 v0, v179, 0, s[2:3]
	v_add_f32_e32 v4, v0, v2
	v_add_u32_e32 v0, 0x113, v18
	v_cmp_gt_u32_e32 vcc, s72, v0
	v_sub_u32_e32 v0, v69, v0
	v_cmp_gt_u32_e64 s[4:5], s96, v0
	s_and_b64 s[2:3], vcc, s[4:5]
	v_cndmask_b32_e64 v0, v179, 0, s[2:3]
	s_mov_b32 s2, 0xff800000
	v_add_f32_e32 v3, v0, v3
	v_max3_f32 v0, v46, s2, v45
	v_max3_f32 v0, v0, v44, v43
	v_max3_f32 v0, v0, v41, v39
	v_max3_f32 v0, v0, v36, v37
	v_max3_f32 v0, v0, v35, v32
	v_max3_f32 v0, v0, v29, v30
	v_max3_f32 v0, v0, v27, v25
	v_max3_f32 v0, v0, v24, v23
	v_max3_f32 v0, v0, v21, v20
	v_max3_f32 v0, v0, v22, v42
	v_max3_f32 v0, v0, v40, v38
	v_max3_f32 v0, v0, v34, v33
	v_max3_f32 v0, v0, v28, v26
	v_max3_f32 v0, v0, v31, v64
	v_max3_f32 v0, v0, v62, v61
	v_max3_f32 v0, v0, v58, v59
	v_max3_f32 v0, v0, v54, v52
	v_max3_f32 v0, v0, v51, v50
	v_max3_f32 v0, v0, v48, v47
	v_max3_f32 v0, v0, v49, v68
	v_max3_f32 v0, v0, v66, v63
	v_max3_f32 v0, v0, v60, v57
	v_max3_f32 v0, v0, v55, v53
	v_max3_f32 v0, v0, v56, v77
	v_max3_f32 v0, v0, v75, v73
	v_max3_f32 v0, v0, v72, v71
	v_max3_f32 v0, v0, v67, v65
	v_max3_f32 v0, v0, v70, v83
	v_max3_f32 v0, v0, v82, v81
	v_max3_f32 v0, v0, v80, v79
	v_max3_f32 v0, v0, v76, v74
	v_max3_f32 v0, v0, v78, v85
	v_add_f32_e32 v15, v15, v89
	v_max3_f32 v0, v0, v84, v19
	v_max3_f32 v0, v0, v17, v15
	v_max3_f32 v0, v0, v6, v5
	v_lshlrev_b32_e32 v1, 2, v16
	v_max3_f32 v0, v0, v4, v3
	v_xor_b32_e32 v2, 64, v1
	ds_bpermute_b32 v7, v2, v0
	s_waitcnt lgkmcnt(0)
; template <int NKT, typename KofsF, typename BiasF> ...
;     ...
;   mx = fmaxf(mx, bperm_xor(mx, lane, 16));
;   mx = fmaxf(mx, bperm_xor(mx, lane, 32));
;   if (has_sink) mx = fmaxf(mx, sinkv);
;   float l = 0.f;
; #pragma unroll
;   for (int kt = 0; kt < NKT; ++kt)
; #pragma unroll
;     for (int j = 0; j < 4; ++j) {
;       float pz = exp2f((s[kt][j] - mx) * 1.4426950408889634f);
;       l += pz;
;       s[kt][j] = pz;
;     }
;   l += bperm_xor(l, lane, 16);
;   l += bperm_xor(l, lane, 32);
;   if (has_sink) l += exp2f((sinkv - mx) * 1.4426950408889634f);
	v_max_f32_e32 v7, v7, v7
	v_max_f32_e32 v7, v0, v7
	v_xor_b32_e32 v0, 0x80, v1
	ds_bpermute_b32 v1, v0, v7
	s_waitcnt vmcnt(0) lgkmcnt(0)
	v_max3_f32 v1, v7, v1, v9
	v_sub_f32_e32 v7, v46, v1
	v_mul_f32_e32 v16, 0x3fb8aa3b, v7
	v_sub_f32_e32 v44, v44, v1
	v_sub_f32_e32 v43, v43, v1
	v_exp_f32_e32 v7, v16
	v_sub_f32_e32 v16, v45, v1
	v_mul_f32_e32 v18, 0x3fb8aa3b, v16
	v_cmp_gt_f32_e64 s[4:5], s46, v18
	v_mul_f32_e32 v45, 0x3fb8aa3b, v44
	v_mul_f32_e32 v46, 0x3fb8aa3b, v43
	v_cndmask_b32_e64 v18, 0, v180, s[4:5]
	v_fmac_f32_e32 v18, 0x3fb8aa3b, v16
	v_exp_f32_e32 v16, v18
	v_sub_f32_e32 v41, v41, v1
	v_sub_f32_e32 v39, v39, v1
	v_exp_f32_e32 v44, v45
	v_sub_f32_e32 v36, v36, v1
	v_sub_f32_e32 v37, v37, v1
	v_exp_f32_e32 v46, v46
	v_mov_b32_e32 v43, v44
	v_mul_f32_e32 v45, 0x3fb8aa3b, v41
	v_mov_b32_e32 v44, v46
	v_mul_f32_e32 v46, 0x3fb8aa3b, v39
	v_exp_f32_e32 v41, v45
	v_cndmask_b32_e64 v18, 0, v178, s[4:5]
	v_exp_f32_e32 v46, v46
	v_mov_b32_e32 v39, v41
	v_mul_f32_e32 v45, 0x3fb8aa3b, v36
	v_mov_b32_e32 v41, v46
	v_mul_f32_e32 v46, 0x3fb8aa3b, v37
	v_exp_f32_e32 v36, v45
	v_ldexp_f32 v16, v16, v18
	v_add_f32_e32 v18, v7, v16
	v_add_f32_e32 v18, v43, v18
	v_exp_f32_e32 v37, v46
	v_add_f32_e32 v18, v44, v18
	v_add_f32_e32 v18, v39, v18
	v_add_f32_e32 v18, v41, v18
	v_add_f32_e32 v18, v36, v18
	v_add_f32_e32 v45, v37, v18
	v_sub_f32_e32 v18, v35, v1
	v_mul_f32_e32 v35, 0x3fb8aa3b, v18
	v_sub_f32_e32 v32, v32, v1
	v_mul_f32_e32 v46, 0x3fb8aa3b, v32
	v_exp_f32_e32 v18, v35
	v_sub_f32_e32 v29, v29, v1
	v_exp_f32_e32 v32, v46
	v_add_f32_e32 v35, v18, v45
	v_sub_f32_e32 v30, v30, v1
	v_mul_f32_e32 v45, 0x3fb8aa3b, v29
	v_mul_f32_e32 v46, 0x3fb8aa3b, v30
	v_add_f32_e32 v35, v32, v35
	v_exp_f32_e32 v29, v45
	v_sub_f32_e32 v27, v27, v1
	v_exp_f32_e32 v30, v46
	v_add_f32_e32 v35, v29, v35
	v_sub_f32_e32 v25, v25, v1
	v_add_f32_e32 v45, v30, v35
	v_mul_f32_e32 v35, 0x3fb8aa3b, v27
	v_mul_f32_e32 v46, 0x3fb8aa3b, v25
	v_sub_f32_e32 v24, v24, v1
	v_exp_f32_e32 v27, v35
	v_sub_f32_e32 v23, v23, v1
	v_mov_b32_e32 v35, v27
	v_exp_f32_e32 v25, v46
	v_add_f32_e32 v27, v35, v45
	v_mul_f32_e32 v46, 0x3fb8aa3b, v23
	v_mul_f32_e32 v45, 0x3fb8aa3b, v24
	v_add_f32_e32 v27, v25, v27
	v_sub_f32_e32 v21, v21, v1
	v_exp_f32_e32 v24, v45
	v_sub_f32_e32 v20, v20, v1
	v_mov_b32_e32 v45, v24
	v_exp_f32_e32 v23, v46
	v_add_f32_e32 v24, v45, v27
	v_sub_f32_e32 v22, v22, v1
	v_mov_b32_e32 v46, v23
	v_add_f32_e32 v23, v46, v24
	v_mul_f32_e32 v24, 0x3fb8aa3b, v21
	v_mul_f32_e32 v27, 0x3fb8aa3b, v20
	v_sub_f32_e32 v38, v38, v1
	v_exp_f32_e32 v21, v24
	v_sub_f32_e32 v33, v33, v1
	v_sub_f32_e32 v26, v26, v1
	v_exp_f32_e32 v27, v27
	v_mov_b32_e32 v20, v21
	v_mul_f32_e32 v24, 0x3fb8aa3b, v22
	v_mov_b32_e32 v21, v27
	v_sub_f32_e32 v27, v42, v1
	v_mul_f32_e32 v42, 0x3fb8aa3b, v27
	v_exp_f32_e32 v22, v24
	v_add_f32_e32 v23, v20, v23
	v_add_f32_e32 v23, v21, v23
	v_exp_f32_e32 v27, v42
	v_mov_b32_e32 v24, v22
	v_add_f32_e32 v22, v24, v23
	v_sub_f32_e32 v23, v40, v1
	v_mul_f32_e32 v40, 0x3fb8aa3b, v23
	v_mul_f32_e32 v42, 0x3fb8aa3b, v38
	v_add_f32_e32 v22, v27, v22
	v_exp_f32_e32 v23, v40
	v_sub_f32_e32 v50, v50, v1
	v_sub_f32_e32 v47, v47, v1
	v_exp_f32_e32 v42, v42
	v_mov_b32_e32 v38, v23
	v_add_f32_e32 v22, v38, v22
	v_mov_b32_e32 v40, v42
	v_sub_f32_e32 v23, v34, v1
	v_mul_f32_e32 v34, 0x3fb8aa3b, v23
	v_mul_f32_e32 v42, 0x3fb8aa3b, v33
	v_add_f32_e32 v22, v40, v22
	v_exp_f32_e32 v23, v34
	v_sub_f32_e32 v53, v53, v1
	v_mov_b32_e32 v69, v23
	v_exp_f32_e32 v33, v42
	v_add_f32_e32 v22, v69, v22
	v_sub_f32_e32 v42, v61, v1
	v_mov_b32_e32 v86, v33
	v_add_f32_e32 v23, v86, v22
	v_sub_f32_e32 v22, v28, v1
	v_mul_f32_e32 v28, 0x3fb8aa3b, v22
	v_mul_f32_e32 v33, 0x3fb8aa3b, v26
	v_mul_f32_e32 v61, 0x3fb8aa3b, v42
	v_exp_f32_e32 v22, v28
	v_sub_f32_e32 v65, v65, v1
	v_exp_f32_e32 v26, v33
	v_add_f32_e32 v28, v22, v23
	v_sub_f32_e32 v33, v64, v1
	v_mov_b32_e32 v23, v26
	v_add_f32_e32 v26, v23, v28
	v_sub_f32_e32 v28, v31, v1
	v_mul_f32_e32 v31, 0x3fb8aa3b, v28
	v_mul_f32_e32 v34, 0x3fb8aa3b, v33
	v_sub_f32_e32 v74, v74, v1
	v_exp_f32_e32 v28, v31
	v_sub_f32_e32 v19, v19, v1
	v_mov_b32_e32 v31, v28
	v_exp_f32_e32 v33, v34
	v_add_f32_e32 v26, v31, v26
	v_sub_f32_e32 v17, v17, v1
	v_sub_f32_e32 v28, v62, v1
	v_mul_f32_e32 v34, 0x3fb8aa3b, v28
	v_add_f32_e32 v26, v33, v26
	v_sub_f32_e32 v15, v15, v1
	v_exp_f32_e32 v28, v34
	v_cmp_gt_f32_e32 vcc, s46, v61
	v_sub_f32_e32 v6, v6, v1
	v_sub_f32_e32 v5, v5, v1
	v_cndmask_b32_e32 v61, 0, v180, vcc
	v_fmac_f32_e32 v61, 0x3fb8aa3b, v42
	v_exp_f32_e32 v42, v61
	v_mov_b32_e32 v61, v28
	v_cndmask_b32_e32 v28, 0, v178, vcc
	v_add_f32_e32 v26, v61, v26
	v_ldexp_f32 v62, v42, v28
	v_sub_f32_e32 v28, v58, v1
	v_mul_f32_e32 v34, 0x3fb8aa3b, v28
	v_sub_f32_e32 v42, v59, v1
	v_mul_f32_e32 v58, 0x3fb8aa3b, v42
	v_exp_f32_e32 v28, v34
	v_add_f32_e32 v26, v62, v26
	v_sub_f32_e32 v4, v4, v1
	v_exp_f32_e32 v42, v58
	v_mov_b32_e32 v58, v28
	v_add_f32_e32 v26, v58, v26
	v_mov_b32_e32 v59, v42
	v_add_f32_e32 v28, v59, v26
	v_sub_f32_e32 v26, v54, v1
	v_mul_f32_e32 v34, 0x3fb8aa3b, v26
	v_sub_f32_e32 v42, v52, v1
	v_mul_f32_e32 v52, 0x3fb8aa3b, v42
	v_exp_f32_e32 v26, v34
	v_sub_f32_e32 v3, v3, v1
	v_exp_f32_e32 v42, v52
	v_add_f32_e32 v34, v26, v28
	v_mul_f32_e32 v52, 0x3fb8aa3b, v50
	v_mov_b32_e32 v28, v42
	v_sub_f32_e32 v42, v51, v1
	v_mul_f32_e32 v51, 0x3fb8aa3b, v42
	v_add_f32_e32 v34, v28, v34
	s_nop 0
	v_exp_f32_e32 v42, v51
	s_nop 1
	v_exp_f32_e32 v52, v52
	v_mov_b32_e32 v50, v42
	v_add_f32_e32 v34, v50, v34
	v_mov_b32_e32 v51, v52
	v_sub_f32_e32 v42, v48, v1
	v_mul_f32_e32 v48, 0x3fb8aa3b, v42
	v_mul_f32_e32 v52, 0x3fb8aa3b, v47
	v_add_f32_e32 v34, v51, v34
; template <int NKT, typename KofsF, typename BiasF> ...
;     ...
;   float l = 0.f;
; #pragma unroll
;   for (int kt = 0; kt < NKT; ++kt)
; #pragma unroll
;     for (int j = 0; j < 4; ++j) {
;       float pz = exp2f((s[kt][j] - mx) * 1.4426950408889634f);
;       l += pz;
;       s[kt][j] = pz;
;     }
;   l += bperm_xor(l, lane, 16);
;   l += bperm_xor(l, lane, 32);
;   if (has_sink) l += exp2f((sinkv - mx) * 1.4426950408889634f);
; #pragma unroll
;   for (int dt = 0; dt < 4; ++dt) oacc[dt] = f32x4{0.f, 0.f, 0.f, 0.f};
; #pragma unroll
;   for (int u = 0; u < NKT / 2; ++u) {
;     bf16x8 bp;
; #pragma unroll
;     for (int i = 0; i < 4; ++i) {
;       bp[i] = (short)f2bf(s[2 * u][i]);
;       bp[4 + i] = (short)f2bf(s[2 * u + 1][i]);
;     }
;     int k0 = kofs(2 * u) + g * 4, k1 = kofs(2 * u + 1) + g * 4;
; #pragma unroll
;     for (int dt = 0; dt < 4; ++dt) {
;       const u16* vrow = Vt + (dt * 16 + fr) * NKP;
;       uint2 v0 = *(const uint2*)(vrow + k0);
;       uint2 v1 = *(const uint2*)(vrow + k1);
;       union { uint4 q; bf16x8 v; } cv;
;       cv.q = make_uint4(v0.x, v0.y, v1.x, v1.y);
;       oacc[dt] = __builtin_amdgcn_mfma_f32_16x16x32_bf16(cv.v, bp, oacc[dt], 0, 0, 0);
;     }
	v_exp_f32_e32 v42, v48
	s_nop 0
	v_mov_b32_e32 v54, v42
	s_nop 0
	v_exp_f32_e32 v47, v52
	v_sub_f32_e32 v48, v68, v1
	v_add_f32_e32 v34, v54, v34
	v_mov_b32_e32 v64, v47
	v_sub_f32_e32 v42, v49, v1
	v_mul_f32_e32 v47, 0x3fb8aa3b, v42
	v_mul_f32_e32 v49, 0x3fb8aa3b, v48
	v_add_f32_e32 v34, v64, v34
	v_exp_f32_e32 v42, v47
	v_sub_f32_e32 v52, v57, v1
	v_mov_b32_e32 v68, v42
	v_exp_f32_e32 v48, v49
	v_add_f32_e32 v34, v68, v34
	v_mul_f32_e32 v57, 0x3fb8aa3b, v52
	v_mov_b32_e32 v87, v48
	v_add_f32_e32 v42, v87, v34
	v_sub_f32_e32 v34, v66, v1
	v_mul_f32_e32 v47, 0x3fb8aa3b, v34
	v_sub_f32_e32 v48, v63, v1
	v_mul_f32_e32 v49, 0x3fb8aa3b, v48
	v_exp_f32_e32 v34, v47
	s_nop 0
	v_exp_f32_e32 v48, v49
	v_add_f32_e32 v47, v34, v42
	v_mov_b32_e32 v42, v48
	v_sub_f32_e32 v48, v60, v1
	v_mul_f32_e32 v49, 0x3fb8aa3b, v48
	v_add_f32_e32 v47, v42, v47
	v_sub_f32_e32 v60, v71, v1
	v_exp_f32_e32 v48, v49
	v_mul_f32_e32 v66, 0x3fb8aa3b, v60
	v_mov_b32_e32 v49, v48
	v_exp_f32_e32 v52, v57
	v_mul_f32_e32 v57, 0x3fb8aa3b, v53
	v_add_f32_e32 v47, v49, v47
	v_sub_f32_e32 v48, v55, v1
	v_mul_f32_e32 v55, 0x3fb8aa3b, v48
	v_add_f32_e32 v47, v52, v47
	s_nop 0
	v_exp_f32_e32 v48, v55
	s_nop 0
	v_mov_b32_e32 v63, v48
	s_nop 0
	v_exp_f32_e32 v53, v57
	v_sub_f32_e32 v55, v77, v1
	v_add_f32_e32 v47, v63, v47
	v_mov_b32_e32 v57, v53
	v_sub_f32_e32 v48, v56, v1
	v_mul_f32_e32 v53, 0x3fb8aa3b, v48
	v_mul_f32_e32 v56, 0x3fb8aa3b, v55
	v_add_f32_e32 v47, v57, v47
	v_exp_f32_e32 v48, v53
	s_nop 0
	v_mov_b32_e32 v77, v48
	s_nop 0
	v_exp_f32_e32 v55, v56
	v_add_f32_e32 v47, v77, v47
	v_mov_b32_e32 v88, v55
	v_add_f32_e32 v48, v88, v47
	v_sub_f32_e32 v47, v75, v1
	v_mul_f32_e32 v53, 0x3fb8aa3b, v47
	v_sub_f32_e32 v55, v73, v1
	v_mul_f32_e32 v56, 0x3fb8aa3b, v55
	v_exp_f32_e32 v47, v53
	v_sub_f32_e32 v75, v79, v1
	v_exp_f32_e32 v55, v56
	v_add_f32_e32 v53, v47, v48
	v_mul_f32_e32 v79, 0x3fb8aa3b, v75
	v_mov_b32_e32 v48, v55
	v_sub_f32_e32 v55, v72, v1
	v_mul_f32_e32 v56, 0x3fb8aa3b, v55
	v_add_f32_e32 v53, v48, v53
	s_nop 0
	v_exp_f32_e32 v55, v56
	v_cmp_gt_f32_e32 vcc, s46, v66
	v_mov_b32_e32 v56, v55
	s_nop 0
	v_cndmask_b32_e32 v66, 0, v180, vcc
	v_fmac_f32_e32 v66, 0x3fb8aa3b, v60
	v_exp_f32_e32 v60, v66
	v_cndmask_b32_e32 v55, 0, v178, vcc
	v_add_f32_e32 v53, v56, v53
	v_ldexp_f32 v60, v60, v55
	v_sub_f32_e32 v55, v67, v1
	v_mul_f32_e32 v66, 0x3fb8aa3b, v55
	v_mul_f32_e32 v67, 0x3fb8aa3b, v65
	v_add_f32_e32 v53, v60, v53
	v_exp_f32_e32 v55, v66
	s_nop 0
	v_mov_b32_e32 v71, v55
	s_nop 0
	v_exp_f32_e32 v65, v67
	v_sub_f32_e32 v67, v83, v1
	v_add_f32_e32 v53, v71, v53
	v_sub_f32_e32 v55, v70, v1
	v_mul_f32_e32 v66, 0x3fb8aa3b, v55
	v_mul_f32_e32 v70, 0x3fb8aa3b, v67
	v_add_f32_e32 v53, v65, v53
	v_exp_f32_e32 v55, v66
	v_bfe_u32 v83, v36, 16, 1
	s_nop 0
	v_exp_f32_e32 v67, v70
	v_mov_b32_e32 v70, v55
	v_add_f32_e32 v53, v70, v53
	v_mov_b32_e32 v72, v67
	v_add_f32_e32 v55, v72, v53
	v_sub_f32_e32 v53, v82, v1
	v_mul_f32_e32 v66, 0x3fb8aa3b, v53
	v_sub_f32_e32 v67, v81, v1
	v_mul_f32_e32 v73, 0x3fb8aa3b, v67
	v_exp_f32_e32 v53, v66
	v_bfe_u32 v82, v37, 16, 1
	v_exp_f32_e32 v67, v73
	v_add_f32_e32 v66, v53, v55
	v_bfe_u32 v81, v43, 16, 1
	v_mov_b32_e32 v55, v67
	v_add_f32_e32 v67, v55, v66
	v_sub_f32_e32 v66, v80, v1
	v_mul_f32_e32 v73, 0x3fb8aa3b, v66
	v_add3_u32 v43, v43, v81, s48
	s_nop 0
	v_exp_f32_e32 v66, v73
	v_cmp_gt_f32_e32 vcc, s46, v79
	s_nop 0
	s_nop 0
	v_cndmask_b32_e32 v79, 0, v180, vcc
	v_fmac_f32_e32 v79, 0x3fb8aa3b, v75
	v_exp_f32_e32 v75, v79
	v_add_f32_e32 v73, v66, v67
	v_cndmask_b32_e32 v67, 0, v178, vcc
	v_mul_f32_e32 v79, 0x3fb8aa3b, v74
	v_ldexp_f32 v67, v75, v67
	v_add_f32_e32 v75, v67, v73
	v_sub_f32_e32 v73, v76, v1
	v_mul_f32_e32 v76, 0x3fb8aa3b, v73
	s_nop 1
	v_exp_f32_e32 v73, v76
	s_nop 0
	v_exp_f32_e32 v74, v79
	v_add_f32_e32 v75, v73, v75
	v_sub_f32_e32 v79, v85, v1
	v_add_f32_e32 v76, v74, v75
	v_sub_f32_e32 v75, v78, v1
	v_mul_f32_e32 v78, 0x3fb8aa3b, v75
	v_mul_f32_e32 v80, 0x3fb8aa3b, v79
	v_bfe_u32 v85, v7, 16, 1
	v_exp_f32_e32 v75, v78
	v_add3_u32 v94, v7, v85, s48
	v_exp_f32_e32 v79, v80
	v_add_f32_e32 v78, v75, v76
	v_lshlrev_b32_e32 v7, 3, v13
	v_mov_b32_e32 v76, v79
	v_add_f32_e32 v89, v76, v78
	v_sub_f32_e32 v78, v84, v1
	v_mul_f32_e32 v79, 0x3fb8aa3b, v78
	v_cmp_gt_f32_e32 vcc, s46, v79
	v_bfe_u32 v79, v39, 16, 1
	v_bfe_u32 v84, v16, 16, 1
	v_cndmask_b32_e32 v98, 0, v180, vcc
	v_fmac_f32_e32 v98, 0x3fb8aa3b, v78
	v_bfe_u32 v78, v41, 16, 1
	v_add3_u32 v39, v39, v79, s48
	v_add3_u32 v41, v41, v78, s48
	v_add3_u32 v110, 0, v14, v7
	v_add3_u32 v7, v36, v83, s48
	v_add3_u32 v14, v37, v82, s48
	v_bfe_u32 v80, v44, 16, 1
	v_add3_u32 v16, v16, v84, s48
	v_add_u32_e32 v13, 0x9000, v110
	v_perm_b32 v85, v14, v7, s47
	v_add_u32_e32 v7, 0xb000, v110
	v_perm_b32 v84, v41, v39, s47
	v_add_u32_e32 v14, 0xd800, v110
	v_add_u32_e32 v41, 0xf800, v110
	v_add3_u32 v44, v44, v80, s48
	ds_read2_b64 v[78:81], v13 offset1:4
	ds_read2_b64 v[90:93], v7 offset0:160 offset1:164
	v_perm_b32 v82, v16, v94, s47
	ds_read2_b64 v[94:97], v14 offset0:64 offset1:68
	v_exp_f32_e32 v16, v98
	ds_read2_b64 v[98:101], v41 offset0:224 offset1:228
	v_cndmask_b32_e32 v36, 0, v178, vcc
	v_perm_b32 v83, v44, v43, s47
	v_ldexp_f32 v16, v16, v36
	v_mul_f32_e32 v36, 0x3fb8aa3b, v19
	v_cmp_gt_f32_e32 vcc, s46, v36
	s_waitcnt lgkmcnt(3)
	v_mfma_f32_16x16x32_bf16 v[78:81], v[78:81], v[82:85], 0
	v_bfe_u32 v39, v25, 16, 1
	v_cndmask_b32_e32 v36, 0, v180, vcc
	v_fmac_f32_e32 v36, 0x3fb8aa3b, v19
	s_waitcnt lgkmcnt(2)
	v_mfma_f32_16x16x32_bf16 v[90:93], v[90:93], v[82:85], 0
	v_exp_f32_e32 v19, v36
	v_bfe_u32 v43, v35, 16, 1
	ds_read2_b64 v[106:109], v7 offset0:168 offset1:172
	s_waitcnt lgkmcnt(2)
; template <int NKT, typename KofsF, typename BiasF> ...
;     ...
;   for (int u = 0; u < NKT / 2; ++u) {
;     bf16x8 bp;
; #pragma unroll
;     for (int i = 0; i < 4; ++i) {
;       bp[i] = (short)f2bf(s[2 * u][i]);
;       bp[4 + i] = (short)f2bf(s[2 * u + 1][i]);
;     }
;     int k0 = kofs(2 * u) + g * 4, k1 = kofs(2 * u + 1) + g * 4;
; #pragma unroll
;     for (int dt = 0; dt < 4; ++dt) {
;       const u16* vrow = Vt + (dt * 16 + fr) * NKP;
;       uint2 v0 = *(const uint2*)(vrow + k0);
;       uint2 v1 = *(const uint2*)(vrow + k1);
;       union { uint4 q; bf16x8 v; } cv;
;       cv.q = make_uint4(v0.x, v0.y, v1.x, v1.y);
;       oacc[dt] = __builtin_amdgcn_mfma_f32_16x16x32_bf16(cv.v, bp, oacc[dt], 0, 0, 0);
;     }
	v_mfma_f32_16x16x32_bf16 v[94:97], v[94:97], v[82:85], 0
	v_add3_u32 v35, v35, v43, s48
	v_add3_u32 v25, v25, v39, s48
	v_perm_b32 v104, v25, v35, s47
	s_waitcnt lgkmcnt(1)
	v_mfma_f32_16x16x32_bf16 v[82:85], v[98:101], v[82:85], 0
	v_bfe_u32 v98, v29, 16, 1
	v_bfe_u32 v99, v32, 16, 1
	v_bfe_u32 v100, v18, 16, 1
	v_add3_u32 v18, v18, v100, s48
	v_add3_u32 v32, v32, v99, s48
	v_add3_u32 v29, v29, v98, s48
	ds_read2_b64 v[98:101], v13 offset0:8 offset1:12
	v_cndmask_b32_e32 v25, 0, v178, vcc
	v_perm_b32 v102, v32, v18, s47
	v_add_f32_e32 v18, v16, v89
	v_ldexp_f32 v89, v19, v25
	v_add_f32_e32 v25, v89, v18
	v_mul_f32_e32 v18, 0x3fb8aa3b, v17
	v_cmp_gt_f32_e32 vcc, s46, v18
	v_bfe_u32 v36, v46, 16, 1
	v_bfe_u32 v37, v45, 16, 1
	v_bfe_u32 v44, v30, 16, 1
	v_cndmask_b32_e32 v18, 0, v180, vcc
	v_add3_u32 v30, v30, v44, s48
	v_add3_u32 v37, v45, v37, s48
	v_add3_u32 v36, v46, v36, s48
	v_fmac_f32_e32 v18, 0x3fb8aa3b, v17
	v_perm_b32 v105, v36, v37, s47
	v_perm_b32 v103, v30, v29, s47
	v_exp_f32_e32 v17, v18
	v_bfe_u32 v18, v40, 16, 1
	v_bfe_u32 v19, v38, 16, 1
	v_bfe_u32 v32, v27, 16, 1
	v_bfe_u32 v35, v24, 16, 1
	v_bfe_u32 v36, v21, 16, 1
	v_bfe_u32 v37, v20, 16, 1
	s_waitcnt lgkmcnt(0)
	v_mfma_f32_16x16x32_bf16 v[78:81], v[98:101], v[102:105], v[78:81]
	ds_read2_b64 v[98:101], v14 offset0:72 offset1:76
	v_add3_u32 v43, v20, v37, s48
	v_add3_u32 v36, v21, v36, s48
	v_mfma_f32_16x16x32_bf16 v[90:93], v[106:109], v[102:105], v[90:93]
	ds_read2_b64 v[106:109], v41 offset0:232 offset1:236
	v_add3_u32 v24, v24, v35, s48
	v_add3_u32 v27, v27, v32, s48
	v_add3_u32 v32, v38, v19, s48
	v_add3_u32 v35, v40, v18, s48
	ds_read2_b64 v[18:21], v13 offset0:16 offset1:20
	v_bfe_u32 v29, v86, 16, 1
	v_bfe_u32 v30, v69, 16, 1
	v_perm_b32 v37, v27, v24, s47
	v_cndmask_b32_e32 v24, 0, v178, vcc
	v_add3_u32 v30, v69, v30, s48
	v_add3_u32 v29, v86, v29, s48
	v_ldexp_f32 v17, v17, v24
	v_mul_f32_e32 v24, 0x3fb8aa3b, v15
	v_perm_b32 v39, v29, v30, s47
	v_perm_b32 v38, v35, v32, s47
	v_perm_b32 v36, v36, v43, s47
	v_add_f32_e32 v35, v17, v25
	v_cmp_gt_f32_e32 vcc, s46, v24
	v_bfe_u32 v24, v62, 16, 1
	v_bfe_u32 v25, v61, 16, 1
	v_bfe_u32 v32, v31, 16, 1
	v_bfe_u32 v40, v23, 16, 1
	v_bfe_u32 v43, v22, 16, 1
	s_waitcnt lgkmcnt(2)
	v_mfma_f32_16x16x32_bf16 v[94:97], v[98:101], v[102:105], v[94:97]
	ds_read2_b64 v[98:101], v7 offset0:176 offset1:180
	v_add3_u32 v43, v22, v43, s48
	v_add3_u32 v40, v23, v40, s48
	s_waitcnt lgkmcnt(2)
	v_mfma_f32_16x16x32_bf16 v[82:85], v[106:109], v[102:105], v[82:85]
	ds_read2_b64 v[102:105], v14 offset0:80 offset1:84
	v_add3_u32 v31, v31, v32, s48
	v_add3_u32 v32, v61, v25, s48
	s_waitcnt lgkmcnt(2)
	v_mfma_f32_16x16x32_bf16 v[18:21], v[18:21], v[36:39], v[78:81]
	v_add3_u32 v44, v62, v24, s48
	ds_read2_b64 v[22:25], v13 offset0:24 offset1:28
	v_cndmask_b32_e32 v27, 0, v180, vcc
	ds_read2_b64 v[78:81], v41 offset0:240 offset1:244
	v_fmac_f32_e32 v27, 0x3fb8aa3b, v15
	v_bfe_u32 v15, v59, 16, 1
	v_bfe_u32 v29, v58, 16, 1
	v_bfe_u32 v30, v33, 16, 1
	v_add3_u32 v30, v33, v30, s48
	v_add3_u32 v29, v58, v29, s48
	v_add3_u32 v15, v59, v15, s48
	v_perm_b32 v33, v15, v29, s47
	v_perm_b32 v32, v44, v32, s47
	v_perm_b32 v31, v30, v31, s47
	v_perm_b32 v30, v40, v43, s47
	s_waitcnt lgkmcnt(3)
	v_mfma_f32_16x16x32_bf16 v[90:93], v[98:101], v[36:39], v[90:93]
	v_exp_f32_e32 v15, v27
	v_cndmask_b32_e32 v27, 0, v178, vcc
	v_bfe_u32 v29, v54, 16, 1
	s_waitcnt lgkmcnt(2)
	v_mfma_f32_16x16x32_bf16 v[94:97], v[102:105], v[36:39], v[94:97]
	v_ldexp_f32 v15, v15, v27
	v_mul_f32_e32 v27, 0x3fb8aa3b, v6
	v_cmp_gt_f32_e32 vcc, s46, v27
	s_waitcnt lgkmcnt(0)
	v_mfma_f32_16x16x32_bf16 v[36:39], v[78:81], v[36:39], v[82:85]
	ds_read2_b64 v[78:81], v7 offset0:184 offset1:188
	v_bfe_u32 v27, v64, 16, 1
	v_add3_u32 v45, v64, v27, s48
	ds_read2_b64 v[82:85], v14 offset0:88 offset1:92
	v_mfma_f32_16x16x32_bf16 v[18:21], v[22:25], v[30:33], v[18:21]
	ds_read2_b64 v[22:25], v41 offset0:248 offset1:252
	v_cndmask_b32_e32 v40, 0, v180, vcc
	v_fmac_f32_e32 v40, 0x3fb8aa3b, v6
	s_waitcnt lgkmcnt(2)
	v_mfma_f32_16x16x32_bf16 v[78:81], v[78:81], v[30:33], v[90:93]
	v_bfe_u32 v6, v87, 16, 1
	v_add3_u32 v6, v87, v6, s48
	s_nop 0
	ds_read2_b64 v[90:93], v14 offset0:96 offset1:100
	s_waitcnt lgkmcnt(2)
	v_mfma_f32_16x16x32_bf16 v[82:85], v[82:85], v[30:33], v[94:97]
	v_sub_f32_e32 v1, v9, v1
	v_ashrrev_i32_e32 v9, 31, v8
	s_waitcnt lgkmcnt(1)
	v_mfma_f32_16x16x32_bf16 v[22:25], v[22:25], v[30:33], v[36:39]
	v_bfe_u32 v32, v50, 16, 1
	v_bfe_u32 v33, v28, 16, 1
	v_add3_u32 v43, v28, v33, s48
	v_bfe_u32 v36, v26, 16, 1
	v_add3_u32 v41, v26, v36, s48
	v_add3_u32 v44, v50, v32, s48
	v_add3_u32 v32, v54, v29, s48
	ds_read2_b64 v[26:29], v13 offset0:32 offset1:36
	v_bfe_u32 v30, v68, 16, 1
	v_bfe_u32 v31, v51, 16, 1
	v_add3_u32 v30, v68, v30, s48
	v_add3_u32 v31, v51, v31, s48
	v_perm_b32 v33, v6, v30, s47
	v_add_u32_e32 v6, 0x2500, v110
	v_perm_b32 v32, v45, v32, s47
	v_perm_b32 v31, v31, v44, s47
	v_perm_b32 v30, v43, v41, s47
	v_add_u32_e32 v50, 0xd800, v6
	ds_read2_b64 v[36:39], v7 offset0:192 offset1:196
	s_waitcnt lgkmcnt(1)
	v_mfma_f32_16x16x32_bf16 v[18:21], v[26:29], v[30:33], v[18:21]
	ds_read2_b64 v[26:29], v50 offset0:96 offset1:100
	v_exp_f32_e32 v6, v40
	v_add_f32_e32 v44, v15, v35
	s_waitcnt lgkmcnt(0)
; template <int NKT, typename KofsF, typename BiasF> ...
;     ...
;   l += bperm_xor(l, lane, 16);
;   l += bperm_xor(l, lane, 32);
;   if (has_sink) l += exp2f((sinkv - mx) * 1.4426950408889634f);
; #pragma unroll
;   for (int dt = 0; dt < 4; ++dt) oacc[dt] = f32x4{0.f, 0.f, 0.f, 0.f};
; #pragma unroll
;   for (int u = 0; u < NKT / 2; ++u) {
;     bf16x8 bp;
; #pragma unroll
;     for (int i = 0; i < 4; ++i) {
;       bp[i] = (short)f2bf(s[2 * u][i]);
;       bp[4 + i] = (short)f2bf(s[2 * u + 1][i]);
;     }
;     int k0 = kofs(2 * u) + g * 4, k1 = kofs(2 * u + 1) + g * 4;
; #pragma unroll
;     for (int dt = 0; dt < 4; ++dt) {
;       const u16* vrow = Vt + (dt * 16 + fr) * NKP;
;       uint2 v0 = *(const uint2*)(vrow + k0);
;       uint2 v1 = *(const uint2*)(vrow + k1);
;       union { uint4 q; bf16x8 v; } cv;
;       cv.q = make_uint4(v0.x, v0.y, v1.x, v1.y);
;       oacc[dt] = __builtin_amdgcn_mfma_f32_16x16x32_bf16(cv.v, bp, oacc[dt], 0, 0, 0);
;     }
	v_mfma_f32_16x16x32_bf16 v[22:25], v[26:29], v[30:33], v[22:25]
	v_bfe_u32 v26, v63, 16, 1
	v_bfe_u32 v27, v52, 16, 1
	v_bfe_u32 v28, v49, 16, 1
	v_bfe_u32 v29, v42, 16, 1
	v_add3_u32 v45, v42, v29, s48
	v_add3_u32 v46, v49, v28, s48
	v_add3_u32 v49, v52, v27, s48
	v_add3_u32 v40, v63, v26, s48
	ds_read2_b64 v[26:29], v13 offset0:40 offset1:44
	v_mfma_f32_16x16x32_bf16 v[36:39], v[36:39], v[30:33], v[78:81]
	v_cndmask_b32_e32 v35, 0, v178, vcc
	v_ldexp_f32 v6, v6, v35
	v_mul_f32_e32 v35, 0x3fb8aa3b, v5
	v_mfma_f32_16x16x32_bf16 v[78:81], v[90:93], v[30:33], v[82:85]
	v_bfe_u32 v30, v88, 16, 1
	v_bfe_u32 v31, v77, 16, 1
	v_bfe_u32 v32, v57, 16, 1
	v_bfe_u32 v33, v34, 16, 1
	v_add3_u32 v34, v34, v33, s48
	v_add3_u32 v32, v57, v32, s48
	v_add3_u32 v31, v77, v31, s48
	v_add3_u32 v30, v88, v30, s48
	v_perm_b32 v33, v30, v31, s47
	v_perm_b32 v32, v32, v40, s47
	v_perm_b32 v31, v49, v46, s47
	v_perm_b32 v30, v45, v34, s47
	ds_read2_b64 v[40:43], v7 offset0:200 offset1:204
	ds_read2_b64 v[82:85], v50 offset0:104 offset1:108
	s_waitcnt lgkmcnt(2)
	v_mfma_f32_16x16x32_bf16 v[18:21], v[26:29], v[30:33], v[18:21]
	ds_read2_b64 v[26:29], v14 offset0:104 offset1:108
	v_cmp_gt_f32_e32 vcc, s46, v35
	v_mul_f32_e32 v46, 0x3fb8aa3b, v4
	s_waitcnt lgkmcnt(2)
	v_mfma_f32_16x16x32_bf16 v[34:37], v[40:43], v[30:33], v[36:39]
	v_cndmask_b32_e32 v45, 0, v180, vcc
	v_fmac_f32_e32 v45, 0x3fb8aa3b, v5
	v_exp_f32_e32 v5, v45
	s_waitcnt lgkmcnt(0)
	v_mfma_f32_16x16x32_bf16 v[26:29], v[26:29], v[30:33], v[78:81]
	v_cndmask_b32_e32 v38, 0, v178, vcc
	v_bfe_u32 v39, v70, 16, 1
	v_ldexp_f32 v5, v5, v38
	v_mfma_f32_16x16x32_bf16 v[22:25], v[82:85], v[30:33], v[22:25]
	v_bfe_u32 v30, v71, 16, 1
	v_bfe_u32 v31, v60, 16, 1
	v_bfe_u32 v32, v56, 16, 1
	v_bfe_u32 v33, v48, 16, 1
	v_add3_u32 v48, v48, v33, s48
	v_add3_u32 v49, v56, v32, s48
	v_add3_u32 v52, v60, v31, s48
	v_add3_u32 v42, v71, v30, s48
	ds_read2_b64 v[30:33], v13 offset0:48 offset1:52
	v_bfe_u32 v38, v72, 16, 1
	v_bfe_u32 v40, v65, 16, 1
	v_bfe_u32 v41, v47, 16, 1
	v_add3_u32 v47, v47, v41, s48
	v_add3_u32 v40, v65, v40, s48
	v_add3_u32 v39, v70, v39, s48
	v_add3_u32 v38, v72, v38, s48
	v_perm_b32 v41, v38, v39, s47
	v_perm_b32 v40, v40, v42, s47
	v_perm_b32 v39, v52, v49, s47
	v_perm_b32 v38, v48, v47, s47
	v_add_f32_e32 v51, v6, v44
	ds_read2_b64 v[42:45], v7 offset0:208 offset1:212
	s_waitcnt lgkmcnt(1)
	v_mfma_f32_16x16x32_bf16 v[18:21], v[30:33], v[38:41], v[18:21]
	ds_read2_b64 v[30:33], v14 offset0:112 offset1:116
	v_cmp_gt_f32_e32 vcc, s46, v46
	ds_read2_b64 v[46:49], v50 offset0:112 offset1:116
	s_waitcnt lgkmcnt(2)
	v_mfma_f32_16x16x32_bf16 v[34:37], v[42:45], v[38:41], v[34:37]
	v_cndmask_b32_e32 v52, 0, v180, vcc
	v_fmac_f32_e32 v52, 0x3fb8aa3b, v4
	v_exp_f32_e32 v4, v52
	s_waitcnt lgkmcnt(1)
	v_mfma_f32_16x16x32_bf16 v[26:29], v[30:33], v[38:41], v[26:29]
	v_bfe_u32 v30, v74, 16, 1
	v_bfe_u32 v31, v73, 16, 1
	v_bfe_u32 v32, v67, 16, 1
	s_waitcnt lgkmcnt(0)
	v_mfma_f32_16x16x32_bf16 v[22:25], v[46:49], v[38:41], v[22:25]
	v_bfe_u32 v33, v66, 16, 1
	v_bfe_u32 v40, v55, 16, 1
	v_bfe_u32 v41, v53, 16, 1
	v_add3_u32 v46, v53, v41, s48
	v_add3_u32 v47, v55, v40, s48
	v_add3_u32 v48, v66, v33, s48
	v_add3_u32 v49, v67, v32, s48
	v_add3_u32 v40, v73, v31, s48
	v_add3_u32 v53, v74, v30, s48
	ds_read2_b64 v[30:33], v13 offset0:56 offset1:60
	v_cndmask_b32_e32 v42, 0, v178, vcc
	v_bfe_u32 v38, v76, 16, 1
	v_bfe_u32 v39, v75, 16, 1
	v_ldexp_f32 v4, v4, v42
	v_add3_u32 v39, v75, v39, s48
	v_add3_u32 v38, v76, v38, s48
	ds_read2_b64 v[42:45], v7 offset0:216 offset1:220
	v_perm_b32 v41, v38, v39, s47
	v_perm_b32 v40, v53, v40, s47
	v_perm_b32 v39, v49, v48, s47
	v_perm_b32 v38, v47, v46, s47
	v_mul_f32_e32 v52, 0x3fb8aa3b, v3
	ds_read2_b64 v[46:49], v14 offset0:120 offset1:124
	s_waitcnt lgkmcnt(2)
	v_mfma_f32_16x16x32_bf16 v[18:21], v[30:33], v[38:41], v[18:21]
	ds_read2_b64 v[30:33], v50 offset0:120 offset1:124
	v_cmp_gt_f32_e32 vcc, s46, v52
	v_add_f32_e32 v51, v5, v51
	s_waitcnt lgkmcnt(2)
	v_mfma_f32_16x16x32_bf16 v[34:37], v[42:45], v[38:41], v[34:37]
	v_cndmask_b32_e32 v52, 0, v180, vcc
	v_fmac_f32_e32 v52, 0x3fb8aa3b, v3
	v_exp_f32_e32 v3, v52
	v_cndmask_b32_e32 v43, 0, v178, vcc
	v_add_f32_e32 v42, v4, v51
	s_waitcnt lgkmcnt(1)
	v_mfma_f32_16x16x32_bf16 v[26:29], v[46:49], v[38:41], v[26:29]
	v_ldexp_f32 v3, v3, v43
	v_add_f32_e32 v42, v3, v42
	ds_bpermute_b32 v2, v2, v42
	s_waitcnt lgkmcnt(1)
	v_mfma_f32_16x16x32_bf16 v[22:25], v[30:33], v[38:41], v[22:25]
	v_bfe_u32 v38, v3, 16, 1
	v_bfe_u32 v39, v4, 16, 1
	v_bfe_u32 v40, v5, 16, 1
	v_bfe_u32 v30, v6, 16, 1
	v_bfe_u32 v41, v16, 16, 1
	v_add3_u32 v6, v6, v30, s48
	v_add3_u32 v5, v5, v40, s48
	v_add3_u32 v4, v4, v39, s48
	v_add3_u32 v3, v3, v38, s48
	v_add3_u32 v16, v16, v41, s48
	v_perm_b32 v41, v3, v4, s47
	v_perm_b32 v40, v5, v6, s47
	ds_read2_b64 v[4:7], v7 offset0:224 offset1:228
	v_bfe_u32 v31, v15, 16, 1
	v_bfe_u32 v32, v17, 16, 1
	v_bfe_u32 v33, v89, 16, 1
	v_add3_u32 v43, v89, v33, s48
	v_add3_u32 v17, v17, v32, s48
	v_add3_u32 v15, v15, v31, s48
	v_perm_b32 v39, v15, v17, s47
	v_perm_b32 v38, v43, v16, s47
	ds_read2_b64 v[30:33], v13 offset0:64 offset1:68
	s_waitcnt lgkmcnt(2)
	v_add_f32_e32 v13, v42, v2
	s_waitcnt lgkmcnt(1)
; __device__ __forceinline__ u32 pack2(float a, float b) { return (u32)f2bf(a) | ((u32)f2bf(b) << 16); }
; template <int NKT, typename KofsF, typename BiasF> ...
;     ...
;   l += bperm_xor(l, lane, 16);
;   l += bperm_xor(l, lane, 32);
;   if (has_sink) l += exp2f((sinkv - mx) * 1.4426950408889634f);
; __device__ __forceinline__ void attnC_item(unsigned char* ws, int item, unsigned char* lds, int wv_) {
;     ...
;   float inv = 1.f / lb;
;   u16* op = O + (size_t)tq * D_ + hq * 64;
; #pragma unroll
;   for (int dt = 0; dt < 4; ++dt)
;     *(uint2*)(op + dt * 16 + g * 4) = make_uint2(pack2(oacc[dt][0] * inv, oacc[dt][1] * inv), pack2(oacc[dt][2] * inv, oacc[dt][3] * inv));
	v_mfma_f32_16x16x32_bf16 v[2:5], v[4:7], v[38:41], v[34:37]
	v_mul_f32_e32 v6, 0x3fb8aa3b, v1
	v_cmp_gt_f32_e32 vcc, s46, v6
	ds_bpermute_b32 v0, v0, v13
	s_waitcnt lgkmcnt(1)
	v_mfma_f32_16x16x32_bf16 v[16:19], v[30:33], v[38:41], v[18:21]
	v_cndmask_b32_e32 v6, 0, v180, vcc
	v_fmac_f32_e32 v6, 0x3fb8aa3b, v1
	v_exp_f32_e32 v1, v6
	v_cndmask_b32_e32 v6, 0, v178, vcc
	s_waitcnt lgkmcnt(0)
	v_add_f32_e32 v0, v13, v0
	ds_read2_b64 v[30:33], v14 offset0:128 offset1:132
	v_ldexp_f32 v1, v1, v6
	v_add_f32_e32 v0, v1, v0
	v_div_scale_f32 v1, s[2:3], v0, v0, 1.0
	v_rcp_f32_e32 v6, v1
	s_waitcnt lgkmcnt(0)
	v_mfma_f32_16x16x32_bf16 v[26:29], v[30:33], v[38:41], v[26:29]
	v_fma_f32 v7, -v1, v6, 1.0
	v_fmac_f32_e32 v6, v7, v6
	v_div_scale_f32 v7, vcc, 1.0, v0, 1.0
	v_mul_f32_e32 v13, v7, v6
	v_fma_f32 v14, -v1, v13, v7
	v_fmac_f32_e32 v13, v14, v6
	v_fma_f32 v1, -v1, v13, v7
	v_div_fmas_f32 v1, v1, v6, v13
	v_div_fixup_f32 v0, v1, v0, 1.0
	v_lshlrev_b64 v[6:7], 12, v[8:9]
	v_lshrrev_b32_e32 v1, 1, v12
	v_mov_b32_e32 v8, v16
	v_mov_b32_e32 v9, v18
	v_lshl_add_u64 v[6:7], s[68:69], 0, v[6:7]
	v_pk_mul_f32 v[8:9], v[8:9], v[0:1] op_sel_hi:[1,0]
	v_mov_b32_e32 v18, v17
	v_lshl_add_u64 v[6:7], v[6:7], 0, v[10:11]
	v_and_b32_e32 v166, 24, v1
	v_pk_mul_f32 v[10:11], v[18:19], v[0:1] op_sel_hi:[1,0]
	v_and_b32_sdwa v1, v9, v177 dst_sel:DWORD dst_unused:UNUSED_PAD src0_sel:WORD_1 src1_sel:DWORD
	v_and_b32_sdwa v12, v8, v177 dst_sel:DWORD dst_unused:UNUSED_PAD src0_sel:WORD_1 src1_sel:DWORD
	v_add3_u32 v8, v8, v12, s48
	v_add3_u32 v1, v9, v1, s48
	v_and_b32_sdwa v9, v11, v177 dst_sel:DWORD dst_unused:UNUSED_PAD src0_sel:WORD_1 src1_sel:DWORD
	v_and_b32_sdwa v12, v10, v177 dst_sel:DWORD dst_unused:UNUSED_PAD src0_sel:WORD_1 src1_sel:DWORD
	v_add3_u32 v9, v11, v9, s48
	v_add3_u32 v10, v10, v12, s48
	v_and_b32_e32 v9, 0xffff0000, v9
	v_and_b32_e32 v10, 0xffff0000, v10
	v_lshl_add_u64 v[6:7], v[6:7], 0, v[166:167]
	v_or_b32_sdwa v9, v9, v1 dst_sel:DWORD dst_unused:UNUSED_PAD src0_sel:DWORD src1_sel:WORD_1
	v_or_b32_sdwa v8, v10, v8 dst_sel:DWORD dst_unused:UNUSED_PAD src0_sel:DWORD src1_sel:WORD_1
	global_store_dwordx2 v[6:7], v[8:9], off
	v_mov_b32_e32 v8, v2
	v_mov_b32_e32 v9, v4
	ds_read2_b64 v[30:33], v50 offset0:128 offset1:132
	v_pk_mul_f32 v[8:9], v[8:9], v[0:1] op_sel_hi:[1,0]
	v_mov_b32_e32 v4, v3
	v_pk_mul_f32 v[2:3], v[4:5], v[0:1] op_sel_hi:[1,0]
	v_and_b32_sdwa v4, v8, v177 dst_sel:DWORD dst_unused:UNUSED_PAD src0_sel:WORD_1 src1_sel:DWORD
	v_add3_u32 v4, v8, v4, s48
	v_and_b32_sdwa v5, v3, v177 dst_sel:DWORD dst_unused:UNUSED_PAD src0_sel:WORD_1 src1_sel:DWORD
	v_and_b32_sdwa v8, v2, v177 dst_sel:DWORD dst_unused:UNUSED_PAD src0_sel:WORD_1 src1_sel:DWORD
	v_and_b32_sdwa v1, v9, v177 dst_sel:DWORD dst_unused:UNUSED_PAD src0_sel:WORD_1 src1_sel:DWORD
	v_add3_u32 v3, v3, v5, s48
	v_add3_u32 v2, v2, v8, s48
	v_add3_u32 v1, v9, v1, s48
	v_and_b32_e32 v3, 0xffff0000, v3
	v_and_b32_e32 v2, 0xffff0000, v2
	v_or_b32_sdwa v3, v3, v1 dst_sel:DWORD dst_unused:UNUSED_PAD src0_sel:DWORD src1_sel:WORD_1
	v_or_b32_sdwa v2, v2, v4 dst_sel:DWORD dst_unused:UNUSED_PAD src0_sel:DWORD src1_sel:WORD_1
	global_store_dwordx2 v[6:7], v[2:3], off offset:32
	v_mov_b32_e32 v2, v26
	v_mov_b32_e32 v3, v28
	v_pk_mul_f32 v[2:3], v[2:3], v[0:1] op_sel_hi:[1,0]
	v_mov_b32_e32 v28, v27
	v_pk_mul_f32 v[4:5], v[28:29], v[0:1] op_sel_hi:[1,0]
	v_and_b32_sdwa v1, v3, v177 dst_sel:DWORD dst_unused:UNUSED_PAD src0_sel:WORD_1 src1_sel:DWORD
	v_and_b32_sdwa v8, v2, v177 dst_sel:DWORD dst_unused:UNUSED_PAD src0_sel:WORD_1 src1_sel:DWORD
	s_waitcnt lgkmcnt(0)
	v_mfma_f32_16x16x32_bf16 v[20:23], v[30:33], v[38:41], v[22:25]
	v_add3_u32 v2, v2, v8, s48
	v_add3_u32 v1, v3, v1, s48
	v_and_b32_sdwa v3, v5, v177 dst_sel:DWORD dst_unused:UNUSED_PAD src0_sel:WORD_1 src1_sel:DWORD
	v_and_b32_sdwa v8, v4, v177 dst_sel:DWORD dst_unused:UNUSED_PAD src0_sel:WORD_1 src1_sel:DWORD
	v_add3_u32 v3, v5, v3, s48
	v_add3_u32 v4, v4, v8, s48
	v_and_b32_e32 v3, 0xffff0000, v3
	v_and_b32_e32 v4, 0xffff0000, v4
	v_or_b32_sdwa v3, v3, v1 dst_sel:DWORD dst_unused:UNUSED_PAD src0_sel:DWORD src1_sel:WORD_1
	v_or_b32_sdwa v2, v4, v2 dst_sel:DWORD dst_unused:UNUSED_PAD src0_sel:DWORD src1_sel:WORD_1
	global_store_dwordx2 v[6:7], v[2:3], off offset:64
	v_mov_b32_e32 v2, v20
	v_mov_b32_e32 v3, v22
	v_pk_mul_f32 v[2:3], v[2:3], v[0:1] op_sel_hi:[1,0]
	v_mov_b32_e32 v22, v21
	v_pk_mul_f32 v[0:1], v[22:23], v[0:1] op_sel_hi:[1,0]
	v_and_b32_sdwa v4, v3, v177 dst_sel:DWORD dst_unused:UNUSED_PAD src0_sel:WORD_1 src1_sel:DWORD
	v_and_b32_sdwa v5, v2, v177 dst_sel:DWORD dst_unused:UNUSED_PAD src0_sel:WORD_1 src1_sel:DWORD
	v_add3_u32 v2, v2, v5, s48
	v_add3_u32 v3, v3, v4, s48
	v_and_b32_sdwa v4, v1, v177 dst_sel:DWORD dst_unused:UNUSED_PAD src0_sel:WORD_1 src1_sel:DWORD
	v_and_b32_sdwa v5, v0, v177 dst_sel:DWORD dst_unused:UNUSED_PAD src0_sel:WORD_1 src1_sel:DWORD
	v_add3_u32 v1, v1, v4, s48
	v_add3_u32 v0, v0, v5, s48
	v_readlane_b32 s2, v253, 8
	v_and_b32_e32 v1, 0xffff0000, v1
	v_and_b32_e32 v0, 0xffff0000, v0
	s_add_i32 s10, s10, s2
	v_or_b32_sdwa v1, v1, v3 dst_sel:DWORD dst_unused:UNUSED_PAD src0_sel:DWORD src1_sel:WORD_1
	v_or_b32_sdwa v0, v0, v2 dst_sel:DWORD dst_unused:UNUSED_PAD src0_sel:DWORD src1_sel:WORD_1
	s_cmpk_lt_i32 s11, 0x400
	global_store_dwordx2 v[6:7], v[0:1], off offset:96
	s_cbranch_scc0 .LBB0_1273

; template <int NKT, typename KofsF, typename BiasF> ...
;     ...
;     for (int j = 0; j < 4; ++j) s[kt][j] = acc[j] + bias(kt, g * 4 + j, fr);
;   }
;   float mx = -INFINITY;
; #pragma unroll
;   for (int kt = 0; kt < NKT; ++kt)
; #pragma unroll
;     for (int j = 0; j < 4; ++j) mx = fmaxf(mx, s[kt][j]);
;   mx = fmaxf(mx, bperm_xor(mx, lane, 16));
;   mx = fmaxf(mx, bperm_xor(mx, lane, 32));
;   if (has_sink) mx = fmaxf(mx, sinkv);
;   float l = 0.f;
; #pragma unroll
;   for (int kt = 0; kt < NKT; ++kt)
; #pragma unroll
;     for (int j = 0; j < 4; ++j) {
;       float pz = exp2f((s[kt][j] - mx) * 1.4426950408889634f);
;       l += pz;
;       s[kt][j] = pz;
;     }
.LBB0_1274:
	s_or_b64 exec, exec, s[2:3]
	s_waitcnt lgkmcnt(0)
	v_add_f32_e32 v4, v4, v8
	v_add_f32_e32 v8, v67, v89
	v_add_f32_e32 v67, v54, v132
	v_add_f32_e32 v82, v47, v125
	v_add_f32_e32 v54, v41, v119
	v_add_f32_e32 v47, v32, v110
	v_add_f32_e32 v32, v27, v105
	v_add_f32_e32 v41, v23, v101
	v_add_f32_e32 v23, v20, v98
	v_add_f32_e32 v27, v14, v85
	v_add_f32_e32 v14, v1, v74
	v_add_f32_e32 v20, v0, v75
	s_mov_b32 s2, 0xff800000
	v_add_f32_e32 v5, v5, v9
	v_add_f32_e32 v9, v66, v86
	v_add_f32_e32 v11, v64, v142
	v_add_f32_e32 v64, v52, v130
	v_add_f32_e32 v66, v50, v128
	v_add_f32_e32 v52, v45, v123
	v_add_f32_e32 v50, v42, v120
	v_add_f32_e32 v45, v38, v116
	v_add_f32_e32 v42, v34, v112
	v_add_f32_e32 v38, v29, v107
	v_add_f32_e32 v34, v25, v103
	v_add_f32_e32 v25, v19, v95
	v_add_f32_e32 v29, v13, v80
	v_add_f32_e32 v19, v3, v77
	v_add_f32_e32 v13, v2, v78
	v_max3_f32 v0, v20, s2, v14
	v_add_f32_e32 v12, v12, v81
	v_max3_f32 v0, v0, v13, v19
	v_add_f32_e32 v15, v15, v84
	v_max3_f32 v0, v0, v12, v29
	v_add_f32_e32 v17, v17, v88
	v_add_f32_e32 v16, v16, v87
	v_max3_f32 v0, v0, v27, v15
	v_add_f32_e32 v18, v18, v94
	v_max3_f32 v0, v0, v16, v17
	v_add_f32_e32 v21, v21, v99
	v_max3_f32 v0, v0, v18, v25
	v_add_f32_e32 v22, v22, v100
	v_max3_f32 v0, v0, v23, v21
	v_add_f32_e32 v24, v24, v102
	v_max3_f32 v0, v0, v22, v41
	v_add_f32_e32 v26, v26, v104
	v_max3_f32 v0, v0, v24, v34
	v_add_f32_e32 v28, v28, v106
	v_max3_f32 v0, v0, v26, v32
	v_and_b32_e32 v90, 63, v76
	v_add_f32_e32 v6, v6, v10
	v_add_f32_e32 v10, v65, v143
	v_add_f32_e32 v76, v49, v127
	v_add_f32_e32 v65, v39, v117
	v_add_f32_e32 v39, v36, v114
	v_add_f32_e32 v49, v31, v109
	v_add_f32_e32 v36, v30, v108
	v_max3_f32 v0, v0, v28, v38
	v_add_f32_e32 v33, v33, v111
	v_max3_f32 v0, v0, v36, v49
	v_add_f32_e32 v35, v35, v113
	v_max3_f32 v0, v0, v47, v33
	v_add_f32_e32 v37, v37, v115
	v_max3_f32 v0, v0, v42, v35
	v_max3_f32 v0, v0, v39, v37
	v_add_f32_e32 v40, v40, v118
	v_max3_f32 v0, v0, v45, v65
	v_add_f32_e32 v79, v48, v126
	v_add_f32_e32 v48, v43, v121
	v_max3_f32 v0, v0, v40, v54
	v_add_f32_e32 v44, v44, v122
	v_max3_f32 v0, v0, v50, v48
	v_add_f32_e32 v46, v46, v124
	v_max3_f32 v0, v0, v44, v52
	v_max3_f32 v0, v0, v46, v82
	v_add_f32_e32 v51, v51, v129
	v_max3_f32 v0, v0, v79, v76
	v_add_f32_e32 v53, v53, v131
	v_max3_f32 v0, v0, v66, v51
	v_add_f32_e32 v55, v55, v133
	v_max3_f32 v0, v0, v64, v53
	v_add_f32_e32 v57, v57, v135
	v_add_f32_e32 v56, v56, v134
	v_max3_f32 v0, v0, v67, v55
	v_add_f32_e32 v59, v59, v137
	v_add_f32_e32 v58, v58, v136
	v_max3_f32 v0, v0, v56, v57
	v_add_f32_e32 v61, v61, v139
	v_add_f32_e32 v60, v60, v138
	v_max3_f32 v0, v0, v58, v59
	v_add_f32_e32 v63, v63, v141
	v_add_f32_e32 v62, v62, v140
	v_max3_f32 v0, v0, v60, v61
	v_max3_f32 v0, v0, v62, v63
	v_max3_f32 v0, v0, v11, v10
	v_max3_f32 v0, v0, v9, v8
	v_add_f32_e32 v2, v7, v83
	v_max3_f32 v0, v0, v4, v5
	v_lshlrev_b32_e32 v3, 2, v90
	v_max3_f32 v0, v0, v6, v2
	v_xor_b32_e32 v1, 64, v3
	ds_bpermute_b32 v7, v1, v0
	v_readlane_b32 s2, v253, 20
	s_add_i32 s28, s28, s39
	s_cmpk_gt_i32 s28, 0x3ff
	s_waitcnt lgkmcnt(0)
	v_max_f32_e32 v7, v7, v7
	v_max_f32_e32 v7, v0, v7
	v_xor_b32_e32 v0, 0x80, v3
	ds_bpermute_b32 v3, v0, v7
	s_waitcnt lgkmcnt(0)
	v_max_f32_e32 v3, v3, v3
	v_max_f32_e32 v3, v7, v3
	v_sub_f32_e32 v7, v20, v3
	v_mul_f32_e32 v20, 0x3fb8aa3b, v7
	v_sub_f32_e32 v14, v14, v3
	v_sub_f32_e32 v13, v13, v3
	v_exp_f32_e32 v7, v20
	v_mul_f32_e32 v30, 0x3fb8aa3b, v13
	v_sub_f32_e32 v19, v19, v3
	v_mul_f32_e32 v20, 0x3fb8aa3b, v14
	v_sub_f32_e32 v12, v12, v3
	v_mul_f32_e32 v31, 0x3fb8aa3b, v12
	v_exp_f32_e32 v14, v20
	v_sub_f32_e32 v29, v29, v3
	v_sub_f32_e32 v27, v27, v3
	v_exp_f32_e32 v30, v30
	v_mov_b32_e32 v13, v14
	v_add_f32_e32 v20, v7, v13
	v_mov_b32_e32 v14, v30
	v_mul_f32_e32 v30, 0x3fb8aa3b, v19
	v_add_f32_e32 v20, v14, v20
	v_sub_f32_e32 v15, v15, v3
	v_exp_f32_e32 v19, v30
	v_sub_f32_e32 v16, v16, v3
	v_exp_f32_e32 v12, v31
	v_add_f32_e32 v30, v19, v20
	v_mul_f32_e32 v31, 0x3fb8aa3b, v27
	v_mov_b32_e32 v20, v12
	v_add_f32_e32 v12, v20, v30
	v_mul_f32_e32 v30, 0x3fb8aa3b, v29
	v_sub_f32_e32 v18, v18, v3
	v_sub_f32_e32 v23, v23, v3
	v_exp_f32_e32 v29, v30
	v_sub_f32_e32 v22, v22, v3
	v_mov_b32_e32 v30, v29
	v_exp_f32_e32 v27, v31
	v_add_f32_e32 v12, v30, v12
	v_sub_f32_e32 v28, v28, v3
	v_mov_b32_e32 v31, v27
	v_mul_f32_e32 v27, 0x3fb8aa3b, v15
	v_mul_f32_e32 v29, 0x3fb8aa3b, v16
	v_add_f32_e32 v12, v31, v12
	v_exp_f32_e32 v15, v27
	v_sub_f32_e32 v39, v39, v3
	v_mov_b32_e32 v43, v15
	v_exp_f32_e32 v16, v29
	v_add_f32_e32 v15, v43, v12
	v_mul_f32_e32 v27, 0x3fb8aa3b, v18
	v_mov_b32_e32 v12, v16
	v_sub_f32_e32 v16, v17, v3
	v_mul_f32_e32 v17, 0x3fb8aa3b, v16
	v_add_f32_e32 v15, v12, v15
	v_sub_f32_e32 v44, v44, v3
	v_exp_f32_e32 v16, v17
	v_sub_f32_e32 v46, v46, v3
	v_exp_f32_e32 v18, v27
	v_mul_f32_e32 v27, 0x3fb8aa3b, v23
	v_add_f32_e32 v15, v16, v15
	v_mov_b32_e32 v17, v18
	v_sub_f32_e32 v18, v25, v3
	v_mul_f32_e32 v25, 0x3fb8aa3b, v18
	v_add_f32_e32 v15, v17, v15
	v_sub_f32_e32 v66, v66, v3
	v_exp_f32_e32 v18, v25
	v_sub_f32_e32 v51, v51, v3
	v_sub_f32_e32 v64, v64, v3
	v_exp_f32_e32 v27, v27
	v_mov_b32_e32 v23, v18
	v_add_f32_e32 v15, v23, v15
	v_mov_b32_e32 v25, v27
	v_sub_f32_e32 v18, v21, v3
	v_mul_f32_e32 v21, 0x3fb8aa3b, v18
	v_mul_f32_e32 v27, 0x3fb8aa3b, v22
	v_add_f32_e32 v15, v25, v15
	v_exp_f32_e32 v18, v21
	v_sub_f32_e32 v67, v67, v3
	v_sub_f32_e32 v11, v11, v3
	v_exp_f32_e32 v22, v27
	v_mov_b32_e32 v27, v18
	v_add_f32_e32 v15, v27, v15
	v_mov_b32_e32 v29, v22
	v_sub_f32_e32 v18, v41, v3
	v_mul_f32_e32 v21, 0x3fb8aa3b, v18
	v_sub_f32_e32 v22, v24, v3
	v_mul_f32_e32 v24, 0x3fb8aa3b, v22
; template <int NKT, typename KofsF, typename BiasF> ...
;     ...
;   float l = 0.f;
; #pragma unroll
;   for (int kt = 0; kt < NKT; ++kt)
; #pragma unroll
;     for (int j = 0; j < 4; ++j) {
;       float pz = exp2f((s[kt][j] - mx) * 1.4426950408889634f);
;       l += pz;
;       s[kt][j] = pz;
;     }
;   l += bperm_xor(l, lane, 16);
;   l += bperm_xor(l, lane, 32);
;   if (has_sink) l += exp2f((sinkv - mx) * 1.4426950408889634f);
; #pragma unroll
;   for (int dt = 0; dt < 4; ++dt) oacc[dt] = f32x4{0.f, 0.f, 0.f, 0.f};
; #pragma unroll
;   for (int u = 0; u < NKT / 2; ++u) {
;     bf16x8 bp;
; #pragma unroll
;     for (int i = 0; i < 4; ++i) {
;       bp[i] = (short)f2bf(s[2 * u][i]);
;       bp[4 + i] = (short)f2bf(s[2 * u + 1][i]);
;     }
;     int k0 = kofs(2 * u) + g * 4, k1 = kofs(2 * u + 1) + g * 4;
; #pragma unroll
;     for (int dt = 0; dt < 4; ++dt) {
;       const u16* vrow = Vt + (dt * 16 + fr) * NKP;
;       uint2 v0 = *(const uint2*)(vrow + k0);
;       uint2 v1 = *(const uint2*)(vrow + k1);
;       union { uint4 q; bf16x8 v; } cv;
;       cv.q = make_uint4(v0.x, v0.y, v1.x, v1.y);
;       oacc[dt] = __builtin_amdgcn_mfma_f32_16x16x32_bf16(cv.v, bp, oacc[dt], 0, 0, 0);
;     }
	v_exp_f32_e32 v18, v21
	v_add_f32_e32 v15, v29, v15
	v_mov_b32_e32 v41, v18
	v_exp_f32_e32 v22, v24
	v_add_f32_e32 v18, v41, v15
	v_sub_f32_e32 v21, v34, v3
	v_mov_b32_e32 v15, v22
	v_mul_f32_e32 v22, 0x3fb8aa3b, v21
	v_sub_f32_e32 v24, v26, v3
	v_mul_f32_e32 v26, 0x3fb8aa3b, v24
	v_exp_f32_e32 v21, v22
	v_add_f32_e32 v18, v15, v18
	v_exp_f32_e32 v24, v26
	v_add_f32_e32 v18, v21, v18
	v_sub_f32_e32 v90, v10, v3
	v_mov_b32_e32 v22, v24
	v_sub_f32_e32 v24, v32, v3
	v_mul_f32_e32 v26, 0x3fb8aa3b, v24
	v_mul_f32_e32 v32, 0x3fb8aa3b, v28
	v_add_f32_e32 v18, v22, v18
	v_exp_f32_e32 v24, v26
	v_mul_f32_e32 v10, 0x3fb8aa3b, v90
	v_bfe_u32 v78, v14, 16, 1
	v_exp_f32_e32 v28, v32
	v_mov_b32_e32 v32, v24
	v_add_f32_e32 v18, v32, v18
	v_mov_b32_e32 v34, v28
	v_sub_f32_e32 v24, v38, v3
	v_mul_f32_e32 v26, 0x3fb8aa3b, v24
	v_sub_f32_e32 v28, v36, v3
	v_mul_f32_e32 v36, 0x3fb8aa3b, v28
	v_exp_f32_e32 v24, v26
	v_add_f32_e32 v18, v34, v18
	v_bfe_u32 v80, v7, 16, 1
	v_exp_f32_e32 v28, v36
	v_mov_b32_e32 v36, v24
	v_add_f32_e32 v18, v36, v18
	v_mov_b32_e32 v38, v28
	v_sub_f32_e32 v24, v49, v3
	v_mul_f32_e32 v26, 0x3fb8aa3b, v24
	v_sub_f32_e32 v28, v47, v3
	v_mul_f32_e32 v47, 0x3fb8aa3b, v28
	v_exp_f32_e32 v24, v26
	v_add_f32_e32 v18, v38, v18
	v_mov_b32_e32 v49, v24
	v_exp_f32_e32 v28, v47
	v_add_f32_e32 v24, v49, v18
	v_sub_f32_e32 v26, v33, v3
	v_mov_b32_e32 v18, v28
	v_mul_f32_e32 v28, 0x3fb8aa3b, v26
	v_sub_f32_e32 v33, v42, v3
	v_mul_f32_e32 v42, 0x3fb8aa3b, v33
	v_exp_f32_e32 v26, v28
	v_add_f32_e32 v24, v18, v24
	v_exp_f32_e32 v33, v42
	v_mul_f32_e32 v42, 0x3fb8aa3b, v39
	v_add_f32_e32 v24, v26, v24
	v_mov_b32_e32 v28, v33
	v_sub_f32_e32 v33, v35, v3
	v_mul_f32_e32 v35, 0x3fb8aa3b, v33
	v_add_f32_e32 v24, v28, v24
	v_add3_u32 v78, v14, v78, s48
	v_exp_f32_e32 v33, v35
	v_lshlrev_b32_e32 v14, 7, v71
	v_add3_u32 v7, v7, v80, s48
	v_exp_f32_e32 v42, v42
	v_mov_b32_e32 v39, v33
	v_add_f32_e32 v24, v39, v24
	v_sub_f32_e32 v33, v37, v3
	v_mul_f32_e32 v35, 0x3fb8aa3b, v33
	v_sub_f32_e32 v37, v45, v3
	v_mul_f32_e32 v45, 0x3fb8aa3b, v37
	v_exp_f32_e32 v33, v35
	v_add_f32_e32 v24, v42, v24
	v_sub_f32_e32 v9, v9, v3
	v_exp_f32_e32 v37, v45
	v_mov_b32_e32 v45, v33
	v_add_f32_e32 v24, v45, v24
	v_mov_b32_e32 v47, v37
	v_sub_f32_e32 v33, v65, v3
	v_mul_f32_e32 v35, 0x3fb8aa3b, v33
	v_sub_f32_e32 v37, v40, v3
	v_mul_f32_e32 v40, 0x3fb8aa3b, v37
	v_exp_f32_e32 v33, v35
	v_add_f32_e32 v24, v47, v24
	v_mov_b32_e32 v65, v33
	v_exp_f32_e32 v37, v40
	v_add_f32_e32 v33, v65, v24
	v_sub_f32_e32 v35, v54, v3
	v_mov_b32_e32 v24, v37
	v_mul_f32_e32 v37, 0x3fb8aa3b, v35
	v_sub_f32_e32 v40, v50, v3
	v_mul_f32_e32 v50, 0x3fb8aa3b, v40
	v_exp_f32_e32 v35, v37
	v_add_f32_e32 v33, v24, v33
	v_exp_f32_e32 v40, v50
	v_mul_f32_e32 v50, 0x3fb8aa3b, v44
	v_add_f32_e32 v33, v35, v33
	v_mov_b32_e32 v37, v40
	v_sub_f32_e32 v40, v48, v3
	v_mul_f32_e32 v48, 0x3fb8aa3b, v40
	v_add_f32_e32 v33, v37, v33
	v_bfe_u32 v71, v25, 16, 1
	v_exp_f32_e32 v40, v48
	v_add3_u32 v25, v25, v71, s48
	v_mov_b32_e32 v48, v40
	v_exp_f32_e32 v44, v50
	v_add_f32_e32 v33, v48, v33
	v_sub_f32_e32 v8, v8, v3
	v_mov_b32_e32 v50, v44
	v_sub_f32_e32 v40, v52, v3
	v_mul_f32_e32 v44, 0x3fb8aa3b, v40
	v_mul_f32_e32 v52, 0x3fb8aa3b, v46
	v_add_f32_e32 v33, v50, v33
	v_exp_f32_e32 v40, v44
	v_sub_f32_e32 v4, v4, v3
	s_nop 0
	v_exp_f32_e32 v46, v52
	v_mov_b32_e32 v52, v40
	v_add_f32_e32 v33, v52, v33
	v_mov_b32_e32 v54, v46
	v_sub_f32_e32 v40, v82, v3
	v_mul_f32_e32 v44, 0x3fb8aa3b, v40
	v_sub_f32_e32 v46, v79, v3
	v_mul_f32_e32 v74, 0x3fb8aa3b, v46
	v_exp_f32_e32 v40, v44
	v_add_f32_e32 v33, v54, v33
	v_mov_b32_e32 v75, v40
	v_exp_f32_e32 v46, v74
	v_add_f32_e32 v40, v75, v33
	v_sub_f32_e32 v44, v76, v3
	v_mov_b32_e32 v33, v46
	v_mul_f32_e32 v46, 0x3fb8aa3b, v44
	v_mul_f32_e32 v74, 0x3fb8aa3b, v66
	v_add_f32_e32 v40, v33, v40
	v_exp_f32_e32 v44, v46
	v_bfe_u32 v79, v13, 16, 1
	v_exp_f32_e32 v66, v74
	v_mul_f32_e32 v74, 0x3fb8aa3b, v64
	v_add_f32_e32 v40, v44, v40
	v_mov_b32_e32 v46, v66
	v_mul_f32_e32 v66, 0x3fb8aa3b, v51
	v_add_f32_e32 v40, v46, v40
	v_add3_u32 v86, v13, v79, s48
	v_exp_f32_e32 v51, v66
	s_nop 1
	v_exp_f32_e32 v74, v74
	v_mov_b32_e32 v64, v51
	v_add_f32_e32 v40, v64, v40
	v_mov_b32_e32 v66, v74
	v_sub_f32_e32 v51, v53, v3
	v_mul_f32_e32 v53, 0x3fb8aa3b, v51
	v_mul_f32_e32 v74, 0x3fb8aa3b, v67
	v_add_f32_e32 v40, v66, v40
	v_exp_f32_e32 v51, v53
	s_nop 1
	v_exp_f32_e32 v74, v74
	v_mov_b32_e32 v67, v51
	v_add_f32_e32 v40, v67, v40
	v_sub_f32_e32 v51, v55, v3
	v_mul_f32_e32 v53, 0x3fb8aa3b, v51
	v_sub_f32_e32 v55, v56, v3
	v_mul_f32_e32 v56, 0x3fb8aa3b, v55
	v_exp_f32_e32 v51, v53
	v_add_f32_e32 v40, v74, v40
	v_mov_b32_e32 v76, v51
	v_exp_f32_e32 v55, v56
	v_add_f32_e32 v51, v76, v40
	v_sub_f32_e32 v56, v58, v3
	v_mov_b32_e32 v40, v55
	v_add_f32_e32 v53, v40, v51
	v_sub_f32_e32 v51, v57, v3
	v_mul_f32_e32 v55, 0x3fb8aa3b, v51
	v_mul_f32_e32 v57, 0x3fb8aa3b, v56
	v_sub_f32_e32 v58, v60, v3
	v_exp_f32_e32 v51, v55
	v_sub_f32_e32 v60, v62, v3
	v_exp_f32_e32 v56, v57
	v_add_f32_e32 v55, v51, v53
	v_mul_f32_e32 v62, 0x3fb8aa3b, v11
	v_mov_b32_e32 v53, v56
	v_add_f32_e32 v56, v53, v55
	v_sub_f32_e32 v55, v59, v3
	v_mul_f32_e32 v57, 0x3fb8aa3b, v55
	v_mul_f32_e32 v59, 0x3fb8aa3b, v58
	s_nop 0
	v_exp_f32_e32 v55, v57
	s_nop 0
	v_exp_f32_e32 v58, v59
	v_add_f32_e32 v57, v55, v56
	v_mov_b32_e32 v56, v58
	v_add_f32_e32 v58, v56, v57
	v_sub_f32_e32 v57, v61, v3
	v_mul_f32_e32 v59, 0x3fb8aa3b, v57
	v_mul_f32_e32 v61, 0x3fb8aa3b, v60
	s_nop 0
	v_exp_f32_e32 v57, v59
	s_nop 0
	v_exp_f32_e32 v60, v61
	v_add_f32_e32 v59, v57, v58
	v_mov_b32_e32 v58, v60
	v_add_f32_e32 v60, v58, v59
	v_sub_f32_e32 v59, v63, v3
	v_mul_f32_e32 v61, 0x3fb8aa3b, v59
	v_bfe_u32 v63, v20, 16, 1
	v_add3_u32 v13, v20, v63, s48
	v_exp_f32_e32 v59, v61
	v_cmp_gt_f32_e32 vcc, s46, v62
	s_nop 0
	s_nop 0
	v_cndmask_b32_e32 v62, 0, v180, vcc
	v_fmac_f32_e32 v62, 0x3fb8aa3b, v11
	v_exp_f32_e32 v11, v62
	v_add_f32_e32 v77, v59, v60
	v_cndmask_b32_e32 v60, 0, v178, vcc
	v_bfe_u32 v61, v31, 16, 1
	v_ldexp_f32 v11, v11, v60
	v_bfe_u32 v60, v43, 16, 1
	v_bfe_u32 v62, v30, 16, 1
	v_cmp_gt_f32_e32 vcc, s46, v10
	v_mul_u32_u24_e32 v10, 0x490, v73
	v_add3_u32 v20, v30, v62, s48
	v_add3_u32 v30, v31, v61, s48
	v_add3_u32 v31, v43, v60, s48
	v_lshlrev_b32_e32 v43, 1, v69
	v_bfe_u32 v73, v19, 16, 1
	v_add3_u32 v10, s2, v10, v43
	v_lshlrev_b32_e32 v43, 1, v72
	v_add3_u32 v19, v19, v73, s48
	v_add3_u32 v14, v10, v14, v43
	v_cndmask_b32_e32 v94, 0, v180, vcc
	v_perm_b32 v80, v20, v13, s47
	v_add_u32_e32 v13, 0x4800, v14
	v_perm_b32 v79, v19, v78, s47
	v_perm_b32 v78, v86, v7, s47
	v_add_u32_e32 v10, 0x9000, v14
	v_add_u32_e32 v7, 0xd800, v14
	ds_read2_b64 v[60:63], v14 offset1:4
	ds_read2_b64 v[82:85], v13 offset0:32 offset1:36
	ds_read2_b64 v[86:89], v10 offset0:64 offset1:68
	v_fmac_f32_e32 v94, 0x3fb8aa3b, v90
	ds_read2_b64 v[90:93], v7 offset0:96 offset1:100
	v_perm_b32 v81, v31, v30, s47
	v_exp_f32_e32 v19, v94
	v_cndmask_b32_e32 v30, 0, v178, vcc
	s_waitcnt lgkmcnt(3)
; template <int NKT, typename KofsF, typename BiasF> ...
;     ...
;   for (int u = 0; u < NKT / 2; ++u) {
;     bf16x8 bp;
; #pragma unroll
;     for (int i = 0; i < 4; ++i) {
;       bp[i] = (short)f2bf(s[2 * u][i]);
;       bp[4 + i] = (short)f2bf(s[2 * u + 1][i]);
;     }
;     int k0 = kofs(2 * u) + g * 4, k1 = kofs(2 * u + 1) + g * 4;
; #pragma unroll
;     for (int dt = 0; dt < 4; ++dt) {
;       const u16* vrow = Vt + (dt * 16 + fr) * NKP;
;       uint2 v0 = *(const uint2*)(vrow + k0);
;       uint2 v1 = *(const uint2*)(vrow + k1);
;       union { uint4 q; bf16x8 v; } cv;
;       cv.q = make_uint4(v0.x, v0.y, v1.x, v1.y);
;       oacc[dt] = __builtin_amdgcn_mfma_f32_16x16x32_bf16(cv.v, bp, oacc[dt], 0, 0, 0);
;     }
	v_mfma_f32_16x16x32_bf16 v[60:63], v[60:63], v[78:81], 0
	v_add_f32_e32 v20, v11, v77
	v_ldexp_f32 v69, v19, v30
	v_mul_f32_e32 v19, 0x3fb8aa3b, v9
	s_waitcnt lgkmcnt(2)
	v_mfma_f32_16x16x32_bf16 v[82:85], v[82:85], v[78:81], 0
	v_bfe_u32 v30, v41, 16, 1
	v_bfe_u32 v31, v29, 16, 1
	v_bfe_u32 v43, v27, 16, 1
	s_waitcnt lgkmcnt(1)
	v_mfma_f32_16x16x32_bf16 v[86:89], v[86:89], v[78:81], 0
	v_bfe_u32 v72, v23, 16, 1
	v_bfe_u32 v73, v17, 16, 1
	v_bfe_u32 v77, v16, 16, 1
	s_waitcnt lgkmcnt(0)
	v_mfma_f32_16x16x32_bf16 v[78:81], v[90:93], v[78:81], 0
	v_bfe_u32 v90, v12, 16, 1
	v_add3_u32 v12, v12, v90, s48
	ds_read2_b64 v[90:93], v14 offset0:16 offset1:20
	v_add3_u32 v16, v16, v77, s48
	v_add3_u32 v17, v17, v73, s48
	v_add3_u32 v23, v23, v72, s48
	v_add3_u32 v27, v27, v43, s48
	v_add3_u32 v29, v29, v31, s48
	v_add3_u32 v30, v41, v30, s48
	v_cmp_gt_f32_e32 vcc, s46, v19
	v_perm_b32 v97, v30, v29, s47
	v_perm_b32 v96, v27, v25, s47
	v_perm_b32 v95, v23, v17, s47
	v_perm_b32 v94, v16, v12, s47
	v_cndmask_b32_e32 v12, 0, v180, vcc
	v_fmac_f32_e32 v12, 0x3fb8aa3b, v9
	s_waitcnt lgkmcnt(0)
	v_mfma_f32_16x16x32_bf16 v[60:63], v[90:93], v[94:97], v[60:63]
	ds_read2_b64 v[90:93], v10 offset0:80 offset1:84
	v_exp_f32_e32 v9, v12
	v_add_f32_e32 v12, v69, v20
	v_bfe_u32 v20, v34, 16, 1
	v_bfe_u32 v23, v32, 16, 1
	v_bfe_u32 v27, v22, 16, 1
	v_bfe_u32 v29, v21, 16, 1
	v_bfe_u32 v30, v15, 16, 1
	v_add3_u32 v15, v15, v30, s48
	v_add3_u32 v29, v21, v29, s48
	v_add3_u32 v27, v22, v27, s48
	v_add3_u32 v30, v32, v23, s48
	v_add3_u32 v31, v34, v20, s48
	ds_read2_b64 v[20:23], v14 offset0:32 offset1:36
	ds_read2_b64 v[98:101], v13 offset0:48 offset1:52
	ds_read2_b64 v[102:105], v7 offset0:112 offset1:116
	v_cndmask_b32_e32 v16, 0, v178, vcc
	v_bfe_u32 v17, v49, 16, 1
	v_bfe_u32 v19, v38, 16, 1
	v_bfe_u32 v25, v36, 16, 1
	v_ldexp_f32 v9, v9, v16
	v_mul_f32_e32 v16, 0x3fb8aa3b, v8
	v_add3_u32 v25, v36, v25, s48
	v_add3_u32 v19, v38, v19, s48
	v_add3_u32 v17, v49, v17, s48
	s_waitcnt lgkmcnt(3)
	v_mfma_f32_16x16x32_bf16 v[86:89], v[90:93], v[94:97], v[86:89]
	v_perm_b32 v93, v17, v19, s47
	v_perm_b32 v92, v25, v31, s47
	v_perm_b32 v91, v30, v27, s47
	v_cmp_gt_f32_e32 vcc, s46, v16
	v_bfe_u32 v16, v42, 16, 1
	v_bfe_u32 v17, v39, 16, 1
	v_bfe_u32 v19, v28, 16, 1
	v_bfe_u32 v30, v26, 16, 1
	v_bfe_u32 v31, v18, 16, 1
	v_perm_b32 v90, v29, v15, s47
	v_add3_u32 v31, v18, v31, s48
	v_add3_u32 v26, v26, v30, s48
	v_add3_u32 v30, v28, v19, s48
	v_add3_u32 v32, v39, v17, s48
	v_add3_u32 v28, v42, v16, s48
	ds_read2_b64 v[16:19], v14 offset0:48 offset1:52
	s_waitcnt lgkmcnt(3)
	v_mfma_f32_16x16x32_bf16 v[20:23], v[20:23], v[90:93], v[60:63]
	v_bfe_u32 v25, v65, 16, 1
	v_bfe_u32 v27, v47, 16, 1
	v_bfe_u32 v29, v45, 16, 1
	ds_read2_b64 v[60:63], v10 offset0:96 offset1:100
	s_waitcnt lgkmcnt(3)
	v_mfma_f32_16x16x32_bf16 v[82:85], v[98:101], v[94:97], v[82:85]
	ds_read2_b64 v[98:101], v7 offset0:128 offset1:132
	v_add3_u32 v34, v45, v29, s48
	v_add3_u32 v27, v47, v27, s48
	s_waitcnt lgkmcnt(3)
	v_mfma_f32_16x16x32_bf16 v[78:81], v[102:105], v[94:97], v[78:81]
	ds_read2_b64 v[94:97], v13 offset0:64 offset1:68
	v_add3_u32 v25, v65, v25, s48
	v_perm_b32 v29, v25, v27, s47
	v_perm_b32 v28, v34, v28, s47
	v_perm_b32 v27, v32, v30, s47
	v_perm_b32 v26, v26, v31, s47
	v_bfe_u32 v34, v48, 16, 1
	v_bfe_u32 v36, v37, 16, 1
	s_waitcnt lgkmcnt(3)
	v_mfma_f32_16x16x32_bf16 v[16:19], v[16:19], v[26:29], v[20:23]
	v_bfe_u32 v38, v35, 16, 1
	v_bfe_u32 v39, v24, 16, 1
	v_add3_u32 v24, v24, v39, s48
	ds_read2_b64 v[20:23], v10 offset0:112 offset1:116
	s_waitcnt lgkmcnt(3)
	v_mfma_f32_16x16x32_bf16 v[60:63], v[60:63], v[90:93], v[86:89]
	v_add3_u32 v38, v35, v38, s48
	v_add3_u32 v39, v37, v36, s48
	v_add3_u32 v41, v48, v34, s48
	ds_read2_b64 v[86:89], v13 offset0:80 offset1:84
	ds_read2_b64 v[34:37], v14 offset0:64 offset1:68
	v_cndmask_b32_e32 v15, 0, v180, vcc
	v_fmac_f32_e32 v15, 0x3fb8aa3b, v8
	s_waitcnt lgkmcnt(3)
	v_mfma_f32_16x16x32_bf16 v[82:85], v[94:97], v[90:93], v[82:85]
	v_exp_f32_e32 v8, v15
	v_bfe_u32 v25, v75, 16, 1
	v_bfe_u32 v30, v54, 16, 1
	v_mfma_f32_16x16x32_bf16 v[78:81], v[98:101], v[90:93], v[78:81]
	ds_read2_b64 v[90:93], v7 offset0:144 offset1:148
	v_bfe_u32 v31, v52, 16, 1
	v_bfe_u32 v32, v50, 16, 1
	v_add3_u32 v32, v50, v32, s48
	v_add3_u32 v31, v52, v31, s48
	v_add3_u32 v30, v54, v30, s48
	v_add3_u32 v25, v75, v25, s48
	s_waitcnt lgkmcnt(3)
	v_mfma_f32_16x16x32_bf16 v[20:23], v[20:23], v[26:29], v[60:63]
	v_cndmask_b32_e32 v15, 0, v178, vcc
	v_ldexp_f32 v8, v8, v15
	v_mul_f32_e32 v15, 0x3fb8aa3b, v4
	v_perm_b32 v63, v25, v30, s47
	v_perm_b32 v62, v31, v32, s47
	v_perm_b32 v61, v41, v39, s47
	v_perm_b32 v60, v38, v24, s47
	s_waitcnt lgkmcnt(2)
	v_mfma_f32_16x16x32_bf16 v[82:85], v[86:89], v[26:29], v[82:85]
	ds_read2_b64 v[86:89], v7 offset0:160 offset1:164
	v_cmp_gt_f32_e32 vcc, s46, v15
	v_bfe_u32 v30, v46, 16, 1
	s_waitcnt lgkmcnt(2)
	v_mfma_f32_16x16x32_bf16 v[16:19], v[34:37], v[60:63], v[16:19]
	ds_read2_b64 v[34:37], v10 offset0:128 offset1:132
	v_cndmask_b32_e32 v15, 0, v180, vcc
	v_fmac_f32_e32 v15, 0x3fb8aa3b, v4
	v_exp_f32_e32 v4, v15
	s_waitcnt lgkmcnt(2)
	v_mfma_f32_16x16x32_bf16 v[26:29], v[90:93], v[26:29], v[78:81]
	v_cndmask_b32_e32 v15, 0, v178, vcc
	v_bfe_u32 v31, v44, 16, 1
	v_ldexp_f32 v15, v4, v15
	v_sub_f32_e32 v4, v5, v3
	s_waitcnt lgkmcnt(0)
; template <int NKT, typename KofsF, typename BiasF> ...
;     ...
;   l += bperm_xor(l, lane, 16);
;   l += bperm_xor(l, lane, 32);
;   if (has_sink) l += exp2f((sinkv - mx) * 1.4426950408889634f);
; #pragma unroll
;   for (int dt = 0; dt < 4; ++dt) oacc[dt] = f32x4{0.f, 0.f, 0.f, 0.f};
; #pragma unroll
;   for (int u = 0; u < NKT / 2; ++u) {
;     bf16x8 bp;
; #pragma unroll
;     for (int i = 0; i < 4; ++i) {
;       bp[i] = (short)f2bf(s[2 * u][i]);
;       bp[4 + i] = (short)f2bf(s[2 * u + 1][i]);
;     }
;     int k0 = kofs(2 * u) + g * 4, k1 = kofs(2 * u + 1) + g * 4;
; #pragma unroll
;     for (int dt = 0; dt < 4; ++dt) {
;       const u16* vrow = Vt + (dt * 16 + fr) * NKP;
;       uint2 v0 = *(const uint2*)(vrow + k0);
;       uint2 v1 = *(const uint2*)(vrow + k1);
;       union { uint4 q; bf16x8 v; } cv;
;       cv.q = make_uint4(v0.x, v0.y, v1.x, v1.y);
;       oacc[dt] = __builtin_amdgcn_mfma_f32_16x16x32_bf16(cv.v, bp, oacc[dt], 0, 0, 0);
;     }
	v_mfma_f32_16x16x32_bf16 v[20:23], v[34:37], v[60:63], v[20:23]
	v_bfe_u32 v36, v33, 16, 1
	v_mul_f32_e32 v5, 0x3fb8aa3b, v4
	v_add3_u32 v41, v33, v36, s48
	v_mfma_f32_16x16x32_bf16 v[24:27], v[86:89], v[60:63], v[26:29]
	v_add3_u32 v42, v44, v31, s48
	v_add3_u32 v33, v46, v30, s48
	v_cmp_gt_f32_e32 vcc, s46, v5
	v_bfe_u32 v28, v66, 16, 1
	v_bfe_u32 v29, v64, 16, 1
	v_add3_u32 v43, v64, v29, s48
	v_add3_u32 v36, v66, v28, s48
	ds_read2_b64 v[28:31], v14 offset0:80 offset1:84
	v_cndmask_b32_e32 v5, 0, v180, vcc
	v_fmac_f32_e32 v5, 0x3fb8aa3b, v4
	v_exp_f32_e32 v4, v5
	v_add_f32_e32 v12, v9, v12
	ds_read2_b64 v[78:81], v13 offset0:96 offset1:100
	v_add_f32_e32 v12, v8, v12
	v_bfe_u32 v32, v76, 16, 1
	v_bfe_u32 v34, v74, 16, 1
	v_bfe_u32 v35, v67, 16, 1
	v_add_f32_e32 v5, v15, v12
	v_cndmask_b32_e32 v12, 0, v178, vcc
	v_add3_u32 v37, v67, v35, s48
	v_add3_u32 v34, v74, v34, s48
	v_add3_u32 v32, v76, v32, s48
	v_ldexp_f32 v12, v4, v12
	v_sub_f32_e32 v4, v6, v3
	v_perm_b32 v35, v32, v34, s47
	v_perm_b32 v34, v37, v36, s47
	v_perm_b32 v33, v43, v33, s47
	v_perm_b32 v32, v42, v41, s47
	ds_read2_b64 v[42:45], v7 offset0:176 offset1:180
	v_mul_f32_e32 v6, 0x3fb8aa3b, v4
	ds_read2_b64 v[36:39], v13 offset0:112 offset1:116
	s_waitcnt lgkmcnt(3)
	v_mfma_f32_16x16x32_bf16 v[16:19], v[28:31], v[32:35], v[16:19]
	ds_read2_b64 v[28:31], v10 offset0:144 offset1:148
	v_cmp_gt_f32_e32 vcc, s46, v6
	v_sub_f32_e32 v41, v2, v3
	s_waitcnt lgkmcnt(3)
	v_mfma_f32_16x16x32_bf16 v[78:81], v[78:81], v[60:63], v[82:85]
	v_cndmask_b32_e32 v6, 0, v180, vcc
	v_fmac_f32_e32 v6, 0x3fb8aa3b, v4
	v_exp_f32_e32 v4, v6
	v_add_f32_e32 v6, v12, v5
	v_cndmask_b32_e32 v5, 0, v178, vcc
	s_waitcnt lgkmcnt(1)
	v_mfma_f32_16x16x32_bf16 v[36:39], v[36:39], v[32:35], v[78:81]
	v_ldexp_f32 v46, v4, v5
	v_mul_f32_e32 v47, 0x3fb8aa3b, v41
	v_cmp_gt_f32_e32 vcc, s46, v47
	v_mfma_f32_16x16x32_bf16 v[2:5], v[42:45], v[32:35], v[24:27]
	v_add_f32_e32 v6, v46, v6
	s_nop 1
	v_bfe_u32 v24, v56, 16, 1
	v_bfe_u32 v25, v55, 16, 1
	v_bfe_u32 v26, v53, 16, 1
	v_bfe_u32 v27, v51, 16, 1
	s_waitcnt lgkmcnt(0)
	v_mfma_f32_16x16x32_bf16 v[20:23], v[28:31], v[32:35], v[20:23]
	v_add3_u32 v42, v51, v27, s48
	v_add3_u32 v43, v53, v26, s48
	v_add3_u32 v44, v55, v25, s48
	v_add3_u32 v32, v56, v24, s48
	ds_read2_b64 v[24:27], v14 offset0:96 offset1:100
	v_bfe_u32 v30, v57, 16, 1
	v_add3_u32 v30, v57, v30, s48
	v_perm_b32 v30, v30, v32, s47
	ds_read2_b64 v[32:35], v13 offset0:128 offset1:132
	v_bfe_u32 v28, v59, 16, 1
	v_bfe_u32 v29, v58, 16, 1
	v_bfe_u32 v31, v40, 16, 1
	v_add3_u32 v40, v40, v31, s48
	v_add3_u32 v29, v58, v29, s48
	v_add3_u32 v28, v59, v28, s48
	v_perm_b32 v31, v28, v29, s47
	v_perm_b32 v29, v44, v43, s47
	v_perm_b32 v28, v42, v40, s47
	v_cndmask_b32_e32 v44, 0, v180, vcc
	v_fmac_f32_e32 v44, 0x3fb8aa3b, v41
	s_waitcnt lgkmcnt(1)
	v_mfma_f32_16x16x32_bf16 v[16:19], v[24:27], v[28:31], v[16:19]
	ds_read2_b64 v[24:27], v10 offset0:160 offset1:164
	ds_read2_b64 v[40:43], v7 offset0:192 offset1:196
	s_waitcnt lgkmcnt(2)
	v_mfma_f32_16x16x32_bf16 v[32:35], v[32:35], v[28:31], v[36:39]
	s_nop 2
	v_exp_f32_e32 v36, v44
	v_cndmask_b32_e32 v37, 0, v178, vcc
	s_waitcnt lgkmcnt(1)
	v_mfma_f32_16x16x32_bf16 v[20:23], v[24:27], v[28:31], v[20:23]
	v_bfe_u32 v24, v15, 16, 1
	v_ldexp_f32 v36, v36, v37
	v_bfe_u32 v25, v8, 16, 1
	s_waitcnt lgkmcnt(0)
	v_mfma_f32_16x16x32_bf16 v[2:5], v[40:43], v[28:31], v[2:5]
	v_bfe_u32 v28, v36, 16, 1
	v_bfe_u32 v29, v46, 16, 1
	v_bfe_u32 v30, v12, 16, 1
	v_bfe_u32 v26, v9, 16, 1
	v_bfe_u32 v27, v69, 16, 1
	v_bfe_u32 v31, v11, 16, 1
	v_add_f32_e32 v6, v36, v6
	v_add3_u32 v11, v11, v31, s48
	v_add3_u32 v37, v69, v27, s48
	v_add3_u32 v9, v9, v26, s48
	v_add3_u32 v8, v8, v25, s48
	v_add3_u32 v38, v15, v24, s48
	ds_read2_b64 v[24:27], v14 offset0:112 offset1:116
	v_add3_u32 v12, v12, v30, s48
	v_add3_u32 v14, v46, v29, s48
	v_add3_u32 v15, v36, v28, s48
	ds_read2_b64 v[28:31], v13 offset0:144 offset1:148
	ds_bpermute_b32 v1, v1, v6
	v_perm_b32 v15, v15, v14, s47
	v_perm_b32 v14, v12, v38, s47
	v_perm_b32 v13, v8, v9, s47
	v_perm_b32 v12, v37, v11, s47
	ds_read2_b64 v[8:11], v10 offset0:176 offset1:180
	s_waitcnt lgkmcnt(1)
	v_add_f32_e32 v1, v6, v1
	ds_bpermute_b32 v0, v0, v1
	v_mfma_f32_16x16x32_bf16 v[16:19], v[24:27], v[12:15], v[16:19]
	v_ashrrev_i32_e32 v69, 31, v68
	v_mfma_f32_16x16x32_bf16 v[24:27], v[28:31], v[12:15], v[32:35]
	ds_read2_b64 v[28:31], v7 offset0:208 offset1:212
	s_waitcnt lgkmcnt(2)
	v_mfma_f32_16x16x32_bf16 v[6:9], v[8:11], v[12:15], v[20:23]
	s_waitcnt lgkmcnt(1)
	v_add_f32_e32 v10, v1, v0
	v_div_scale_f32 v11, s[2:3], v10, v10, 1.0
	v_rcp_f32_e32 v20, v11
	s_waitcnt lgkmcnt(0)
; __device__ __forceinline__ u32 pack2(float a, float b) { return (u32)f2bf(a) | ((u32)f2bf(b) << 16); }
; __device__ __forceinline__ void attnD_item(unsigned char* ws, int item, unsigned char* lds, int wv_) {
;     ...
;   float inv = 1.f / lb;
;   u16* op = O + (size_t)tq * D_ + 1024 + h * 64;
; #pragma unroll
;   for (int dt = 0; dt < 4; ++dt)
;     *(uint2*)(op + dt * 16 + g * 4) = make_uint2(pack2(oacc[dt][0] * inv, oacc[dt][1] * inv), pack2(oacc[dt][2] * inv, oacc[dt][3] * inv));
	v_mfma_f32_16x16x32_bf16 v[0:3], v[28:31], v[12:15], v[2:5]
	v_mov_b32_e32 v14, v16
	v_mov_b32_e32 v15, v18
	s_nop 0
	v_fma_f32 v4, -v11, v20, 1.0
	v_fmac_f32_e32 v20, v4, v20
	v_div_scale_f32 v4, vcc, 1.0, v10, 1.0
	v_mul_f32_e32 v5, v4, v20
	v_fma_f32 v12, -v11, v5, v4
	v_fmac_f32_e32 v5, v12, v20
	v_fma_f32 v4, -v11, v5, v4
	v_div_fmas_f32 v4, v4, v20, v5
	v_div_fixup_f32 v4, v4, v10, 1.0
	v_lshlrev_b64 v[10:11], 12, v[68:69]
	v_lshrrev_b32_e32 v5, 1, v70
	v_lshl_add_u64 v[10:11], s[78:79], 0, v[10:11]
	v_pk_mul_f32 v[14:15], v[14:15], v[4:5] op_sel_hi:[1,0]
	v_mov_b32_e32 v18, v17
	v_lshl_add_u64 v[10:11], v[10:11], 0, s[84:85]
	v_and_b32_e32 v166, 24, v5
	v_pk_mul_f32 v[16:17], v[18:19], v[4:5] op_sel_hi:[1,0]
	v_and_b32_sdwa v5, v15, v177 dst_sel:DWORD dst_unused:UNUSED_PAD src0_sel:WORD_1 src1_sel:DWORD
	v_and_b32_sdwa v18, v14, v177 dst_sel:DWORD dst_unused:UNUSED_PAD src0_sel:WORD_1 src1_sel:DWORD
	v_lshl_add_u64 v[10:11], v[10:11], 0, v[166:167]
	s_mov_b64 s[2:3], 0x23140800
	v_add3_u32 v14, v14, v18, s48
	v_add3_u32 v5, v15, v5, s48
	v_and_b32_sdwa v15, v17, v177 dst_sel:DWORD dst_unused:UNUSED_PAD src0_sel:WORD_1 src1_sel:DWORD
	v_and_b32_sdwa v18, v16, v177 dst_sel:DWORD dst_unused:UNUSED_PAD src0_sel:WORD_1 src1_sel:DWORD
	v_lshl_add_u64 v[12:13], v[10:11], 0, s[2:3]
	v_add3_u32 v15, v17, v15, s48
	v_add3_u32 v16, v16, v18, s48
	s_mov_b32 s2, 0x23140000
	v_and_b32_e32 v15, 0xffff0000, v15
	v_and_b32_e32 v16, 0xffff0000, v16
	v_add_co_u32_e32 v10, vcc, s2, v10
	v_or_b32_sdwa v15, v15, v5 dst_sel:DWORD dst_unused:UNUSED_PAD src0_sel:DWORD src1_sel:WORD_1
	v_or_b32_sdwa v14, v16, v14 dst_sel:DWORD dst_unused:UNUSED_PAD src0_sel:DWORD src1_sel:WORD_1
	v_addc_co_u32_e32 v11, vcc, 0, v11, vcc
	global_store_dwordx2 v[10:11], v[14:15], off offset:2048
	v_mov_b32_e32 v10, v24
	v_mov_b32_e32 v11, v26
	v_pk_mul_f32 v[10:11], v[10:11], v[4:5] op_sel_hi:[1,0]
	v_mov_b32_e32 v26, v25
	v_pk_mul_f32 v[14:15], v[26:27], v[4:5] op_sel_hi:[1,0]
	v_and_b32_sdwa v5, v11, v177 dst_sel:DWORD dst_unused:UNUSED_PAD src0_sel:WORD_1 src1_sel:DWORD
	v_and_b32_sdwa v16, v10, v177 dst_sel:DWORD dst_unused:UNUSED_PAD src0_sel:WORD_1 src1_sel:DWORD
	v_add3_u32 v10, v10, v16, s48
	v_add3_u32 v5, v11, v5, s48
	v_and_b32_sdwa v11, v15, v177 dst_sel:DWORD dst_unused:UNUSED_PAD src0_sel:WORD_1 src1_sel:DWORD
	v_and_b32_sdwa v16, v14, v177 dst_sel:DWORD dst_unused:UNUSED_PAD src0_sel:WORD_1 src1_sel:DWORD
	v_add3_u32 v11, v15, v11, s48
	v_add3_u32 v14, v14, v16, s48
	v_and_b32_e32 v11, 0xffff0000, v11
	v_and_b32_e32 v14, 0xffff0000, v14
	v_or_b32_sdwa v11, v11, v5 dst_sel:DWORD dst_unused:UNUSED_PAD src0_sel:DWORD src1_sel:WORD_1
	v_or_b32_sdwa v10, v14, v10 dst_sel:DWORD dst_unused:UNUSED_PAD src0_sel:DWORD src1_sel:WORD_1
	global_store_dwordx2 v[12:13], v[10:11], off offset:32
	v_mov_b32_e32 v10, v6
	v_mov_b32_e32 v11, v8
	v_pk_mul_f32 v[10:11], v[10:11], v[4:5] op_sel_hi:[1,0]
	v_mov_b32_e32 v8, v7
	v_pk_mul_f32 v[6:7], v[8:9], v[4:5] op_sel_hi:[1,0]
	v_and_b32_sdwa v8, v10, v177 dst_sel:DWORD dst_unused:UNUSED_PAD src0_sel:WORD_1 src1_sel:DWORD
	v_add3_u32 v8, v10, v8, s48
	v_and_b32_sdwa v9, v7, v177 dst_sel:DWORD dst_unused:UNUSED_PAD src0_sel:WORD_1 src1_sel:DWORD
	v_and_b32_sdwa v10, v6, v177 dst_sel:DWORD dst_unused:UNUSED_PAD src0_sel:WORD_1 src1_sel:DWORD
	v_and_b32_sdwa v5, v11, v177 dst_sel:DWORD dst_unused:UNUSED_PAD src0_sel:WORD_1 src1_sel:DWORD
	v_add3_u32 v7, v7, v9, s48
	v_add3_u32 v6, v6, v10, s48
	v_add3_u32 v5, v11, v5, s48
	v_and_b32_e32 v7, 0xffff0000, v7
	v_and_b32_e32 v6, 0xffff0000, v6
	v_or_b32_sdwa v7, v7, v5 dst_sel:DWORD dst_unused:UNUSED_PAD src0_sel:DWORD src1_sel:WORD_1
	v_or_b32_sdwa v6, v6, v8 dst_sel:DWORD dst_unused:UNUSED_PAD src0_sel:DWORD src1_sel:WORD_1
	global_store_dwordx2 v[12:13], v[6:7], off offset:64
	v_mov_b32_e32 v7, v2
	v_mov_b32_e32 v2, v1
	v_mov_b32_e32 v6, v0
	v_pk_mul_f32 v[0:1], v[2:3], v[4:5] op_sel_hi:[1,0]
	v_pk_mul_f32 v[6:7], v[6:7], v[4:5] op_sel_hi:[1,0]
	v_and_b32_sdwa v4, v1, v177 dst_sel:DWORD dst_unused:UNUSED_PAD src0_sel:WORD_1 src1_sel:DWORD
	v_and_b32_sdwa v5, v0, v177 dst_sel:DWORD dst_unused:UNUSED_PAD src0_sel:WORD_1 src1_sel:DWORD
	v_and_b32_sdwa v2, v7, v177 dst_sel:DWORD dst_unused:UNUSED_PAD src0_sel:WORD_1 src1_sel:DWORD
	v_and_b32_sdwa v3, v6, v177 dst_sel:DWORD dst_unused:UNUSED_PAD src0_sel:WORD_1 src1_sel:DWORD
	v_add3_u32 v1, v1, v4, s48
	v_add3_u32 v0, v0, v5, s48
	v_add3_u32 v3, v6, v3, s48
	v_add3_u32 v2, v7, v2, s48
	v_and_b32_e32 v1, 0xffff0000, v1
	v_and_b32_e32 v0, 0xffff0000, v0
	v_or_b32_sdwa v1, v1, v2 dst_sel:DWORD dst_unused:UNUSED_PAD src0_sel:DWORD src1_sel:WORD_1
	v_or_b32_sdwa v0, v0, v3 dst_sel:DWORD dst_unused:UNUSED_PAD src0_sel:DWORD src1_sel:WORD_1
	global_store_dwordx2 v[12:13], v[0:1], off offset:96
	s_cbranch_scc1 .LBB0_380
